# plus: conv_drain overlaps both items loads before gain multiply; att_q_g gains preloaded at att_core start; unit-start store-drain waits removed
# speedup vs baseline: 1.0267x; 1.0010x over previous
; #define GAS __attribute__((address_space(1)))
; __device__ __forceinline__ void item_load(const ItemP& p, f32x4 (&v)[16], int lane) {
;     const int c4 = 4 * (lane & 15);
; #pragma unroll
;     for (int i = 0; i < 16; ++i) { v[i] = (f32x4){0.f, 0.f, 0.f, 0.f}; if (c4 < p.nvalid) v[i] = __builtin_nontemporal_load((const GAS f32x4*)(p.src + (size_t)(4 * i + (lane >> 4)) * p.ldw + c4)); }
;     if (p.gk) {
; #pragma unroll
;         for (int i = 0; i < 16; ++i) v[i] = v[i] * p.gk[4 * i + (lane >> 4)]; }
; __device__ __forceinline__ void conv_drain(const float* const* in, unsigned char* ws, LAS unsigned char* lds, int layer, int tid) {
;     ...
;         f32x4 va[16], vb[16];
;         const ItemP pa = item_decode(in, ws, layer * I_L + base + w), pb = item_decode(in, ws, layer * I_L + base + 8 + w);
;         item_load(pa, va, lane); item_load(pb, vb, lane);
.LBB0_497:
	s_or_b64 exec, exec, s[24:25]
	s_mov_b64 s[100:101], s[16:17]
	v_lshlrev_b32_e32 v137, 2, v134

; __device__ __forceinline__ void item_load(const ItemP& p, f32x4 (&v)[16], int lane) {
;     ...
;     if (p.gk) {
; #pragma unroll
;         for (int i = 0; i < 16; ++i) v[i] = v[i] * p.gk[4 * i + (lane >> 4)]; }
; __device__ __forceinline__ void conv_drain(const float* const* in, unsigned char* ws, LAS unsigned char* lds, int layer, int tid) {
;     ...
;         item_load(pa, va, lane); item_load(pb, vb, lane);
.LBB0_531:
	s_or_b64 exec, exec, s[16:17]
	s_cmp_lg_u64 s[100:101], 0
	s_cbranch_scc0 .Lgk_a_skip
	global_load_dword v0, v137, s[100:101]
	s_waitcnt vmcnt(0)
	v_pk_mul_f32 v[6:7], v[6:7], v[0:1] op_sel_hi:[1,0]
	v_pk_mul_f32 v[4:5], v[4:5], v[0:1] op_sel_hi:[1,0]
	global_load_dword v0, v137, s[100:101] offset:16
	s_waitcnt vmcnt(0)
	v_pk_mul_f32 v[10:11], v[10:11], v[0:1] op_sel_hi:[1,0]
	v_pk_mul_f32 v[8:9], v[8:9], v[0:1] op_sel_hi:[1,0]
	global_load_dword v0, v137, s[100:101] offset:32
	s_waitcnt vmcnt(0)
	v_pk_mul_f32 v[14:15], v[14:15], v[0:1] op_sel_hi:[1,0]
	v_pk_mul_f32 v[12:13], v[12:13], v[0:1] op_sel_hi:[1,0]
	global_load_dword v0, v137, s[100:101] offset:48
	s_waitcnt vmcnt(0)
	v_pk_mul_f32 v[18:19], v[18:19], v[0:1] op_sel_hi:[1,0]
	v_pk_mul_f32 v[16:17], v[16:17], v[0:1] op_sel_hi:[1,0]
	global_load_dword v0, v137, s[100:101] offset:64
	s_waitcnt vmcnt(0)
	v_pk_mul_f32 v[22:23], v[22:23], v[0:1] op_sel_hi:[1,0]
	v_pk_mul_f32 v[20:21], v[20:21], v[0:1] op_sel_hi:[1,0]
	global_load_dword v0, v137, s[100:101] offset:80
	s_waitcnt vmcnt(0)
	v_pk_mul_f32 v[26:27], v[26:27], v[0:1] op_sel_hi:[1,0]
	v_pk_mul_f32 v[24:25], v[24:25], v[0:1] op_sel_hi:[1,0]
	global_load_dword v0, v137, s[100:101] offset:96
	s_waitcnt vmcnt(0)
	v_pk_mul_f32 v[30:31], v[30:31], v[0:1] op_sel_hi:[1,0]
	v_pk_mul_f32 v[28:29], v[28:29], v[0:1] op_sel_hi:[1,0]
	global_load_dword v0, v137, s[100:101] offset:112
	s_waitcnt vmcnt(0)
	v_pk_mul_f32 v[34:35], v[34:35], v[0:1] op_sel_hi:[1,0]
	v_pk_mul_f32 v[32:33], v[32:33], v[0:1] op_sel_hi:[1,0]
	global_load_dword v0, v137, s[100:101] offset:128
	s_waitcnt vmcnt(0)
	v_pk_mul_f32 v[38:39], v[38:39], v[0:1] op_sel_hi:[1,0]
	v_pk_mul_f32 v[36:37], v[36:37], v[0:1] op_sel_hi:[1,0]
	global_load_dword v0, v137, s[100:101] offset:144
	s_waitcnt vmcnt(0)
	v_pk_mul_f32 v[42:43], v[42:43], v[0:1] op_sel_hi:[1,0]
	v_pk_mul_f32 v[40:41], v[40:41], v[0:1] op_sel_hi:[1,0]
	global_load_dword v0, v137, s[100:101] offset:160
	s_waitcnt vmcnt(0)
	v_pk_mul_f32 v[46:47], v[46:47], v[0:1] op_sel_hi:[1,0]
	v_pk_mul_f32 v[44:45], v[44:45], v[0:1] op_sel_hi:[1,0]
	global_load_dword v0, v137, s[100:101] offset:176
	s_waitcnt vmcnt(0)
	v_pk_mul_f32 v[50:51], v[50:51], v[0:1] op_sel_hi:[1,0]
	v_pk_mul_f32 v[48:49], v[48:49], v[0:1] op_sel_hi:[1,0]
	global_load_dword v0, v137, s[100:101] offset:192
	s_waitcnt vmcnt(0)
	v_pk_mul_f32 v[54:55], v[54:55], v[0:1] op_sel_hi:[1,0]
	v_pk_mul_f32 v[52:53], v[52:53], v[0:1] op_sel_hi:[1,0]
	global_load_dword v0, v137, s[100:101] offset:208
	s_waitcnt vmcnt(0)
	v_pk_mul_f32 v[58:59], v[58:59], v[0:1] op_sel_hi:[1,0]
	v_pk_mul_f32 v[56:57], v[56:57], v[0:1] op_sel_hi:[1,0]
	global_load_dword v0, v137, s[100:101] offset:224
	s_waitcnt vmcnt(0)
	v_pk_mul_f32 v[62:63], v[62:63], v[0:1] op_sel_hi:[1,0]
	v_pk_mul_f32 v[60:61], v[60:61], v[0:1] op_sel_hi:[1,0]
	global_load_dword v0, v137, s[100:101] offset:240
	s_waitcnt vmcnt(0)
	v_pk_mul_f32 v[66:67], v[66:67], v[0:1] op_sel_hi:[1,0]
	v_pk_mul_f32 v[64:65], v[64:65], v[0:1] op_sel_hi:[1,0]
.Lgk_a_skip:
	s_cmp_lg_u64 s[8:9], 0
	s_cbranch_scc0 .LBB0_450
	global_load_dword v0, v137, s[8:9]
	s_waitcnt vmcnt(0)
	v_pk_mul_f32 v[70:71], v[70:71], v[0:1] op_sel_hi:[1,0]
	v_pk_mul_f32 v[68:69], v[68:69], v[0:1] op_sel_hi:[1,0]
	global_load_dword v0, v137, s[8:9] offset:16
	s_waitcnt vmcnt(0)
	v_pk_mul_f32 v[74:75], v[74:75], v[0:1] op_sel_hi:[1,0]
	v_pk_mul_f32 v[72:73], v[72:73], v[0:1] op_sel_hi:[1,0]
	global_load_dword v0, v137, s[8:9] offset:32
	s_waitcnt vmcnt(0)
	v_pk_mul_f32 v[78:79], v[78:79], v[0:1] op_sel_hi:[1,0]
	v_pk_mul_f32 v[76:77], v[76:77], v[0:1] op_sel_hi:[1,0]
	global_load_dword v0, v137, s[8:9] offset:48
	s_waitcnt vmcnt(0)
	v_pk_mul_f32 v[82:83], v[82:83], v[0:1] op_sel_hi:[1,0]
	v_pk_mul_f32 v[80:81], v[80:81], v[0:1] op_sel_hi:[1,0]
	global_load_dword v0, v137, s[8:9] offset:64
	s_waitcnt vmcnt(0)
	v_pk_mul_f32 v[86:87], v[86:87], v[0:1] op_sel_hi:[1,0]
	v_pk_mul_f32 v[84:85], v[84:85], v[0:1] op_sel_hi:[1,0]
	global_load_dword v0, v137, s[8:9] offset:80
	s_waitcnt vmcnt(0)
	v_pk_mul_f32 v[90:91], v[90:91], v[0:1] op_sel_hi:[1,0]
	v_pk_mul_f32 v[88:89], v[88:89], v[0:1] op_sel_hi:[1,0]
	global_load_dword v0, v137, s[8:9] offset:96
	s_waitcnt vmcnt(0)
	v_pk_mul_f32 v[94:95], v[94:95], v[0:1] op_sel_hi:[1,0]
	v_pk_mul_f32 v[92:93], v[92:93], v[0:1] op_sel_hi:[1,0]
	global_load_dword v0, v137, s[8:9] offset:112
	s_waitcnt vmcnt(0)
	v_pk_mul_f32 v[98:99], v[98:99], v[0:1] op_sel_hi:[1,0]
	v_pk_mul_f32 v[96:97], v[96:97], v[0:1] op_sel_hi:[1,0]
	global_load_dword v0, v137, s[8:9] offset:128
	s_waitcnt vmcnt(0)
	v_pk_mul_f32 v[102:103], v[102:103], v[0:1] op_sel_hi:[1,0]
	v_pk_mul_f32 v[100:101], v[100:101], v[0:1] op_sel_hi:[1,0]
	global_load_dword v0, v137, s[8:9] offset:144
	s_waitcnt vmcnt(0)
	v_pk_mul_f32 v[106:107], v[106:107], v[0:1] op_sel_hi:[1,0]
	v_pk_mul_f32 v[104:105], v[104:105], v[0:1] op_sel_hi:[1,0]
	global_load_dword v0, v137, s[8:9] offset:160
	s_waitcnt vmcnt(0)
	v_pk_mul_f32 v[110:111], v[110:111], v[0:1] op_sel_hi:[1,0]
	v_pk_mul_f32 v[108:109], v[108:109], v[0:1] op_sel_hi:[1,0]
	global_load_dword v0, v137, s[8:9] offset:176
	s_waitcnt vmcnt(0)
	v_pk_mul_f32 v[114:115], v[114:115], v[0:1] op_sel_hi:[1,0]
	v_pk_mul_f32 v[112:113], v[112:113], v[0:1] op_sel_hi:[1,0]
	global_load_dword v0, v137, s[8:9] offset:192
	s_waitcnt vmcnt(0)
	v_pk_mul_f32 v[118:119], v[118:119], v[0:1] op_sel_hi:[1,0]
	v_pk_mul_f32 v[116:117], v[116:117], v[0:1] op_sel_hi:[1,0]
	global_load_dword v0, v137, s[8:9] offset:208
	s_waitcnt vmcnt(0)
	v_pk_mul_f32 v[122:123], v[122:123], v[0:1] op_sel_hi:[1,0]
	v_pk_mul_f32 v[120:121], v[120:121], v[0:1] op_sel_hi:[1,0]
	global_load_dword v0, v137, s[8:9] offset:224
	s_waitcnt vmcnt(0)
	v_pk_mul_f32 v[126:127], v[126:127], v[0:1] op_sel_hi:[1,0]
	v_pk_mul_f32 v[124:125], v[124:125], v[0:1] op_sel_hi:[1,0]
	global_load_dword v0, v137, s[8:9] offset:240
	s_waitcnt vmcnt(0)
	v_pk_mul_f32 v[130:131], v[130:131], v[0:1] op_sel_hi:[1,0]
	v_pk_mul_f32 v[128:129], v[128:129], v[0:1] op_sel_hi:[1,0]
	s_branch .LBB0_450

; #define LAS __attribute__((address_space(3)))
; __device__ __forceinline__ void att_unit(LAS unsigned char* lds, const bf16* P, const bf16* AKV, const bf16* IKC, bf16* ACAT, const float* aqg, const float* ssq_ak, const float* ssq_ik, int b, int qg, int tid) {
;     asm volatile("" : "+s"(P), "+s"(AKV), "+s"(IKC), "+s"(ACAT), "+s"(aqg), "+s"(ssq_ak), "+s"(ssq_ik), "+s"(qg), "+v"(tid));
;     const int lane = tid & 63, w = __builtin_amdgcn_readfirstlane(tid >> 6), fr = lane & 15, fq = lane >> 4;
;     LAS unsigned char* IK = lds;
;     LAS unsigned char* Vst = lds + w * 9216;
;     LAS int* list0 = (LAS int*)(lds + 73728 + w * 6144);
;     const int L = 64 * ((qg >> 2) + 1);
;     const bf16* AKVb = AKV + (size_t)(b * SEQ) * 256;
;     const bf16* IKb = IKC + (size_t)(b * SEQ) * 128;
;     const GAS f32x4* sak = (const GAS f32x4*)ssq_ak + b * SEQ;
;     const size_t tok0 = (size_t)(b * SEQ + 16 * qg + 2 * w);
;     int cnt;
;     if (L <= 256) {
;         cnt = L;
; #pragma unroll
;         for (int r = 0; r < 4; ++r) { const int i = 64 * r + lane; const int kx = i < L ? i : 0; const f32x4 q4 = sak[kx]; const float rk = rsqrtf(((q4.x + q4.y) + (q4.z + q4.w)) * (1.f / 128.f) + EPS);
;             list0[i] = kx; ((LAS float*)list0)[256 + i] = rk; list0[512 + i] = kx; ((LAS float*)list0)[768 + i] = rk;
;             const int tp = ((i >> 5) * 4 + (i & 3)) * 8 + ((i >> 2) & 7); ((LAS unsigned*)list0)[1024 + tp] = (unsigned)kx * 512u; ((LAS unsigned*)list0)[1280 + tp] = (unsigned)kx * 512u; }
;     } else {
;         cnt = 256;
;         typedef float f32x2 __attribute__((ext_vector_type(2)));
;         const GAS f32x2* sik = (const GAS f32x2*)ssq_ik + b * SEQ;
;         bf16x8 Qi[2][2]; float wv[2][4];
; #pragma unroll
;         for (int q = 0; q < 2; ++q) {
; #pragma unroll
;             for (int kk = 0; kk < 2; ++kk) Qi[q][kk] = *(const GAS bf16x8*)(P + (tok0 + q) * NP + C_IQ + fr * 64 + 32 * kk + 8 * fq);
;             const u32x2 ww = *(const GAS u32x2*)(IKC + (tok0 + q) * 128 + 64 + 4 * fq); wv[q][0] = bflo(ww.x); wv[q][1] = bfhi(ww.x); wv[q][2] = bflo(ww.y); wv[q][3] = bfhi(ww.y);
;         }
;         unsigned uk[2][32];
;         const int ntile = (L + 255) >> 8;
;         const int skey = tid >> 3, spart = tid & 7;
;         const bf16* sb = IKb + (size_t)skey * 128 + spart * 8;
;         u32x4 ikr[4]; f32x2 rik[4];
; #pragma unroll
.LBB0_593:
	v_readlane_b32 s0, v254, 13
	v_readlane_b32 s70, v254, 19
	v_readlane_b32 s2, v254, 9
	v_readlane_b32 s76, v254, 11
	v_readlane_b32 s8, v254, 5
	v_readlane_b32 s6, v254, 7
	v_readlane_b32 s4, v254, 3
	v_readlane_b32 s1, v254, 14
	v_readlane_b32 s71, v254, 20
	v_readlane_b32 s3, v254, 10
	v_readlane_b32 s77, v254, 12
	s_nop 0
	v_mov_b32_e32 v18, v220
	v_readlane_b32 s9, v254, 6
	v_readlane_b32 s7, v254, 8
	v_readlane_b32 s5, v254, 4
	s_mov_b32 s11, 0x8c00
	v_writelane_b32 v254, s8, 43
	v_mov_b64_e32 v[154:155], s[4:5]
	v_readfirstlane_b32 s4, v18
	s_ashr_i32 s74, s4, 6
	v_writelane_b32 v254, s9, 44
	s_mul_i32 s4, s74, 0x1800
	s_lshl_b32 s5, s26, 4
	s_add_i32 s33, s4, 0
	s_and_b32 s4, s5, 0xffffffc0
	v_readlane_b32 s9, v254, 38
	s_add_i32 s33, s33, 0x12000
	s_add_i32 s81, s4, 64
	s_lshl_b32 s8, s9, 4
	s_add_u32 s72, s6, s8
	s_addc_u32 s73, s7, 0
	s_lshl_b32 s6, s74, 1
	s_add_i32 s6, s6, s9
	s_add_i32 s5, s6, s5
	s_ashr_i32 s6, s5, 31
	v_and_b32_e32 v124, 63, v18
	v_and_b32_e32 v125, 15, v18
	v_bfe_u32 v126, v18, 4, 2
	v_writelane_b32 v254, s5, 45
	s_cmpk_gt_i32 s81, 0x100
	s_movk_i32 s10, 0x4000
	v_mov_b32_e32 v6, s81
	v_mov_b32_e32 v156, s5
	v_writelane_b32 v254, s6, 46
	v_mov_b32_e32 v157, s6
	s_cselect_b64 s[6:7], -1, 0
	v_lshlrev_b32_e32 v50, 7, v125
	v_lshlrev_b32_e32 v52, 3, v124
	v_lshlrev_b32_e32 v2, 3, v126
	v_and_b32_e32 v51, 48, v18
	s_and_saveexec_b64 s[8:9], s[6:7]
	s_xor_b64 s[82:83], exec, s[8:9]
	s_cbranch_execz .LBB0_1007
	v_mov_b64_e32 v[20:21], s[2:3]
	v_readlane_b32 s2, v254, 41
	v_mov_b64_e32 v[2:3], s[0:1]
	v_readlane_b32 s3, v254, 42
	v_mov_b32_e32 v51, v1
	v_lshlrev_b32_e32 v4, 4, v126
	v_lshl_add_u64 v[22:23], v[2:3], 0, s[2:3]
	v_readlane_b32 s2, v254, 45
	v_mov_b32_e32 v5, v1
	v_lshlrev_b64 v[24:25], 8, v[156:157]
	v_mov_b32_e32 v2, s2
	v_mad_i64_i32 v[2:3], s[2:3], v2, s11, v[154:155]
	v_lshl_add_u64 v[2:3], v[2:3], 0, v[50:51]
	v_lshl_add_u64 v[2:3], v[2:3], 0, v[4:5]
	s_mov_b64 s[2:3], 0x6200
	v_add_co_u32_e32 v6, vcc, 0x6000, v2
	v_lshl_add_u64 v[4:5], v[2:3], 0, s[2:3]
	s_nop 0
	v_addc_co_u32_e32 v7, vcc, 0, v3, vcc
	global_load_dwordx4 v[14:17], v[6:7], off offset:512
	global_load_dwordx4 v[10:13], v[4:5], off offset:64
	v_lshl_add_u64 v[4:5], s[0:1], 0, v[24:25]
	v_or_b32_e32 v24, 0x100, v24
	s_mov_b64 s[2:3], 0xee00
	v_lshl_add_u64 v[24:25], s[0:1], 0, v[24:25]
	v_readlane_b32 s0, v253, 34
	v_lshlrev_b32_e32 v0, 3, v126
	v_lshl_add_u64 v[6:7], v[2:3], 0, s[2:3]
	v_add_co_u32_e32 v2, vcc, 0xe000, v2
	v_readlane_b32 s1, v253, 35
	v_readlane_b32 s0, v254, 38
	v_ashrrev_i32_e32 v32, 3, v18
	v_lshl_add_u64 v[4:5], v[4:5], 0, v[0:1]
	v_addc_co_u32_e32 v3, vcc, 0, v3, vcc
	v_lshl_add_u64 v[24:25], v[24:25], 0, v[0:1]
	s_mov_b32 s3, s1
	s_lshl_b32 s2, s0, 3
	v_ashrrev_i32_e32 v33, 31, v32
	global_load_dwordx2 v[40:41], v[4:5], off offset:128
	s_nop 0
	global_load_dwordx4 v[2:5], v[2:3], off offset:3584
	s_nop 0
	global_load_dwordx4 v[6:9], v[6:7], off offset:64
	v_lshlrev_b32_e32 v19, 4, v18
	global_load_dwordx2 v[38:39], v[24:25], off offset:128
	v_lshl_add_u64 v[24:25], v[20:21], 0, s[2:3]
	v_lshlrev_b64 v[20:21], 8, v[32:33]
	v_lshl_add_u64 v[20:21], v[22:23], 0, v[20:21]
	v_and_b32_e32 v54, 0x70, v19
	v_mov_b32_e32 v55, v1
	v_lshl_add_u64 v[66:67], v[20:21], 0, v[54:55]
	v_mov_b32_e32 v53, v1
	v_writelane_b32 v253, s0, 34
	v_lshl_add_u64 v[88:89], v[24:25], 0, v[52:53]
	v_add_co_u32_e32 v24, vcc, s10, v66
	v_writelane_b32 v253, s1, 35
	s_nop 0
	v_addc_co_u32_e32 v25, vcc, 0, v67, vcc
	s_mov_b32 s0, 0x8000
	v_add_co_u32_e32 v28, vcc, s0, v66
	s_mov_b32 s0, 0xc000
	s_nop 0
	v_addc_co_u32_e32 v29, vcc, 0, v67, vcc
	v_add_co_u32_e32 v36, vcc, s0, v66
	global_load_dwordx4 v[20:23], v[66:67], off
	s_nop 0
	v_addc_co_u32_e32 v37, vcc, 0, v67, vcc
	global_load_dwordx2 v[42:43], v[88:89], off
	s_nop 0
	global_load_dwordx4 v[24:27], v[24:25], off
	s_nop 0
	global_load_dwordx2 v[44:45], v[88:89], off offset:512
	s_nop 0
	global_load_dwordx4 v[28:31], v[28:29], off
	s_nop 0
	global_load_dwordx2 v[34:35], v[88:89], off offset:1024
	global_load_dwordx4 v[46:49], v[36:37], off
	s_nop 0
	global_load_dwordx2 v[36:37], v[88:89], off offset:1536
	s_movk_i32 s0, 0x90
	v_mul_lo_u32 v32, v32, s0
	v_and_b32_e32 v51, 48, v18
	v_and_b32_e32 v18, 16, v18
	s_mov_b32 s0, 0x10000
	v_add_u32_e32 v19, 0, v54
	v_cmp_eq_u32_e64 s[6:7], 0, v18
	v_add_co_u32_e32 v18, vcc, s0, v66
	v_add_u32_e32 v129, v19, v32
	s_nop 0
	v_addc_co_u32_e32 v19, vcc, 0, v67, vcc
	s_mov_b32 s0, 0x14000
	s_mov_b32 s2, 0x3c800000
	v_mov_b32_e32 v132, s4
	s_mov_b32 s18, 0x800000
	s_waitcnt vmcnt(7)
	ds_write_b128 v129, v[20:23]
	s_waitcnt vmcnt(5)
	ds_write_b128 v129, v[24:27] offset:9216
	s_waitcnt vmcnt(3)
	ds_write_b128 v129, v[28:31] offset:18432
	s_waitcnt vmcnt(1)
	ds_write_b128 v129, v[46:49] offset:27648
	v_add_co_u32_e32 v22, vcc, s0, v66
	s_mov_b32 s0, 0x18000
	s_nop 0
	v_addc_co_u32_e32 v23, vcc, 0, v67, vcc
	v_add_co_u32_e32 v26, vcc, s0, v66
	s_mov_b32 s0, 0x1c000
	s_nop 0
	v_addc_co_u32_e32 v27, vcc, 0, v67, vcc
	v_add_co_u32_e32 v30, vcc, s0, v66
	v_mul_u32_u24_e32 v48, 0x90, v125
	s_nop 0
	v_addc_co_u32_e32 v31, vcc, 0, v67, vcc
	v_add3_u32 v131, 0, v51, v48
	s_waitcnt lgkmcnt(0)
	s_barrier
; #define LAS __attribute__((address_space(3)))
; #define GAS __attribute__((address_space(1)))
; __device__ __forceinline__ f32x4 mfma16(bf16x8 a, bf16x8 b, f32x4 c) { return __builtin_amdgcn_mfma_f32_16x16x32_bf16(a, b, c, 0, 0, 0); }
; __device__ __forceinline__ void att_unit(LAS unsigned char* lds, const bf16* P, const bf16* AKV, const bf16* IKC, bf16* ACAT, const float* aqg, const float* ssq_ak, const float* ssq_ik, int b, int qg, int tid) {
;     ...
;         for (int tile = 0; tile < 8; ++tile) {
;             if (tile < ntile) {
;                 LAS unsigned char* IKc = IK + (tile & 1) * 36864;
;                 f32x2 rc[4];
; #pragma unroll
;                 for (int i = 0; i < 4; ++i) rc[i] = rik[i];
;                 if (tile + 1 < ntile) {
; #pragma unroll
;                     for (int i = 0; i < 4; ++i) { ikr[i] = *(const GAS u32x4*)(sb + (size_t)(256 * (tile + 1) + 64 * i) * 128); rik[i] = sik[256 * (tile + 1) + 64 * i + lane]; }
;                 }
; #pragma unroll
;                 for (int r4 = 0; r4 < 4; ++r4) {
;                     float pt[2][4];
; #pragma unroll
;                     for (int q4 = 0; q4 < 4; ++q4) {
;                         const LAS unsigned char* kp = IKc + (64 * r4 + 16 * q4 + fr) * 144 + fq * 16;
;                         const bf16x8 K0 = *(const LAS bf16x8*)kp, K1 = *(const LAS bf16x8*)(kp + 64);
; #pragma unroll
;                         for (int q = 0; q < 2; ++q) {
;                             f32x4 a = (f32x4){0.f, 0.f, 0.f, 0.f};
;                             a = mfma16(Qi[q][0], K0, a); a = mfma16(Qi[q][1], K1, a);
;                             pt[q][q4] = fmaxf(a[0], 0.f) * wv[q][0] + fmaxf(a[1], 0.f) * wv[q][1] + fmaxf(a[2], 0.f) * wv[q][2] + fmaxf(a[3], 0.f) * wv[q][3];
	global_load_dwordx4 v[18:21], v[18:19], off
	s_nop 0
	global_load_dwordx2 v[46:47], v[88:89], off offset:2048
	s_nop 0
	global_load_dwordx4 v[22:25], v[22:23], off
	s_nop 0
	global_load_dwordx2 v[104:105], v[88:89], off offset:2560
	s_nop 0
	global_load_dwordx4 v[26:29], v[26:27], off
	s_nop 0
	global_load_dwordx2 v[100:101], v[88:89], off offset:3072
	s_nop 0
	global_load_dwordx4 v[30:33], v[30:31], off
	s_nop 0
	global_load_dwordx2 v[94:95], v[88:89], off offset:3584
	ds_read_b128 v[54:57], v131
	ds_read_b128 v[60:63], v131 offset:64
	s_waitcnt lgkmcnt(1)
	v_mfma_f32_16x16x32_bf16 v[68:71], v[14:17], v[54:57], 0
	s_mov_b32 s0, 0x358637bd
	v_mfma_f32_16x16x32_bf16 v[54:57], v[2:5], v[54:57], 0
	s_waitcnt lgkmcnt(0)
	v_mfma_f32_16x16x32_bf16 v[68:71], v[10:13], v[60:63], v[68:71]
	v_mfma_f32_16x16x32_bf16 v[54:57], v[6:9], v[60:63], v[54:57]
	ds_read_b128 v[60:63], v131 offset:2304
	ds_read_b128 v[72:75], v131 offset:2368
	s_nop 4
	v_max_f32_e32 v64, 0, v68
	v_max_f32_e32 v65, 0, v69
	v_max_f32_e32 v59, 0, v70
	v_max_f32_e32 v58, 0, v71
	s_waitcnt lgkmcnt(1)
	v_mfma_f32_16x16x32_bf16 v[68:71], v[14:17], v[60:63], 0
	v_max_f32_e32 v54, 0, v54
	s_waitcnt lgkmcnt(0)
	v_mfma_f32_16x16x32_bf16 v[76:79], v[10:13], v[72:75], v[68:71]
	v_max_f32_e32 v55, 0, v55
	v_mfma_f32_16x16x32_bf16 v[60:63], v[2:5], v[60:63], 0
	v_max_f32_e32 v49, 0, v56
	s_nop 2
	s_nop 1
	v_max_f32_e32 v70, 0, v76
	v_max_f32_e32 v71, 0, v77
	v_max_f32_e32 v69, 0, v78
	v_max_f32_e32 v68, 0, v79
	ds_read_b128 v[78:81], v131 offset:4608
	ds_read_b128 v[82:85], v131 offset:4672
	v_mfma_f32_16x16x32_bf16 v[60:63], v[6:9], v[72:75], v[60:63]
	v_max_f32_e32 v48, 0, v57
	s_waitcnt lgkmcnt(1)
	v_mfma_f32_16x16x32_bf16 v[72:75], v[14:17], v[78:81], 0
	s_waitcnt lgkmcnt(0)
	v_mfma_f32_16x16x32_bf16 v[72:75], v[10:13], v[82:85], v[72:75]
	s_nop 0
	s_nop 1
	v_max_f32_e32 v60, 0, v60
	v_mfma_f32_16x16x32_bf16 v[78:81], v[2:5], v[78:81], 0
	v_max_f32_e32 v61, 0, v61
	v_max_f32_e32 v57, 0, v62
	v_max_f32_e32 v56, 0, v63
	v_mfma_f32_16x16x32_bf16 v[80:83], v[6:9], v[82:85], v[78:81]
	v_max_f32_e32 v76, 0, v72
	v_max_f32_e32 v77, 0, v73
	v_max_f32_e32 v73, 0, v74
	v_max_f32_e32 v72, 0, v75
	s_nop 0
	s_nop 2
	v_max_f32_e32 v80, 0, v80
	v_max_f32_e32 v81, 0, v81
	v_max_f32_e32 v63, 0, v82
	v_max_f32_e32 v62, 0, v83
	ds_read_b128 v[82:85], v131 offset:6912
	ds_read_b128 v[96:99], v131 offset:6976
	s_waitcnt lgkmcnt(1)
	v_mfma_f32_16x16x32_bf16 v[90:93], v[14:17], v[82:85], 0
	v_mov_b32_e32 v75, v42
	v_mov_b32_e32 v42, v45
	s_waitcnt lgkmcnt(0)
	v_mfma_f32_16x16x32_bf16 v[90:93], v[10:13], v[96:99], v[90:93]
	v_mfma_f32_16x16x32_bf16 v[82:85], v[2:5], v[82:85], 0
	v_mfma_f32_16x16x32_bf16 v[84:87], v[6:9], v[96:99], v[82:85]
	s_nop 5
	v_max_f32_e32 v78, 0, v90
	ds_read_b128 v[96:99], v131 offset:9216
	ds_read_b128 v[106:109], v131 offset:9280
	v_max_f32_e32 v79, 0, v91
	v_max_f32_e32 v91, 0, v92
	v_max_f32_e32 v90, 0, v93
	v_max_f32_e32 v84, 0, v84
	s_waitcnt lgkmcnt(1)
	v_mfma_f32_16x16x32_bf16 v[110:113], v[14:17], v[96:99], 0
	v_max_f32_e32 v85, 0, v85
	v_max_f32_e32 v83, 0, v86
	v_mfma_f32_16x16x32_bf16 v[96:99], v[2:5], v[96:99], 0
	v_max_f32_e32 v82, 0, v87
	v_mbcnt_hi_u32_b32 v53, -1, v221
	v_and_b32_e32 v74, 64, v53
	s_waitcnt lgkmcnt(0)
	v_mfma_f32_16x16x32_bf16 v[110:113], v[10:13], v[106:109], v[110:113]
	v_xor_b32_e32 v127, 16, v53
	v_add_u32_e32 v128, 64, v74
	v_cmp_lt_i32_e32 vcc, v127, v128
	v_mfma_f32_16x16x32_bf16 v[96:99], v[6:9], v[106:109], v[96:99]
	ds_read_b128 v[106:109], v131 offset:11520
	ds_read_b128 v[114:117], v131 offset:11584
	v_cndmask_b32_e32 v74, v53, v127, vcc
	v_lshlrev_b32_e32 v130, 2, v74
	s_waitcnt lgkmcnt(1)
	v_mfma_f32_16x16x32_bf16 v[118:121], v[14:17], v[106:109], 0
	v_max_f32_e32 v110, 0, v110
	v_max_f32_e32 v111, 0, v111
	v_max_f32_e32 v103, 0, v112
	v_mfma_f32_16x16x32_bf16 v[106:109], v[2:5], v[106:109], 0
	v_max_f32_e32 v102, 0, v113
	v_max_f32_e32 v96, 0, v96
	s_waitcnt lgkmcnt(0)
	v_mfma_f32_16x16x32_bf16 v[118:121], v[10:13], v[114:117], v[118:121]
	v_max_f32_e32 v97, 0, v97
	v_max_f32_e32 v87, 0, v98
	v_mfma_f32_16x16x32_bf16 v[106:109], v[6:9], v[114:117], v[106:109]
	ds_read_b128 v[114:117], v131 offset:13824
	ds_read_b128 v[134:137], v131 offset:13888
	v_max_f32_e32 v86, 0, v99
	s_nop 1
	v_max_f32_e32 v118, 0, v118
	v_max_f32_e32 v119, 0, v119
	v_max_f32_e32 v113, 0, v120
	v_max_f32_e32 v112, 0, v121
	s_waitcnt lgkmcnt(1)
	v_mfma_f32_16x16x32_bf16 v[120:123], v[14:17], v[114:117], 0
	v_max_f32_e32 v106, 0, v106
	v_mfma_f32_16x16x32_bf16 v[114:117], v[2:5], v[114:117], 0
	v_max_f32_e32 v107, 0, v107
	s_waitcnt lgkmcnt(0)
	v_mfma_f32_16x16x32_bf16 v[120:123], v[10:13], v[134:137], v[120:123]
	v_max_f32_e32 v99, 0, v108
	v_max_f32_e32 v98, 0, v109
	v_mfma_f32_16x16x32_bf16 v[114:117], v[6:9], v[134:137], v[114:117]
	ds_read_b128 v[134:137], v131 offset:16128
	ds_read_b128 v[138:141], v131 offset:16192
	s_nop 1
	s_nop 0
	v_max_f32_e32 v146, 0, v120
	s_waitcnt lgkmcnt(1)
	v_mfma_f32_16x16x32_bf16 v[142:145], v[14:17], v[134:137], 0
	v_max_f32_e32 v147, 0, v121
	v_max_f32_e32 v121, 0, v122
	v_max_f32_e32 v120, 0, v123
	s_waitcnt lgkmcnt(0)
	v_mfma_f32_16x16x32_bf16 v[142:145], v[10:13], v[138:141], v[142:145]
	v_max_f32_e32 v114, 0, v114
	v_max_f32_e32 v115, 0, v115
	v_mfma_f32_16x16x32_bf16 v[134:137], v[2:5], v[134:137], 0
	v_max_f32_e32 v109, 0, v116
	v_max_f32_e32 v108, 0, v117
	v_mfma_f32_16x16x32_bf16 v[134:137], v[6:9], v[138:141], v[134:137]
	s_nop 1
	v_max_f32_e32 v148, 0, v142
	v_max_f32_e32 v149, 0, v143
	v_max_f32_e32 v151, 0, v144
	v_max_f32_e32 v150, 0, v145
	s_nop 0
	s_nop 0
	v_max_f32_e32 v122, 0, v134
	v_max_f32_e32 v123, 0, v135
	v_max_f32_e32 v117, 0, v136
	v_max_f32_e32 v116, 0, v137
	ds_read_b128 v[134:137], v131 offset:18432
	ds_read_b128 v[138:141], v131 offset:18496
	s_waitcnt lgkmcnt(1)
; #define LAS __attribute__((address_space(3)))
; __device__ __forceinline__ f32x4 mfma16(bf16x8 a, bf16x8 b, f32x4 c) { return __builtin_amdgcn_mfma_f32_16x16x32_bf16(a, b, c, 0, 0, 0); }
; __device__ __forceinline__ void att_unit(LAS unsigned char* lds, const bf16* P, const bf16* AKV, const bf16* IKC, bf16* ACAT, const float* aqg, const float* ssq_ak, const float* ssq_ik, int b, int qg, int tid) {
;     ...
;                 for (int r4 = 0; r4 < 4; ++r4) {
;                     float pt[2][4];
; #pragma unroll
;                     for (int q4 = 0; q4 < 4; ++q4) {
;                         const LAS unsigned char* kp = IKc + (64 * r4 + 16 * q4 + fr) * 144 + fq * 16;
;                         const bf16x8 K0 = *(const LAS bf16x8*)kp, K1 = *(const LAS bf16x8*)(kp + 64);
; #pragma unroll
;                         for (int q = 0; q < 2; ++q) {
;                             f32x4 a = (f32x4){0.f, 0.f, 0.f, 0.f};
;                             a = mfma16(Qi[q][0], K0, a); a = mfma16(Qi[q][1], K1, a);
;                             pt[q][q4] = fmaxf(a[0], 0.f) * wv[q][0] + fmaxf(a[1], 0.f) * wv[q][1] + fmaxf(a[2], 0.f) * wv[q][2] + fmaxf(a[3], 0.f) * wv[q][3];
;                         }
;                     }
;                     const int rr = 4 * tile + r4;
;                     const float rscale = rsqrtf((rc[r4].x + rc[r4].y) * (1.f / 64.f) + EPS);
;                     const bool live = 64 * rr + lane < L;
; #pragma unroll
;                     for (int q = 0; q < 2; ++q) {
;                         float hx; const float A = half_sum32(pt[q][0], pt[q][2], hx), B = half_sum32(pt[q][1], pt[q][3], hx);
;                         const bool odd = fq & 1;
;                         const float send = odd ? A : B, keep = odd ? B : A;
;                         const float sc = live ? (keep + __shfl_xor(send, 16)) * rscale : -INFINITY;
;                         const unsigned bts = __float_as_uint(sc);
;                         uk[q][rr] = bts ^ ((unsigned)((int)bts >> 31) | 0x80000000u);
;                     }
	v_mfma_f32_16x16x32_bf16 v[142:145], v[14:17], v[134:137], 0
	v_mov_b32_e32 v74, v44
	v_pk_add_f32 v[44:45], v[74:75], v[42:43]
	v_and_b32_e32 v75, 0xffff0000, v40
	s_waitcnt lgkmcnt(0)
	v_mfma_f32_16x16x32_bf16 v[142:145], v[10:13], v[138:141], v[142:145]
	v_lshlrev_b32_e32 v74, 16, v40
	v_mul_f32_e32 v40, v65, v75
	v_pk_fma_f32 v[64:65], v[64:65], v[74:75], v[40:41] op_sel_hi:[1,1,0]
	v_mul_f32_e32 v40, v71, v75
	v_pk_fma_f32 v[70:71], v[70:71], v[74:75], v[40:41] op_sel_hi:[1,1,0]
	v_mul_f32_e32 v40, v77, v75
	v_mov_b64_e32 v[42:43], s[0:1]
	v_pk_fma_f32 v[76:77], v[76:77], v[74:75], v[40:41] op_sel_hi:[1,1,0]
	v_mul_f32_e32 v40, v79, v75
	v_pk_fma_f32 v[92:93], v[44:45], s[2:3], v[42:43] op_sel_hi:[1,0,0]
	v_max_f32_e32 v44, 0, v142
	v_max_f32_e32 v45, 0, v143
	v_pk_fma_f32 v[142:143], v[78:79], v[74:75], v[40:41] op_sel_hi:[1,1,0]
	v_mul_f32_e32 v40, v111, v75
	v_pk_fma_f32 v[110:111], v[110:111], v[74:75], v[40:41] op_sel_hi:[1,1,0]
	v_mul_f32_e32 v40, v119, v75
	v_pk_fma_f32 v[118:119], v[118:119], v[74:75], v[40:41] op_sel_hi:[1,1,0]
	v_mul_f32_e32 v40, v147, v75
	v_pk_fma_f32 v[146:147], v[146:147], v[74:75], v[40:41] op_sel_hi:[1,1,0]
	v_mul_f32_e32 v40, v149, v75
	v_pk_fma_f32 v[148:149], v[148:149], v[74:75], v[40:41] op_sel_hi:[1,1,0]
	v_mul_f32_e32 v40, v45, v75
	v_pk_fma_f32 v[44:45], v[44:45], v[74:75], v[40:41] op_sel_hi:[1,1,0]
	v_max_f32_e32 v153, 0, v144
	v_lshlrev_b32_e32 v79, 16, v41
	v_max_f32_e32 v152, 0, v145
	v_mul_f32_e32 v40, v59, v79
	v_and_b32_e32 v78, 0xffff0000, v41
	v_pk_add_f32 v[40:41], v[40:41], v[64:65] op_sel_hi:[0,1]
	v_pk_fma_f32 v[40:41], v[58:59], v[78:79], v[40:41]
	v_mul_f32_e32 v58, v69, v79
	v_pk_add_f32 v[58:59], v[58:59], v[70:71] op_sel_hi:[0,1]
	v_pk_fma_f32 v[58:59], v[68:69], v[78:79], v[58:59]
	v_mul_f32_e32 v64, v73, v79
	v_mul_f32_e32 v68, v91, v79
	v_pk_add_f32 v[64:65], v[64:65], v[76:77] op_sel_hi:[0,1]
	v_pk_add_f32 v[68:69], v[68:69], v[142:143] op_sel_hi:[0,1]
	v_pk_fma_f32 v[64:65], v[72:73], v[78:79], v[64:65]
	v_pk_fma_f32 v[68:69], v[90:91], v[78:79], v[68:69]
	v_mul_f32_e32 v70, v103, v79
	v_mul_f32_e32 v72, v113, v79
	v_mul_f32_e32 v76, v121, v79
	v_mul_f32_e32 v90, v151, v79
	v_pk_add_f32 v[70:71], v[70:71], v[110:111] op_sel_hi:[0,1]
	v_pk_add_f32 v[72:73], v[72:73], v[118:119] op_sel_hi:[0,1]
	v_pk_add_f32 v[76:77], v[76:77], v[146:147] op_sel_hi:[0,1]
	v_pk_add_f32 v[90:91], v[90:91], v[148:149] op_sel_hi:[0,1]
	v_permlane32_swap_b32_e32 v40, v64
	v_permlane32_swap_b32_e32 v58, v68
	v_pk_fma_f32 v[70:71], v[102:103], v[78:79], v[70:71]
	v_pk_fma_f32 v[72:73], v[112:113], v[78:79], v[72:73]
	v_pk_fma_f32 v[76:77], v[120:121], v[78:79], v[76:77]
	v_pk_fma_f32 v[90:91], v[150:151], v[78:79], v[90:91]
	v_mfma_f32_16x16x32_bf16 v[110:113], v[2:5], v[134:137], 0
	v_permlane32_swap_b32_e32 v70, v76
	v_permlane32_swap_b32_e32 v72, v90
	v_mov_b32_e32 v73, v58
	v_mov_b32_e32 v91, v68
	v_mov_b32_e32 v71, v40
	v_mov_b32_e32 v77, v64
	v_pk_add_f32 v[68:69], v[72:73], v[90:91]
	v_pk_add_f32 v[70:71], v[70:71], v[76:77]
	v_and_b32_e32 v77, 0xffff0000, v38
	v_cndmask_b32_e64 v40, v71, v69, s[6:7]
	v_lshlrev_b32_e32 v76, 16, v38
	v_mul_f32_e32 v38, v55, v77
	ds_bpermute_b32 v73, v130, v40
	v_cndmask_b32_e64 v40, v70, v68, s[6:7]
	v_mfma_f32_16x16x32_bf16 v[110:113], v[6:9], v[138:141], v[110:113]
	v_fma_f32 v54, v54, v76, v38
	v_fma_f32 v55, v55, v77, v38
	v_mul_f32_e32 v38, v61, v77
	ds_bpermute_b32 v72, v130, v40
	v_mul_f32_e32 v40, v153, v79
	v_pk_fma_f32 v[58:59], v[60:61], v[76:77], v[38:39] op_sel_hi:[1,1,0]
	v_mul_f32_e32 v38, v81, v77
	v_pk_add_f32 v[40:41], v[40:41], v[44:45] op_sel_hi:[0,1]
	v_pk_fma_f32 v[60:61], v[80:81], v[76:77], v[38:39] op_sel_hi:[1,1,0]
	v_mul_f32_e32 v38, v85, v77
	v_pk_fma_f32 v[40:41], v[152:153], v[78:79], v[40:41]
	v_pk_fma_f32 v[64:65], v[84:85], v[76:77], v[38:39] op_sel_hi:[1,1,0]
	v_mul_f32_e32 v38, v97, v77
	v_pk_fma_f32 v[84:85], v[96:97], v[76:77], v[38:39] op_sel_hi:[1,1,0]
	v_mul_f32_e32 v38, v107, v77
	v_max_f32_e32 v44, 0, v110
	v_pk_fma_f32 v[90:91], v[106:107], v[76:77], v[38:39] op_sel_hi:[1,1,0]
	v_mul_f32_e32 v38, v115, v77
	v_max_f32_e32 v45, 0, v111
	v_pk_fma_f32 v[96:97], v[114:115], v[76:77], v[38:39] op_sel_hi:[1,1,0]
	v_mul_f32_e32 v38, v123, v77
	v_pk_fma_f32 v[102:103], v[122:123], v[76:77], v[38:39] op_sel_hi:[1,1,0]
	v_mul_f32_e32 v38, v45, v77
	v_pk_fma_f32 v[44:45], v[44:45], v[76:77], v[38:39] op_sel_hi:[1,1,0]
	v_max_f32_e32 v107, 0, v112
	v_lshlrev_b32_e32 v81, 16, v39
	v_max_f32_e32 v106, 0, v113
	v_mul_f32_e32 v38, v49, v81
	v_and_b32_e32 v80, 0xffff0000, v39
	v_pk_add_f32 v[38:39], v[38:39], v[54:55] op_sel_hi:[0,1]
	v_pk_fma_f32 v[38:39], v[48:49], v[80:81], v[38:39]
	v_mul_f32_e32 v48, v57, v81
	v_mul_f32_e32 v54, v63, v81
	v_pk_add_f32 v[48:49], v[48:49], v[58:59] op_sel_hi:[0,1]
	v_pk_add_f32 v[54:55], v[54:55], v[60:61] op_sel_hi:[0,1]
	v_pk_fma_f32 v[48:49], v[56:57], v[80:81], v[48:49]
	v_pk_fma_f32 v[56:57], v[62:63], v[80:81], v[54:55]
	v_mul_f32_e32 v54, v83, v81
	v_pk_add_f32 v[54:55], v[54:55], v[64:65] op_sel_hi:[0,1]
	v_mul_f32_e32 v58, v87, v81
	v_mul_f32_e32 v60, v99, v81
	v_mul_f32_e32 v62, v109, v81
	v_mul_f32_e32 v64, v117, v81
	v_pk_fma_f32 v[54:55], v[82:83], v[80:81], v[54:55]
	v_pk_add_f32 v[58:59], v[58:59], v[84:85] op_sel_hi:[0,1]
	v_pk_add_f32 v[60:61], v[60:61], v[90:91] op_sel_hi:[0,1]
	v_pk_add_f32 v[62:63], v[62:63], v[96:97] op_sel_hi:[0,1]
	v_pk_add_f32 v[64:65], v[64:65], v[102:103] op_sel_hi:[0,1]
	v_permlane32_swap_b32_e32 v38, v56
	v_permlane32_swap_b32_e32 v48, v54
	v_pk_fma_f32 v[58:59], v[86:87], v[80:81], v[58:59]
	v_pk_fma_f32 v[60:61], v[98:99], v[80:81], v[60:61]
	v_pk_fma_f32 v[62:63], v[108:109], v[80:81], v[62:63]
	v_pk_fma_f32 v[64:65], v[116:117], v[80:81], v[64:65]
	s_nop 0
	v_permlane32_swap_b32_e32 v58, v62
	v_permlane32_swap_b32_e32 v60, v64
	v_mov_b32_e32 v61, v48
	v_mov_b32_e32 v65, v54
	v_mov_b32_e32 v59, v38
	v_mov_b32_e32 v63, v56
	v_pk_add_f32 v[54:55], v[60:61], v[64:65]
	v_pk_add_f32 v[58:59], v[58:59], v[62:63]
	ds_read_b128 v[60:63], v131 offset:20736
	ds_read_b128 v[82:85], v131 offset:20800
	s_waitcnt lgkmcnt(1)
; #define LAS __attribute__((address_space(3)))
; __device__ __forceinline__ f32x4 mfma16(bf16x8 a, bf16x8 b, f32x4 c) { return __builtin_amdgcn_mfma_f32_16x16x32_bf16(a, b, c, 0, 0, 0); }
; __device__ __forceinline__ void att_unit(LAS unsigned char* lds, const bf16* P, const bf16* AKV, const bf16* IKC, bf16* ACAT, const float* aqg, const float* ssq_ak, const float* ssq_ik, int b, int qg, int tid) {
;     ...
;                 for (int r4 = 0; r4 < 4; ++r4) {
;                     float pt[2][4];
; #pragma unroll
;                     for (int q4 = 0; q4 < 4; ++q4) {
;                         const LAS unsigned char* kp = IKc + (64 * r4 + 16 * q4 + fr) * 144 + fq * 16;
;                         const bf16x8 K0 = *(const LAS bf16x8*)kp, K1 = *(const LAS bf16x8*)(kp + 64);
; #pragma unroll
;                         for (int q = 0; q < 2; ++q) {
;                             f32x4 a = (f32x4){0.f, 0.f, 0.f, 0.f};
;                             a = mfma16(Qi[q][0], K0, a); a = mfma16(Qi[q][1], K1, a);
;                             pt[q][q4] = fmaxf(a[0], 0.f) * wv[q][0] + fmaxf(a[1], 0.f) * wv[q][1] + fmaxf(a[2], 0.f) * wv[q][2] + fmaxf(a[3], 0.f) * wv[q][3];
;                         }
;                     }
;                     const int rr = 4 * tile + r4;
;                     const float rscale = rsqrtf((rc[r4].x + rc[r4].y) * (1.f / 64.f) + EPS);
;                     const bool live = 64 * rr + lane < L;
; #pragma unroll
;                     for (int q = 0; q < 2; ++q) {
;                         float hx; const float A = half_sum32(pt[q][0], pt[q][2], hx), B = half_sum32(pt[q][1], pt[q][3], hx);
;                         const bool odd = fq & 1;
;                         const float send = odd ? A : B, keep = odd ? B : A;
;                         const float sc = live ? (keep + __shfl_xor(send, 16)) * rscale : -INFINITY;
;                         const unsigned bts = __float_as_uint(sc);
;                         uk[q][rr] = bts ^ ((unsigned)((int)bts >> 31) | 0x80000000u);
;                     }
	v_mfma_f32_16x16x32_bf16 v[96:99], v[14:17], v[60:63], 0
	v_cndmask_b32_e64 v38, v59, v55, s[6:7]
	ds_bpermute_b32 v57, v130, v38
	v_cndmask_b32_e64 v38, v58, v54, s[6:7]
	s_waitcnt lgkmcnt(1)
	v_mfma_f32_16x16x32_bf16 v[96:99], v[10:13], v[82:85], v[96:99]
	ds_bpermute_b32 v56, v130, v38
	v_mul_f32_e32 v38, v107, v81
	v_pk_add_f32 v[38:39], v[38:39], v[44:45] op_sel_hi:[0,1]
	v_mfma_f32_16x16x32_bf16 v[60:63], v[2:5], v[60:63], 0
	v_fma_f32 v38, v106, v80, v38
	v_fma_f32 v39, v107, v81, v39
	s_mov_b32 s0, 0x800000
	s_nop 0
	v_max_f32_e32 v44, 0, v96
	v_max_f32_e32 v45, 0, v97
	v_mfma_f32_16x16x32_bf16 v[60:63], v[6:9], v[82:85], v[60:63]
	v_mul_f32_e32 v48, v45, v75
	v_pk_fma_f32 v[44:45], v[44:45], v[74:75], v[48:49] op_sel_hi:[1,1,0]
	v_max_f32_e32 v49, 0, v98
	v_mul_f32_e32 v64, v49, v79
	v_max_f32_e32 v48, 0, v99
	v_pk_add_f32 v[44:45], v[64:65], v[44:45] op_sel_hi:[0,1]
	v_pk_fma_f32 v[44:45], v[48:49], v[78:79], v[44:45]
	s_nop 0
	v_max_f32_e32 v48, 0, v60
	v_max_f32_e32 v49, 0, v61
	v_mul_f32_e32 v60, v49, v77
	v_pk_fma_f32 v[48:49], v[48:49], v[76:77], v[60:61] op_sel_hi:[1,1,0]
	v_max_f32_e32 v61, 0, v62
	v_mul_f32_e32 v62, v61, v81
	v_max_f32_e32 v60, 0, v63
	v_pk_add_f32 v[48:49], v[62:63], v[48:49] op_sel_hi:[0,1]
	v_pk_fma_f32 v[48:49], v[60:61], v[80:81], v[48:49]
	ds_read_b128 v[60:63], v131 offset:23040
	ds_read_b128 v[96:99], v131 offset:23104
	s_waitcnt lgkmcnt(1)
	v_mfma_f32_16x16x32_bf16 v[82:85], v[14:17], v[60:63], 0
	v_cmp_gt_f32_e64 s[8:9], s0, v92
	v_cmp_gt_f32_e64 s[10:11], s0, v93
	v_mfma_f32_16x16x32_bf16 v[60:63], v[2:5], v[60:63], 0
	s_waitcnt lgkmcnt(0)
	v_mfma_f32_16x16x32_bf16 v[82:85], v[10:13], v[96:99], v[82:85]
	v_mfma_f32_16x16x32_bf16 v[60:63], v[6:9], v[96:99], v[60:63]
	ds_read_b128 v[96:99], v131 offset:25344
	ds_read_b128 v[106:109], v131 offset:25408
	s_nop 4
	v_max_f32_e32 v64, 0, v82
	v_max_f32_e32 v65, 0, v83
	v_mul_f32_e32 v82, v65, v75
	s_waitcnt lgkmcnt(1)
	v_mfma_f32_16x16x32_bf16 v[110:113], v[14:17], v[96:99], 0
	v_fma_f32 v64, v64, v74, v82
	v_fma_f32 v65, v65, v75, v82
	v_max_f32_e32 v83, 0, v84
	v_max_f32_e32 v82, 0, v85
	v_mul_f32_e32 v84, v83, v79
	v_max_f32_e32 v60, 0, v60
	v_pk_add_f32 v[64:65], v[84:85], v[64:65] op_sel_hi:[0,1]
	v_max_f32_e32 v61, 0, v61
	s_waitcnt lgkmcnt(0)
	v_mfma_f32_16x16x32_bf16 v[110:113], v[10:13], v[106:109], v[110:113]
	v_fma_f32 v84, v82, v78, v64
	v_fma_f32 v85, v83, v79, v65
	v_mul_f32_e32 v64, v61, v77
	v_pk_fma_f32 v[60:61], v[60:61], v[76:77], v[64:65] op_sel_hi:[1,1,0]
	v_max_f32_e32 v65, 0, v62
	v_mfma_f32_16x16x32_bf16 v[96:99], v[2:5], v[96:99], 0
	v_mul_f32_e32 v62, v65, v81
	v_max_f32_e32 v64, 0, v63
	v_pk_add_f32 v[60:61], v[62:63], v[60:61] op_sel_hi:[0,1]
	v_pk_fma_f32 v[62:63], v[64:65], v[80:81], v[60:61]
	v_max_f32_e32 v60, 0, v110
	v_max_f32_e32 v61, 0, v111
	v_mfma_f32_16x16x32_bf16 v[96:99], v[6:9], v[106:109], v[96:99]
	v_mul_f32_e32 v64, v61, v75
	v_pk_fma_f32 v[60:61], v[60:61], v[74:75], v[64:65] op_sel_hi:[1,1,0]
	v_max_f32_e32 v65, 0, v112
	v_mul_f32_e32 v82, v65, v79
	v_max_f32_e32 v64, 0, v113
	v_pk_add_f32 v[60:61], v[82:83], v[60:61] op_sel_hi:[0,1]
	v_pk_fma_f32 v[82:83], v[64:65], v[78:79], v[60:61]
	s_nop 0
	v_max_f32_e32 v60, 0, v96
	v_max_f32_e32 v61, 0, v97
	v_mul_f32_e32 v64, v61, v77
	v_pk_fma_f32 v[60:61], v[60:61], v[76:77], v[64:65] op_sel_hi:[1,1,0]
	v_max_f32_e32 v65, 0, v98
	v_max_f32_e32 v64, 0, v99
	ds_read_b128 v[96:99], v131 offset:27648
	ds_read_b128 v[106:109], v131 offset:27712
	s_waitcnt lgkmcnt(1)
	v_mfma_f32_16x16x32_bf16 v[110:113], v[14:17], v[96:99], 0
	v_mul_f32_e32 v86, v65, v81
	v_pk_add_f32 v[60:61], v[86:87], v[60:61] op_sel_hi:[0,1]
	s_waitcnt lgkmcnt(0)
	v_mfma_f32_16x16x32_bf16 v[110:113], v[10:13], v[106:109], v[110:113]
	v_fma_f32 v60, v64, v80, v60
	v_fma_f32 v61, v65, v81, v61
	v_permlane32_swap_b32_e32 v38, v62
	v_mfma_f32_16x16x32_bf16 v[96:99], v[2:5], v[96:99], 0
	v_permlane32_swap_b32_e32 v48, v60
	s_nop 2
	v_max_f32_e32 v64, 0, v110
	v_max_f32_e32 v65, 0, v111
	v_mfma_f32_16x16x32_bf16 v[96:99], v[6:9], v[106:109], v[96:99]
	v_mul_f32_e32 v86, v65, v75
	v_pk_fma_f32 v[64:65], v[64:65], v[74:75], v[86:87] op_sel_hi:[1,1,0]
	v_max_f32_e32 v87, 0, v112
	v_mul_f32_e32 v90, v87, v79
	v_max_f32_e32 v86, 0, v113
	v_pk_add_f32 v[64:65], v[90:91], v[64:65] op_sel_hi:[0,1]
	v_pk_fma_f32 v[86:87], v[86:87], v[78:79], v[64:65]
	s_nop 0
	v_max_f32_e32 v64, 0, v96
	v_max_f32_e32 v65, 0, v97
	v_mul_f32_e32 v90, v65, v77
	v_pk_fma_f32 v[64:65], v[64:65], v[76:77], v[90:91] op_sel_hi:[1,1,0]
	v_max_f32_e32 v91, 0, v98
	v_mul_f32_e32 v96, v91, v81
	v_max_f32_e32 v90, 0, v99
	v_pk_add_f32 v[64:65], v[96:97], v[64:65] op_sel_hi:[0,1]
	ds_read_b128 v[96:99], v131 offset:29952
	ds_read_b128 v[106:109], v131 offset:30016
	s_waitcnt lgkmcnt(1)
	v_mfma_f32_16x16x32_bf16 v[110:113], v[14:17], v[96:99], 0
	v_pk_fma_f32 v[64:65], v[90:91], v[80:81], v[64:65]
	v_permlane32_swap_b32_e32 v40, v84
	s_waitcnt lgkmcnt(0)
	v_mfma_f32_16x16x32_bf16 v[110:113], v[10:13], v[106:109], v[110:113]
	v_mov_b32_e32 v65, v38
	v_permlane32_swap_b32_e32 v44, v82
	v_mfma_f32_16x16x32_bf16 v[96:99], v[2:5], v[96:99], 0
	v_mov_b32_e32 v87, v40
	s_nop 3
	v_max_f32_e32 v90, 0, v110
	v_max_f32_e32 v91, 0, v111
	v_mul_f32_e32 v102, v91, v75
	v_pk_fma_f32 v[90:91], v[90:91], v[74:75], v[102:103] op_sel_hi:[1,1,0]
	v_max_f32_e32 v103, 0, v112
	v_mul_f32_e32 v110, v103, v79
	v_max_f32_e32 v102, 0, v113
	v_pk_add_f32 v[90:91], v[110:111], v[90:91] op_sel_hi:[0,1]
	v_mfma_f32_16x16x32_bf16 v[96:99], v[6:9], v[106:109], v[96:99]
	ds_read_b128 v[106:109], v131 offset:32256
	ds_read_b128 v[110:113], v131 offset:32320
	v_pk_fma_f32 v[90:91], v[102:103], v[78:79], v[90:91]
	s_waitcnt lgkmcnt(1)
; #define LAS __attribute__((address_space(3)))
; __device__ __forceinline__ f32x4 mfma16(bf16x8 a, bf16x8 b, f32x4 c) { return __builtin_amdgcn_mfma_f32_16x16x32_bf16(a, b, c, 0, 0, 0); }
; __device__ __forceinline__ void att_unit(LAS unsigned char* lds, const bf16* P, const bf16* AKV, const bf16* IKC, bf16* ACAT, const float* aqg, const float* ssq_ak, const float* ssq_ik, int b, int qg, int tid) {
;     ...
;                 for (int r4 = 0; r4 < 4; ++r4) {
;                     float pt[2][4];
; #pragma unroll
;                     for (int q4 = 0; q4 < 4; ++q4) {
;                         const LAS unsigned char* kp = IKc + (64 * r4 + 16 * q4 + fr) * 144 + fq * 16;
;                         const bf16x8 K0 = *(const LAS bf16x8*)kp, K1 = *(const LAS bf16x8*)(kp + 64);
; #pragma unroll
;                         for (int q = 0; q < 2; ++q) {
;                             f32x4 a = (f32x4){0.f, 0.f, 0.f, 0.f};
;                             a = mfma16(Qi[q][0], K0, a); a = mfma16(Qi[q][1], K1, a);
;                             pt[q][q4] = fmaxf(a[0], 0.f) * wv[q][0] + fmaxf(a[1], 0.f) * wv[q][1] + fmaxf(a[2], 0.f) * wv[q][2] + fmaxf(a[3], 0.f) * wv[q][3];
;                         }
;                     }
;                     const int rr = 4 * tile + r4;
;                     const float rscale = rsqrtf((rc[r4].x + rc[r4].y) * (1.f / 64.f) + EPS);
;                     const bool live = 64 * rr + lane < L;
; #pragma unroll
;                     for (int q = 0; q < 2; ++q) {
;                         float hx; const float A = half_sum32(pt[q][0], pt[q][2], hx), B = half_sum32(pt[q][1], pt[q][3], hx);
;                         const bool odd = fq & 1;
;                         const float send = odd ? A : B, keep = odd ? B : A;
;                         const float sc = live ? (keep + __shfl_xor(send, 16)) * rscale : -INFINITY;
;                         const unsigned bts = __float_as_uint(sc);
;                         uk[q][rr] = bts ^ ((unsigned)((int)bts >> 31) | 0x80000000u);
;                     }
;                 }
;                 if (tile + 1 < ntile) {
; #pragma unroll
;                     for (int i = 0; i < 4; ++i) *(LAS u32x4*)(IK + ((tile + 1) & 1) * 36864 + (skey + 64 * i) * 144 + spart * 16) = ikr[i];
;                 }
;                 __syncthreads();
	v_mfma_f32_16x16x32_bf16 v[114:117], v[14:17], v[106:109], 0
	s_nop 1
	s_nop 0
	v_max_f32_e32 v96, 0, v96
	s_waitcnt lgkmcnt(0)
	v_mfma_f32_16x16x32_bf16 v[114:117], v[10:13], v[110:113], v[114:117]
	v_max_f32_e32 v97, 0, v97
	v_mul_f32_e32 v102, v97, v77
	v_mfma_f32_16x16x32_bf16 v[106:109], v[2:5], v[106:109], 0
	v_fma_f32 v96, v96, v76, v102
	v_fma_f32 v97, v97, v77, v102
	v_max_f32_e32 v103, 0, v98
	v_max_f32_e32 v102, 0, v99
	v_mul_f32_e32 v98, v103, v81
	v_pk_add_f32 v[96:97], v[98:99], v[96:97] op_sel_hi:[0,1]
	v_max_f32_e32 v98, 0, v114
	v_max_f32_e32 v99, 0, v115
	v_mfma_f32_16x16x32_bf16 v[106:109], v[6:9], v[110:113], v[106:109]
	v_fma_f32 v96, v102, v80, v96
	v_fma_f32 v97, v103, v81, v97
	v_mul_f32_e32 v102, v99, v75
	v_pk_fma_f32 v[98:99], v[98:99], v[74:75], v[102:103] op_sel_hi:[1,1,0]
	v_max_f32_e32 v103, 0, v116
	v_mul_f32_e32 v114, v103, v79
	v_max_f32_e32 v102, 0, v117
	v_pk_add_f32 v[98:99], v[114:115], v[98:99] op_sel_hi:[0,1]
	v_pk_fma_f32 v[98:99], v[102:103], v[78:79], v[98:99]
	v_max_f32_e32 v102, 0, v106
	v_max_f32_e32 v103, 0, v107
	v_mul_f32_e32 v106, v103, v77
	v_pk_fma_f32 v[102:103], v[102:103], v[76:77], v[106:107] op_sel_hi:[1,1,0]
	v_max_f32_e32 v107, 0, v108
	v_mul_f32_e32 v108, v107, v81
	v_max_f32_e32 v106, 0, v109
	v_pk_add_f32 v[102:103], v[108:109], v[102:103] op_sel_hi:[0,1]
	v_pk_fma_f32 v[102:103], v[106:107], v[80:81], v[102:103]
	ds_read_b128 v[106:109], v131 offset:34560
	ds_read_b128 v[110:113], v131 offset:34624
	s_waitcnt lgkmcnt(1)
	v_mfma_f32_16x16x32_bf16 v[114:117], v[14:17], v[106:109], 0
	v_permlane32_swap_b32_e32 v64, v102
	v_mov_b32_e32 v97, v48
	s_waitcnt lgkmcnt(0)
	v_mfma_f32_16x16x32_bf16 v[114:117], v[10:13], v[110:113], v[114:117]
	v_mov_b32_e32 v103, v62
	v_pk_add_f32 v[64:65], v[64:65], v[102:103]
	v_permlane32_swap_b32_e32 v86, v98
	v_mfma_f32_16x16x32_bf16 v[106:109], v[2:5], v[106:109], 0
	s_nop 3
	v_max_f32_e32 v114, 0, v114
	v_mfma_f32_16x16x32_bf16 v[106:109], v[6:9], v[110:113], v[106:109]
	v_max_f32_e32 v115, 0, v115
	v_mul_f32_e32 v118, v115, v75
	v_pk_fma_f32 v[114:115], v[114:115], v[74:75], v[118:119] op_sel_hi:[1,1,0]
	v_max_f32_e32 v119, 0, v116
	v_max_f32_e32 v118, 0, v117
	s_nop 0
	s_nop 1
	v_max_f32_e32 v106, 0, v106
	v_max_f32_e32 v107, 0, v107
	v_mul_f32_e32 v110, v107, v77
	v_pk_fma_f32 v[106:107], v[106:107], v[76:77], v[110:111] op_sel_hi:[1,1,0]
	v_max_f32_e32 v111, 0, v108
	v_mul_f32_e32 v108, v111, v81
	v_max_f32_e32 v110, 0, v109
	v_pk_add_f32 v[106:107], v[108:109], v[106:107] op_sel_hi:[0,1]
	v_mul_f32_e32 v116, v119, v79
	v_pk_fma_f32 v[108:109], v[110:111], v[80:81], v[106:107]
	v_pk_add_f32 v[114:115], v[116:117], v[114:115] op_sel_hi:[0,1]
	s_nop 0
	v_permlane32_swap_b32_e32 v96, v108
	s_waitcnt vmcnt(8)
	v_mov_b32_e32 v106, v36
	v_mov_b32_e32 v107, v34
	v_mov_b32_e32 v34, v37
	v_mov_b32_e32 v109, v60
	v_pk_fma_f32 v[114:115], v[118:119], v[78:79], v[114:115]
	v_pk_add_f32 v[34:35], v[106:107], v[34:35]
	v_pk_add_f32 v[60:61], v[96:97], v[108:109]
	v_permlane32_swap_b32_e32 v90, v114
	v_pk_fma_f32 v[106:107], v[34:35], s[2:3], v[42:43] op_sel_hi:[1,0,0]
	v_cndmask_b32_e64 v34, v65, v61, s[6:7]
	v_mov_b32_e32 v91, v44
	v_mov_b32_e32 v115, v82
	v_mov_b32_e32 v99, v84
	ds_bpermute_b32 v63, v130, v34
	v_cndmask_b32_e64 v34, v64, v60, s[6:7]
	v_pk_add_f32 v[82:83], v[90:91], v[114:115]
	v_pk_add_f32 v[86:87], v[86:87], v[98:99]
	ds_bpermute_b32 v62, v130, v34
	v_cndmask_b32_e64 v34, v87, v83, s[6:7]
	ds_bpermute_b32 v85, v130, v34
	v_cndmask_b32_e64 v34, v86, v82, s[6:7]
	ds_bpermute_b32 v84, v130, v34
	v_cmp_gt_f32_e64 s[12:13], s0, v106
	v_cmp_gt_f32_e64 s[14:15], s0, v107
	s_movk_i32 s0, 0x1c0
	v_cmp_lt_u32_e64 s[0:1], s0, v132
	s_waitcnt vmcnt(0)
	v_mov_b64_e32 v[90:91], v[94:95]
	v_mov_b64_e32 v[96:97], v[100:101]
	v_mov_b64_e32 v[98:99], v[104:105]
	v_mov_b64_e32 v[102:103], v[46:47]
	ds_write_b128 v129, v[18:21] offset:36864
	ds_write_b128 v129, v[22:25] offset:46080
	ds_write_b128 v129, v[26:29] offset:55296
	ds_write_b128 v129, v[30:33] offset:64512
	s_waitcnt lgkmcnt(0)
	s_barrier
	s_and_saveexec_b64 s[2:3], s[0:1]
	s_cbranch_execz .LBB0_596
	v_add_co_u32_e32 v18, vcc, 0x20000, v66
	s_nop 1
	v_addc_co_u32_e32 v19, vcc, 0, v67, vcc
	v_add_co_u32_e32 v34, vcc, 0x1000, v88
	global_load_dwordx4 v[18:21], v[18:19], off
	s_nop 0
	v_addc_co_u32_e32 v35, vcc, 0, v89, vcc
	v_add_co_u32_e32 v22, vcc, 0x24000, v66
	s_nop 1
	v_addc_co_u32_e32 v23, vcc, 0, v67, vcc
	v_add_co_u32_e32 v26, vcc, 0x28000, v66
	s_nop 1
	v_addc_co_u32_e32 v27, vcc, 0, v67, vcc
	v_add_co_u32_e32 v30, vcc, 0x2c000, v66
	global_load_dwordx4 v[22:25], v[22:23], off
	s_nop 0
	global_load_dwordx4 v[26:29], v[26:27], off
	v_addc_co_u32_e32 v31, vcc, 0, v67, vcc
	global_load_dwordx4 v[30:33], v[30:31], off
	s_nop 0
	global_load_dwordx2 v[102:103], v[34:35], off
	global_load_dwordx2 v[98:99], v[34:35], off offset:512
	global_load_dwordx2 v[96:97], v[34:35], off offset:1024
	global_load_dwordx2 v[90:91], v[34:35], off offset:1536

; #define LAS __attribute__((address_space(3)))
; #define GAS __attribute__((address_space(1)))
; __device__ __forceinline__ float bflo(unsigned w) { return __uint_as_float(w << 16); }
; __device__ __forceinline__ float bfhi(unsigned w) { return __uint_as_float(w & 0xffff0000u); }
; __device__ __forceinline__ void att_core(LAS unsigned char* Vst, const LAS float* listr, const LAS unsigned* listT, const bf16* P, const bf16* AKVb, bf16* ACAT, const float* aqg, size_t tok, int cnt, int lane) {
;     const int fr = lane & 15, fq = lane >> 4;
;     const GAS unsigned char* kbase = (const GAS unsigned char*)AKVb + fr * 16;
;     const LAS unsigned* lt = listT + fq * 8;
;     u32x4 kb[3][8];
; #pragma unroll
;     for (int s2 = 0; s2 < 3; ++s2) {
;         const u32x4 o0 = *(const LAS u32x4*)(lt + s2 * 32), o1 = *(const LAS u32x4*)(lt + s2 * 32 + 4);
; #pragma unroll
;         for (int i = 0; i < 8; ++i) kb[s2][i] = *(const GAS u32x4*)(kbase + (i < 4 ? o0[i & 3] : o1[i & 3]));
;     }
;     bf16x8 Qf[4];
;     {
;         u32x4 raw[4]; float ss = 0.f;
; #pragma unroll
;         for (int kk = 0; kk < 4; ++kk) { raw[kk] = *(const GAS u32x4*)(P + tok * NP + C_AQ + fr * 128 + 32 * kk + 8 * fq);
; #pragma unroll
;             for (int e = 0; e < 4; ++e) { const float lo = bflo(raw[kk][e]), hi = bfhi(raw[kk][e]); ss += lo * lo + hi * hi; } }
;         ss += __shfl_xor(ss, 16); ss += __shfl_xor(ss, 32);
;         const float rq = rsqrtf(ss * (1.f / 128.f) + EPS) * (0.08838834764831845f * LOG2E);
; #pragma unroll
;         for (int kk = 0; kk < 4; ++kk) { const f32x4 g0 = *(const GAS f32x4*)(aqg + 32 * kk + 8 * fq), g1 = *(const GAS f32x4*)(aqg + 32 * kk + 8 * fq + 4); u32x4 o;
.LBB0_1010:
	global_load_dwordx4 v[232:235], v[162:163], off offset:16
	global_load_dwordx4 v[236:239], v[162:163], off
	global_load_dwordx4 v[240:243], v[162:163], off offset:144
	global_load_dwordx4 v[244:247], v[162:163], off offset:128
	global_load_dwordx4 v[248:251], v[162:163], off offset:272
	global_load_dwordx4 v[140:143], v[162:163], off offset:256
	global_load_dwordx4 v[144:147], v[162:163], off offset:400
	global_load_dwordx4 v[148:151], v[162:163], off offset:384
	v_lshl_add_u32 v167, s33, 10, v184
	ds_read_b128 v[2:5], v167 offset:4096
	ds_read_b128 v[6:9], v167 offset:4112
	v_cndmask_b32_e64 v0, 0, 1, s[42:43]
	v_cmp_ne_u32_e64 s[40:41], 1, v0
	v_mov_b32_e32 v0, s45
	v_or_b32_e32 v156, s33, v0
	s_waitcnt lgkmcnt(1)
	v_mov_b32_e32 v0, v2
	v_lshl_add_u64 v[10:11], v[160:161], 0, v[0:1]
	v_mov_b32_e32 v0, v3
	v_lshl_add_u64 v[2:3], v[160:161], 0, v[0:1]
	v_mov_b32_e32 v0, v4
	global_load_dwordx4 v[66:69], v[10:11], off
	global_load_dwordx4 v[70:73], v[2:3], off
	v_lshl_add_u64 v[2:3], v[160:161], 0, v[0:1]
	v_mov_b32_e32 v0, v5
	global_load_dwordx4 v[74:77], v[2:3], off
	v_lshl_add_u64 v[2:3], v[160:161], 0, v[0:1]
	s_waitcnt lgkmcnt(0)
	v_mov_b32_e32 v0, v6
	global_load_dwordx4 v[78:81], v[2:3], off
	v_lshl_add_u64 v[2:3], v[160:161], 0, v[0:1]
	v_mov_b32_e32 v0, v7
	global_load_dwordx4 v[82:85], v[2:3], off
	v_lshl_add_u64 v[2:3], v[160:161], 0, v[0:1]
	v_mov_b32_e32 v0, v8
	global_load_dwordx4 v[86:89], v[2:3], off
	v_lshl_add_u64 v[2:3], v[160:161], 0, v[0:1]
	v_mov_b32_e32 v0, v9
	global_load_dwordx4 v[90:93], v[2:3], off
	v_lshl_add_u64 v[2:3], v[160:161], 0, v[0:1]
	global_load_dwordx4 v[94:97], v[2:3], off
	ds_read_b128 v[2:5], v167 offset:4224
	ds_read_b128 v[6:9], v167 offset:4240
	v_mov_b32_e32 v98, s48
	v_mad_u64_u32 v[182:183], s[42:43], v156, s44, v[154:155]
	s_waitcnt lgkmcnt(1)
	v_mov_b32_e32 v0, v2
	v_lshl_add_u64 v[10:11], v[160:161], 0, v[0:1]
	v_mov_b32_e32 v0, v3
	v_lshl_add_u64 v[2:3], v[160:161], 0, v[0:1]
	v_mov_b32_e32 v0, v4
	global_load_dwordx4 v[34:37], v[10:11], off
	global_load_dwordx4 v[38:41], v[2:3], off
	v_lshl_add_u64 v[2:3], v[160:161], 0, v[0:1]
	v_mov_b32_e32 v0, v5
	v_mad_i32_i24 v183, v98, s44, v183
	v_mov_b32_e32 v165, v1
	global_load_dwordx4 v[42:45], v[2:3], off
	v_lshl_add_u64 v[2:3], v[160:161], 0, v[0:1]
	s_waitcnt lgkmcnt(0)
	v_mov_b32_e32 v0, v6
	v_lshl_add_u64 v[98:99], v[182:183], 0, v[164:165]
	global_load_dwordx4 v[46:49], v[2:3], off
	v_lshl_add_u64 v[2:3], v[160:161], 0, v[0:1]
	v_mov_b32_e32 v0, v7
	v_lshl_add_u64 v[100:101], v[158:159], 1, v[98:99]
	s_mov_b64 s[42:43], 0x4000
	global_load_dwordx4 v[50:53], v[2:3], off
	v_lshl_add_u64 v[2:3], v[160:161], 0, v[0:1]
	v_mov_b32_e32 v0, v8
	v_lshl_add_u64 v[98:99], v[100:101], 0, s[42:43]
	s_movk_i32 s42, 0x4000
	global_load_dwordx4 v[54:57], v[2:3], off
	v_lshl_add_u64 v[2:3], v[160:161], 0, v[0:1]
	v_mov_b32_e32 v0, v9
	v_add_co_u32_e32 v100, vcc, s42, v100
	global_load_dwordx4 v[58:61], v[2:3], off
	v_lshl_add_u64 v[2:3], v[160:161], 0, v[0:1]
	v_addc_co_u32_e32 v101, vcc, 0, v101, vcc
	global_load_dwordx4 v[62:65], v[2:3], off
	ds_read_b128 v[12:15], v167 offset:4352
	ds_read_b128 v[28:31], v167 offset:4368
	global_load_dwordx4 v[100:103], v[100:101], off
	v_lshl_add_u32 v165, s33, 11, v197
	global_load_dwordx4 v[104:107], v[98:99], off offset:64
	global_load_dwordx4 v[132:135], v[98:99], off offset:192
	s_waitcnt lgkmcnt(1)
	v_mov_b32_e32 v0, v12
	v_lshl_add_u64 v[2:3], v[160:161], 0, v[0:1]
	v_mov_b32_e32 v0, v13
	v_lshl_add_u64 v[6:7], v[160:161], 0, v[0:1]
	v_mov_b32_e32 v0, v14
	v_lshl_add_u64 v[10:11], v[160:161], 0, v[0:1]
	v_mov_b32_e32 v0, v15
	v_lshl_add_u64 v[14:15], v[160:161], 0, v[0:1]
	s_waitcnt lgkmcnt(0)
	v_mov_b32_e32 v0, v28
	v_lshl_add_u64 v[18:19], v[160:161], 0, v[0:1]
	v_mov_b32_e32 v0, v29
	v_lshl_add_u64 v[22:23], v[160:161], 0, v[0:1]
	v_mov_b32_e32 v0, v30
	v_lshl_add_u64 v[26:27], v[160:161], 0, v[0:1]
	v_mov_b32_e32 v0, v31
	v_lshl_add_u64 v[30:31], v[160:161], 0, v[0:1]
	global_load_dwordx4 v[2:5], v[2:3], off
	s_waitcnt vmcnt(3)
	v_lshlrev_b32_e32 v131, 16, v100
	v_and_b32_e32 v127, 0xffff0000, v100
	v_and_b32_e32 v100, 0xffff0000, v101
	v_mul_f32_e32 v0, v127, v127
	v_lshlrev_b32_e32 v128, 16, v101
	v_mul_f32_e32 v101, v100, v100
	v_fmac_f32_e32 v0, v131, v131
	v_fmac_f32_e32 v101, v128, v128
	v_add_f32_e32 v0, v0, v101
	v_and_b32_e32 v101, 0xffff0000, v102
	v_lshlrev_b32_e32 v129, 16, v102
	v_mul_f32_e32 v102, v101, v101
	v_fmac_f32_e32 v102, v129, v129
	v_and_b32_e32 v126, 0xffff0000, v103
	v_add_f32_e32 v0, v102, v0
	v_lshlrev_b32_e32 v130, 16, v103
	v_mul_f32_e32 v102, v126, v126
	v_fmac_f32_e32 v102, v130, v130
	v_add_f32_e32 v103, v102, v0
	s_waitcnt vmcnt(2)
	v_and_b32_e32 v0, 0xffff0000, v104
	v_lshlrev_b32_e32 v102, 16, v104
	v_mul_f32_e32 v104, v0, v0
	v_fmac_f32_e32 v104, v102, v102
	v_add_f32_e32 v104, v104, v103
	v_and_b32_e32 v103, 0xffff0000, v105
	v_lshlrev_b32_e32 v122, 16, v105
	v_mul_f32_e32 v105, v103, v103
	v_fmac_f32_e32 v105, v122, v122
	v_add_f32_e32 v105, v105, v104
	v_and_b32_e32 v104, 0xffff0000, v106
	v_lshlrev_b32_e32 v123, 16, v106
	v_mul_f32_e32 v106, v104, v104
	v_fmac_f32_e32 v106, v123, v123
	v_add_f32_e32 v106, v106, v105
	v_and_b32_e32 v105, 0xffff0000, v107
	v_lshlrev_b32_e32 v124, 16, v107
	v_mul_f32_e32 v107, v105, v105
	v_fmac_f32_e32 v107, v124, v124
	v_add_f32_e32 v114, v107, v106
	global_load_dwordx4 v[106:109], v[98:99], off offset:128
	s_waitcnt vmcnt(2)
; #define LAS __attribute__((address_space(3)))
; #define GAS __attribute__((address_space(1)))
; __device__ __forceinline__ void att_core(LAS unsigned char* Vst, const LAS float* listr, const LAS unsigned* listT, const bf16* P, const bf16* AKVb, bf16* ACAT, const float* aqg, size_t tok, int cnt, int lane) {
;     ...
;     bf16x8 Qf[4];
;     {
;         u32x4 raw[4]; float ss = 0.f;
; #pragma unroll
;         for (int kk = 0; kk < 4; ++kk) { raw[kk] = *(const GAS u32x4*)(P + tok * NP + C_AQ + fr * 128 + 32 * kk + 8 * fq);
; #pragma unroll
;             for (int e = 0; e < 4; ++e) { const float lo = bflo(raw[kk][e]), hi = bfhi(raw[kk][e]); ss += lo * lo + hi * hi; } }
;         ss += __shfl_xor(ss, 16); ss += __shfl_xor(ss, 32);
;         const float rq = rsqrtf(ss * (1.f / 128.f) + EPS) * (0.08838834764831845f * LOG2E);
; #pragma unroll
;         for (int kk = 0; kk < 4; ++kk) { const f32x4 g0 = *(const GAS f32x4*)(aqg + 32 * kk + 8 * fq), g1 = *(const GAS f32x4*)(aqg + 32 * kk + 8 * fq + 4); u32x4 o;
;             o.x = pk2(bflo(raw[kk].x) * rq * g0.x, bfhi(raw[kk].x) * rq * g0.y); o.y = pk2(bflo(raw[kk].y) * rq * g0.z, bfhi(raw[kk].y) * rq * g0.w);
;             o.z = pk2(bflo(raw[kk].z) * rq * g1.x, bfhi(raw[kk].z) * rq * g1.y); o.w = pk2(bflo(raw[kk].w) * rq * g1.z, bfhi(raw[kk].w) * rq * g1.w);
;             Qf[kk] = __builtin_bit_cast(bf16x8, o); }
;     }
;     f32x4 lg[16];
;     float mx = -INFINITY;
; #pragma unroll
;     for (int st = 0; st < 8; ++st) {
; #pragma unroll
;         for (int i = 0; i < 8; ++i) *(LAS u32x4*)(Vst + (4 * i + fq) * 272 + fr * 16) = kb[st % 3][i];
;         __builtin_amdgcn_fence(__ATOMIC_RELEASE, "wavefront"); __builtin_amdgcn_wave_barrier();
;         bf16x8 Kf[2][4];
; #pragma unroll
;         for (int gg = 0; gg < 2; ++gg)
; #pragma unroll
;             for (int kk = 0; kk < 4; ++kk) Kf[gg][kk] = *(const LAS bf16x8*)(Vst + (16 * gg + fr) * 272 + kk * 64 + fq * 16);
;         const f32x4 lr0 = *(const LAS f32x4*)(listr + 32 * st + 4 * fq), lr1 = *(const LAS f32x4*)(listr + 32 * st + 16 + 4 * fq);
;         if (st + 3 < 8) {
;             const u32x4 o0 = *(const LAS u32x4*)(lt + (st + 3) * 32), o1 = *(const LAS u32x4*)(lt + (st + 3) * 32 + 4);
; #pragma unroll
;             for (int i = 0; i < 8; ++i) kb[st % 3][i] = *(const GAS u32x4*)(kbase + (i < 4 ? o0[i & 3] : o1[i & 3]));
	v_and_b32_e32 v119, 0xffff0000, v133
	v_and_b32_e32 v118, 0xffff0000, v132
	v_lshlrev_b32_e32 v121, 16, v133
	v_lshlrev_b32_e32 v120, 16, v132
	v_pk_mul_f32 v[98:99], v[118:119], v[118:119]
	global_load_dwordx4 v[6:9], v[6:7], off
	v_pk_fma_f32 v[98:99], v[120:121], v[120:121], v[98:99]
	global_load_dwordx4 v[10:13], v[10:11], off
	v_lshlrev_b32_e32 v117, 16, v135
	global_load_dwordx4 v[14:17], v[14:15], off
	s_waitcnt vmcnt(3)
	v_lshlrev_b32_e32 v113, 16, v107
	v_lshlrev_b32_e32 v112, 16, v106
	v_and_b32_e32 v107, 0xffff0000, v107
	v_and_b32_e32 v106, 0xffff0000, v106
	v_pk_mul_f32 v[110:111], v[106:107], v[106:107]
	global_load_dwordx4 v[18:21], v[18:19], off
	v_pk_fma_f32 v[110:111], v[112:113], v[112:113], v[110:111]
	global_load_dwordx4 v[22:25], v[22:23], off
	v_add_f32_e32 v110, v110, v114
	v_add_f32_e32 v116, v111, v110
	v_lshlrev_b32_e32 v111, 16, v109
	v_lshlrev_b32_e32 v110, 16, v108
	v_and_b32_e32 v109, 0xffff0000, v109
	v_and_b32_e32 v108, 0xffff0000, v108
	v_pk_mul_f32 v[114:115], v[108:109], v[108:109]
	global_load_dwordx4 v[26:29], v[26:27], off
	v_pk_fma_f32 v[114:115], v[110:111], v[110:111], v[114:115]
	global_load_dwordx4 v[30:33], v[30:31], off
	v_add_f32_e32 v114, v114, v116
	v_add_f32_e32 v114, v115, v114
	v_add_f32_e32 v98, v98, v114
	v_lshlrev_b32_e32 v116, 16, v134
	v_and_b32_e32 v115, 0xffff0000, v135
	v_and_b32_e32 v114, 0xffff0000, v134
	v_mov_b64_e32 v[132:133], v[232:233]
	v_mov_b64_e32 v[134:135], v[234:235]
	v_mov_b64_e32 v[136:137], v[236:237]
	v_mov_b64_e32 v[138:139], v[238:239]
	v_add_f32_e32 v125, v99, v98
	v_pk_mul_f32 v[98:99], v[114:115], v[114:115]
	s_nop 0
	v_pk_fma_f32 v[98:99], v[116:117], v[116:117], v[98:99]
	s_nop 0
	v_add_f32_e32 v98, v98, v125
	v_add_f32_e32 v98, v99, v98
	ds_bpermute_b32 v99, v185, v98
	s_waitcnt lgkmcnt(0)
	v_add_f32_e32 v98, v98, v99
	ds_bpermute_b32 v99, v194, v98
	s_waitcnt lgkmcnt(0)
	v_add_f32_e32 v98, v98, v99
	v_fmamk_f32 v98, v98, 0x3c000000, v222
	v_cmp_gt_f32_e32 vcc, s49, v98
	v_mul_f32_e32 v99, 0x4b800000, v98
	s_nop 0
	v_cndmask_b32_e32 v98, v98, v99, vcc
	v_rsq_f32_e32 v98, v98
	s_nop 0
	v_mul_f32_e32 v99, 0x45800000, v98
	v_cndmask_b32_e32 v98, v98, v99, vcc
	v_mul_f32_e32 v125, 0x3e0293ee, v98
	v_mul_f32_e32 v98, v125, v131
	v_mul_f32_e32 v99, v125, v127
	v_mul_f32_e32 v100, v125, v100
	v_mul_f32_e32 v101, v125, v101
	v_mul_f32_e32 v126, v125, v126
	v_mul_f32_e32 v102, v125, v102
	v_mul_f32_e32 v0, v125, v0
	v_mul_f32_e32 v103, v125, v103
	v_mul_f32_e32 v104, v125, v104
	v_mul_f32_e32 v105, v125, v105
	v_mul_f32_e32 v106, v125, v106
	v_mul_f32_e32 v107, v125, v107
	v_mul_f32_e32 v108, v125, v108
	v_mul_f32_e32 v109, v125, v109
	s_waitcnt vmcnt(1)
	v_mul_f32_e32 v101, v133, v101
	s_waitcnt vmcnt(0)
	v_mul_f32_e32 v98, v136, v98
	v_mul_f32_e32 v99, v137, v99
	v_cvt_pk_bf16_f32 v98, v98, v99
	v_mul_f32_e32 v99, v125, v128
	v_mul_f32_e32 v99, v138, v99
	v_mul_f32_e32 v100, v139, v100
	v_cvt_pk_bf16_f32 v99, v99, v100
	v_mul_f32_e32 v100, v125, v129
	v_mul_f32_e32 v100, v132, v100
	v_cvt_pk_bf16_f32 v100, v100, v101
	v_mul_f32_e32 v101, v125, v130
	v_mul_f32_e32 v101, v134, v101
	v_mul_f32_e32 v126, v135, v126
	v_cvt_pk_bf16_f32 v101, v101, v126
	v_mov_b64_e32 v[126:127], v[240:241]
	v_mov_b64_e32 v[128:129], v[242:243]
	v_mov_b64_e32 v[130:131], v[244:245]
	v_mov_b64_e32 v[132:133], v[246:247]
	s_waitcnt vmcnt(1)
	v_mul_f32_e32 v104, v127, v104
	s_waitcnt vmcnt(0)
	v_mul_f32_e32 v102, v130, v102
	v_mul_f32_e32 v0, v131, v0
	v_cvt_pk_bf16_f32 v102, v102, v0
	v_mul_f32_e32 v0, v125, v122
	v_mul_f32_e32 v0, v132, v0
	v_mul_f32_e32 v103, v133, v103
	v_cvt_pk_bf16_f32 v103, v0, v103
	v_mul_f32_e32 v0, v125, v123
	v_mul_f32_e32 v0, v126, v0
	v_cvt_pk_bf16_f32 v104, v0, v104
	v_mul_f32_e32 v0, v125, v124
	v_mul_f32_e32 v0, v128, v0
	v_mul_f32_e32 v105, v129, v105
	v_mov_b64_e32 v[126:127], v[248:249]
	v_mov_b64_e32 v[128:129], v[250:251]
	v_mov_b64_e32 v[130:131], v[140:141]
	v_mov_b64_e32 v[132:133], v[142:143]
	v_cvt_pk_bf16_f32 v105, v0, v105
	v_mul_f32_e32 v0, v125, v112
	s_waitcnt vmcnt(1)
	v_mul_f32_e32 v108, v127, v108
	s_waitcnt vmcnt(0)
	v_mul_f32_e32 v0, v130, v0
	v_mul_f32_e32 v106, v131, v106
	v_cvt_pk_bf16_f32 v106, v0, v106
	v_mul_f32_e32 v0, v125, v113
	v_mul_f32_e32 v0, v132, v0
	v_mul_f32_e32 v107, v133, v107
	v_cvt_pk_bf16_f32 v107, v0, v107
	v_mul_f32_e32 v0, v125, v110
	v_mul_f32_e32 v0, v126, v0
	v_cvt_pk_bf16_f32 v108, v0, v108
	v_mul_f32_e32 v0, v125, v111
	v_mul_f32_e32 v0, v128, v0
	v_mul_f32_e32 v109, v129, v109
	v_mov_b64_e32 v[126:127], v[144:145]
	v_mov_b64_e32 v[128:129], v[146:147]
	v_mov_b64_e32 v[110:111], v[148:149]
	v_mov_b64_e32 v[112:113], v[150:151]
	v_cvt_pk_bf16_f32 v109, v0, v109
	v_mul_f32_e32 v0, v125, v120
	ds_write_b128 v198, v[66:69]
	ds_write_b128 v198, v[70:73] offset:1088
	ds_write_b128 v198, v[74:77] offset:2176
	ds_write_b128 v198, v[78:81] offset:3264
	ds_write_b128 v198, v[82:85] offset:4352
	ds_write_b128 v198, v[86:89] offset:5440
	ds_write_b128 v198, v[90:93] offset:6528
	ds_write_b128 v198, v[94:97] offset:7616
	s_waitcnt vmcnt(0)
	v_mul_f32_e32 v0, v110, v0
	v_mul_f32_e32 v110, v125, v118
	v_mul_f32_e32 v110, v111, v110
	v_cvt_pk_bf16_f32 v110, v0, v110
	v_mul_f32_e32 v0, v125, v121
	v_mul_f32_e32 v111, v125, v119
	v_mul_f32_e32 v0, v112, v0
	v_mul_f32_e32 v111, v113, v111
	v_cvt_pk_bf16_f32 v111, v0, v111
	v_mul_f32_e32 v0, v125, v116
	v_mul_f32_e32 v112, v125, v114
	v_mul_f32_e32 v0, v126, v0
	v_mul_f32_e32 v112, v127, v112
	v_cvt_pk_bf16_f32 v112, v0, v112
	v_mul_f32_e32 v0, v125, v117
	v_mul_f32_e32 v113, v125, v115
	v_mul_f32_e32 v0, v128, v0
	v_mul_f32_e32 v113, v129, v113
	ds_read_b128 v[138:141], v199
	ds_read_b128 v[142:145], v199 offset:64
	ds_read_b128 v[146:149], v199 offset:128
	ds_read_b128 v[150:153], v199 offset:192
	ds_read_b128 v[134:137], v199 offset:4352
	ds_read_b128 v[130:133], v199 offset:4416
	ds_read_b128 v[122:125], v199 offset:4480
	ds_read_b128 v[118:121], v199 offset:4544
	ds_read_b128 v[126:129], v165 offset:1024
	ds_read_b128 v[114:117], v165 offset:1088
	ds_read_b128 v[76:79], v167 offset:4480
	ds_read_b128 v[92:95], v167 offset:4496
	v_cvt_pk_bf16_f32 v113, v0, v113
	s_waitcnt lgkmcnt(1)
; #define LAS __attribute__((address_space(3)))
; #define GAS __attribute__((address_space(1)))
; __device__ __forceinline__ f32x4 mfma16(bf16x8 a, bf16x8 b, f32x4 c) { return __builtin_amdgcn_mfma_f32_16x16x32_bf16(a, b, c, 0, 0, 0); }
; __device__ __forceinline__ void att_core(LAS unsigned char* Vst, const LAS float* listr, const LAS unsigned* listT, const bf16* P, const bf16* AKVb, bf16* ACAT, const float* aqg, size_t tok, int cnt, int lane) {
;     ...
;     for (int st = 0; st < 8; ++st) {
; #pragma unroll
;         for (int i = 0; i < 8; ++i) *(LAS u32x4*)(Vst + (4 * i + fq) * 272 + fr * 16) = kb[st % 3][i];
;         __builtin_amdgcn_fence(__ATOMIC_RELEASE, "wavefront"); __builtin_amdgcn_wave_barrier();
;         bf16x8 Kf[2][4];
; #pragma unroll
;         for (int gg = 0; gg < 2; ++gg)
; #pragma unroll
;             for (int kk = 0; kk < 4; ++kk) Kf[gg][kk] = *(const LAS bf16x8*)(Vst + (16 * gg + fr) * 272 + kk * 64 + fq * 16);
;         const f32x4 lr0 = *(const LAS f32x4*)(listr + 32 * st + 4 * fq), lr1 = *(const LAS f32x4*)(listr + 32 * st + 16 + 4 * fq);
;         if (st + 3 < 8) {
;             const u32x4 o0 = *(const LAS u32x4*)(lt + (st + 3) * 32), o1 = *(const LAS u32x4*)(lt + (st + 3) * 32 + 4);
; #pragma unroll
;             for (int i = 0; i < 8; ++i) kb[st % 3][i] = *(const GAS u32x4*)(kbase + (i < 4 ? o0[i & 3] : o1[i & 3]));
;         }
;         __builtin_amdgcn_sched_barrier(0);
; #pragma unroll
;         for (int gg = 0; gg < 2; ++gg) {
;             const int g = 2 * st + gg;
;             f32x4 a = (f32x4){0.f, 0.f, 0.f, 0.f};
; #pragma unroll
;             for (int kk = 0; kk < 4; ++kk) a = mfma16(Kf[gg][kk], Qf[kk], a);
;             const f32x4 lr = gg ? lr1 : lr0;
; #pragma unroll
;             for (int r = 0; r < 4; ++r) lg[g][r] = (16 * g + 4 * fq + r < cnt) ? a[r] * lr[r] : -INFINITY;
;             mx = fmaxf(mx, fmaxf(fmaxf(lg[g][0], lg[g][1]), fmaxf(lg[g][2], lg[g][3])));
;         }
;         __builtin_amdgcn_fence(__ATOMIC_RELEASE, "wavefront"); __builtin_amdgcn_wave_barrier();
;         __builtin_amdgcn_sched_barrier(0);
;     }
	v_mov_b32_e32 v0, v76
	v_lshl_add_u64 v[66:67], v[160:161], 0, v[0:1]
	v_mov_b32_e32 v0, v77
	v_lshl_add_u64 v[70:71], v[160:161], 0, v[0:1]
	v_mov_b32_e32 v0, v78
	v_lshl_add_u64 v[74:75], v[160:161], 0, v[0:1]
	v_mov_b32_e32 v0, v79
	v_lshl_add_u64 v[78:79], v[160:161], 0, v[0:1]
	s_waitcnt lgkmcnt(0)
	v_mov_b32_e32 v0, v92
	v_lshl_add_u64 v[82:83], v[160:161], 0, v[0:1]
	v_mov_b32_e32 v0, v93
	v_lshl_add_u64 v[86:87], v[160:161], 0, v[0:1]
	v_mov_b32_e32 v0, v94
	v_lshl_add_u64 v[90:91], v[160:161], 0, v[0:1]
	v_mov_b32_e32 v0, v95
	v_lshl_add_u64 v[94:95], v[160:161], 0, v[0:1]
	global_load_dwordx4 v[66:69], v[66:67], off
	s_nop 0
	global_load_dwordx4 v[70:73], v[70:71], off
	s_nop 0
	global_load_dwordx4 v[74:77], v[74:75], off
	s_nop 0
	global_load_dwordx4 v[78:81], v[78:79], off
	s_nop 0
	global_load_dwordx4 v[82:85], v[82:83], off
	s_nop 0
	global_load_dwordx4 v[86:89], v[86:87], off
	s_nop 0
	global_load_dwordx4 v[90:93], v[90:91], off
	s_nop 0
	global_load_dwordx4 v[94:97], v[94:95], off
	v_mfma_f32_16x16x32_bf16 v[138:141], v[138:141], v[98:101], 0
	v_readlane_b32 s42, v254, 47
	v_readlane_b32 s43, v254, 48
	s_mov_b32 s33, 0xff800000
	v_mfma_f32_16x16x32_bf16 v[138:141], v[142:145], v[102:105], v[138:141]
	v_mfma_f32_16x16x32_bf16 v[138:141], v[146:149], v[106:109], v[138:141]
	v_mfma_f32_16x16x32_bf16 v[134:137], v[134:137], v[98:101], 0
	v_mfma_f32_16x16x32_bf16 v[138:141], v[150:153], v[110:113], v[138:141]
	v_mfma_f32_16x16x32_bf16 v[130:133], v[130:133], v[102:105], v[134:137]
	v_mfma_f32_16x16x32_bf16 v[130:133], v[122:125], v[106:109], v[130:133]
	s_nop 5
	v_mul_f32_e32 v0, v126, v138
	v_cndmask_b32_e64 v126, v231, v0, s[42:43]
	v_readlane_b32 s42, v254, 49
	v_mul_f32_e32 v0, v127, v139
	v_readlane_b32 s43, v254, 50
	v_mfma_f32_16x16x32_bf16 v[118:121], v[118:121], v[110:113], v[130:133]
	s_nop 0
	v_cndmask_b32_e64 v127, v231, v0, s[42:43]
	v_readlane_b32 s42, v254, 51
	v_mul_f32_e32 v0, v128, v140
	v_readlane_b32 s43, v254, 52
	s_nop 2
	v_mul_f32_e32 v114, v114, v118
	v_mul_f32_e32 v115, v115, v119
	v_cndmask_b32_e64 v128, v231, v0, s[42:43]
	v_readlane_b32 s42, v254, 53
	v_mul_f32_e32 v0, v129, v141
	v_readlane_b32 s43, v254, 54
	v_mul_f32_e32 v116, v116, v120
	v_mul_f32_e32 v117, v117, v121
	v_cndmask_b32_e64 v122, v231, v0, s[42:43]
	v_readlane_b32 s42, v254, 55
	v_readlane_b32 s43, v254, 56
	v_max_f32_e32 v0, v128, v122
	v_max3_f32 v0, v126, v127, v0
	v_cndmask_b32_e64 v114, v231, v114, s[42:43]
	v_readlane_b32 s42, v254, 57
	v_readlane_b32 s43, v254, 58
	s_nop 1
	v_cndmask_b32_e64 v115, v231, v115, s[42:43]
	v_readlane_b32 s42, v254, 59
	v_readlane_b32 s43, v254, 60
	s_nop 1
	v_cndmask_b32_e64 v116, v231, v116, s[42:43]
	v_readlane_b32 s42, v254, 61
	v_readlane_b32 s43, v254, 62
	s_nop 1
	v_cndmask_b32_e64 v117, v231, v117, s[42:43]
	v_max_f32_e32 v118, v116, v117
	v_max3_f32 v118, v114, v115, v118
	v_max3_f32 v169, v0, s33, v118
	ds_write_b128 v198, v[34:37]
	ds_write_b128 v198, v[38:41] offset:1088
	ds_write_b128 v198, v[42:45] offset:2176
	ds_write_b128 v198, v[46:49] offset:3264
	ds_write_b128 v198, v[50:53] offset:4352
	ds_write_b128 v198, v[54:57] offset:5440
	ds_write_b128 v198, v[58:61] offset:6528
	ds_write_b128 v198, v[62:65] offset:7616
	ds_read_b128 v[40:43], v167 offset:4608
	ds_read_b128 v[56:59], v167 offset:4624
	s_waitcnt lgkmcnt(1)
	v_mov_b32_e32 v0, v40
	v_lshl_add_u64 v[34:35], v[160:161], 0, v[0:1]
	v_mov_b32_e32 v0, v41
	v_lshl_add_u64 v[38:39], v[160:161], 0, v[0:1]
	v_mov_b32_e32 v0, v42
	v_lshl_add_u64 v[44:45], v[160:161], 0, v[0:1]
	v_mov_b32_e32 v0, v43
	v_lshl_add_u64 v[46:47], v[160:161], 0, v[0:1]
	s_waitcnt lgkmcnt(0)
	v_mov_b32_e32 v0, v56
	v_lshl_add_u64 v[50:51], v[160:161], 0, v[0:1]
	v_mov_b32_e32 v0, v57
	v_lshl_add_u64 v[54:55], v[160:161], 0, v[0:1]
	v_mov_b32_e32 v0, v58
	v_lshl_add_u64 v[60:61], v[160:161], 0, v[0:1]
	v_mov_b32_e32 v0, v59
	v_lshl_add_u64 v[62:63], v[160:161], 0, v[0:1]
	global_load_dwordx4 v[34:37], v[34:35], off
	s_nop 0
	global_load_dwordx4 v[38:41], v[38:39], off
	s_nop 0
	global_load_dwordx4 v[42:45], v[44:45], off
	s_nop 0
	global_load_dwordx4 v[46:49], v[46:47], off
	s_nop 0
	global_load_dwordx4 v[50:53], v[50:51], off
	s_nop 0
	global_load_dwordx4 v[54:57], v[54:55], off
	s_nop 0
	global_load_dwordx4 v[58:61], v[60:61], off
	s_nop 0
	global_load_dwordx4 v[62:65], v[62:63], off
	ds_read_b128 v[118:121], v199
	ds_read_b128 v[130:133], v199 offset:64
	ds_read_b128 v[134:137], v199 offset:128
	ds_read_b128 v[138:141], v199 offset:192
	ds_read_b128 v[142:145], v199 offset:4352
	ds_read_b128 v[146:149], v199 offset:4416
	ds_read_b128 v[150:153], v199 offset:4480
	ds_read_b128 v[210:213], v199 offset:4544
	ds_read_b128 v[214:217], v165 offset:1152
	ds_read_b128 v[232:235], v165 offset:1216
	s_waitcnt lgkmcnt(9)
	v_mfma_f32_16x16x32_bf16 v[118:121], v[118:121], v[98:101], 0
	v_readlane_b32 s42, v254, 63
	v_readlane_b32 s43, v252, 0
	s_waitcnt lgkmcnt(8)
	v_mfma_f32_16x16x32_bf16 v[118:121], v[130:133], v[102:105], v[118:121]
	s_waitcnt lgkmcnt(7)
	v_mfma_f32_16x16x32_bf16 v[118:121], v[134:137], v[106:109], v[118:121]
	s_waitcnt lgkmcnt(5)
	v_mfma_f32_16x16x32_bf16 v[130:133], v[142:145], v[98:101], 0
	v_mfma_f32_16x16x32_bf16 v[118:121], v[138:141], v[110:113], v[118:121]
	s_waitcnt lgkmcnt(4)
	v_mfma_f32_16x16x32_bf16 v[130:133], v[146:149], v[102:105], v[130:133]
	s_waitcnt lgkmcnt(3)
	v_mfma_f32_16x16x32_bf16 v[130:133], v[150:153], v[106:109], v[130:133]
	s_waitcnt lgkmcnt(1)
; #define LAS __attribute__((address_space(3)))
; #define GAS __attribute__((address_space(1)))
; __device__ __forceinline__ f32x4 mfma16(bf16x8 a, bf16x8 b, f32x4 c) { return __builtin_amdgcn_mfma_f32_16x16x32_bf16(a, b, c, 0, 0, 0); }
; __device__ __forceinline__ void att_core(LAS unsigned char* Vst, const LAS float* listr, const LAS unsigned* listT, const bf16* P, const bf16* AKVb, bf16* ACAT, const float* aqg, size_t tok, int cnt, int lane) {
;     ...
;     for (int st = 0; st < 8; ++st) {
; #pragma unroll
;         for (int i = 0; i < 8; ++i) *(LAS u32x4*)(Vst + (4 * i + fq) * 272 + fr * 16) = kb[st % 3][i];
;         __builtin_amdgcn_fence(__ATOMIC_RELEASE, "wavefront"); __builtin_amdgcn_wave_barrier();
;         bf16x8 Kf[2][4];
; #pragma unroll
;         for (int gg = 0; gg < 2; ++gg)
; #pragma unroll
;             for (int kk = 0; kk < 4; ++kk) Kf[gg][kk] = *(const LAS bf16x8*)(Vst + (16 * gg + fr) * 272 + kk * 64 + fq * 16);
;         const f32x4 lr0 = *(const LAS f32x4*)(listr + 32 * st + 4 * fq), lr1 = *(const LAS f32x4*)(listr + 32 * st + 16 + 4 * fq);
;         if (st + 3 < 8) {
;             const u32x4 o0 = *(const LAS u32x4*)(lt + (st + 3) * 32), o1 = *(const LAS u32x4*)(lt + (st + 3) * 32 + 4);
; #pragma unroll
;             for (int i = 0; i < 8; ++i) kb[st % 3][i] = *(const GAS u32x4*)(kbase + (i < 4 ? o0[i & 3] : o1[i & 3]));
;         }
;         __builtin_amdgcn_sched_barrier(0);
; #pragma unroll
;         for (int gg = 0; gg < 2; ++gg) {
;             const int g = 2 * st + gg;
;             f32x4 a = (f32x4){0.f, 0.f, 0.f, 0.f};
; #pragma unroll
;             for (int kk = 0; kk < 4; ++kk) a = mfma16(Kf[gg][kk], Qf[kk], a);
;             const f32x4 lr = gg ? lr1 : lr0;
; #pragma unroll
;             for (int r = 0; r < 4; ++r) lg[g][r] = (16 * g + 4 * fq + r < cnt) ? a[r] * lr[r] : -INFINITY;
;             mx = fmaxf(mx, fmaxf(fmaxf(lg[g][0], lg[g][1]), fmaxf(lg[g][2], lg[g][3])));
;         }
;         __builtin_amdgcn_fence(__ATOMIC_RELEASE, "wavefront"); __builtin_amdgcn_wave_barrier();
;         __builtin_amdgcn_sched_barrier(0);
;     }
	s_nop 2
	v_mul_f32_e32 v0, v214, v118
	v_cndmask_b32_e64 v118, v231, v0, s[42:43]
	v_readlane_b32 s42, v252, 1
	v_mul_f32_e32 v0, v215, v119
	v_readlane_b32 s43, v252, 2
	v_mfma_f32_16x16x32_bf16 v[130:133], v[210:213], v[110:113], v[130:133]
	s_nop 0
	v_cndmask_b32_e64 v119, v231, v0, s[42:43]
	v_readlane_b32 s42, v252, 3
	v_mul_f32_e32 v0, v216, v120
	v_readlane_b32 s43, v252, 4
	s_waitcnt lgkmcnt(0)
	s_nop 1
	v_mul_f32_e32 v123, v232, v130
	v_mul_f32_e32 v124, v233, v131
	v_cndmask_b32_e64 v120, v231, v0, s[42:43]
	v_readlane_b32 s42, v252, 5
	v_mul_f32_e32 v0, v217, v121
	v_readlane_b32 s43, v252, 6
	v_mul_f32_e32 v125, v234, v132
	v_mul_f32_e32 v129, v235, v133
	v_cndmask_b32_e64 v121, v231, v0, s[42:43]
	v_readlane_b32 s42, v252, 7
	v_readlane_b32 s43, v252, 8
	v_max_f32_e32 v0, v120, v121
	v_max3_f32 v0, v118, v119, v0
	v_cndmask_b32_e64 v123, v231, v123, s[42:43]
	v_readlane_b32 s42, v252, 9
	v_readlane_b32 s43, v252, 10
	s_nop 1
	v_cndmask_b32_e64 v124, v231, v124, s[42:43]
	v_readlane_b32 s42, v252, 11
	v_readlane_b32 s43, v252, 12
	s_nop 1
	v_cndmask_b32_e64 v125, v231, v125, s[42:43]
	v_readlane_b32 s42, v252, 13
	v_readlane_b32 s43, v252, 14
	s_nop 1
	v_cndmask_b32_e64 v129, v231, v129, s[42:43]
	v_max_f32_e32 v130, v125, v129
	v_max3_f32 v130, v123, v124, v130
	v_max3_f32 v169, v169, v0, v130
	ds_write_b128 v198, v[2:5]
	ds_write_b128 v198, v[6:9] offset:1088
	ds_write_b128 v198, v[10:13] offset:2176
	ds_write_b128 v198, v[14:17] offset:3264
	ds_write_b128 v198, v[18:21] offset:4352
	ds_write_b128 v198, v[22:25] offset:5440
	ds_write_b128 v198, v[26:29] offset:6528
	ds_write_b128 v198, v[30:33] offset:7616
	ds_read_b128 v[8:11], v167 offset:4736
	ds_read_b128 v[24:27], v167 offset:4752
	s_waitcnt lgkmcnt(1)
	v_mov_b32_e32 v0, v8
	v_lshl_add_u64 v[2:3], v[160:161], 0, v[0:1]
	v_mov_b32_e32 v0, v9
	v_lshl_add_u64 v[6:7], v[160:161], 0, v[0:1]
	v_mov_b32_e32 v0, v10
	v_lshl_add_u64 v[12:13], v[160:161], 0, v[0:1]
	v_mov_b32_e32 v0, v11
	v_lshl_add_u64 v[14:15], v[160:161], 0, v[0:1]
	s_waitcnt lgkmcnt(0)
	v_mov_b32_e32 v0, v24
	v_lshl_add_u64 v[18:19], v[160:161], 0, v[0:1]
	v_mov_b32_e32 v0, v25
	v_lshl_add_u64 v[22:23], v[160:161], 0, v[0:1]
	v_mov_b32_e32 v0, v26
	v_lshl_add_u64 v[28:29], v[160:161], 0, v[0:1]
	v_mov_b32_e32 v0, v27
	v_lshl_add_u64 v[30:31], v[160:161], 0, v[0:1]
	global_load_dwordx4 v[2:5], v[2:3], off
	s_nop 0
	global_load_dwordx4 v[6:9], v[6:7], off
	s_nop 0
	global_load_dwordx4 v[10:13], v[12:13], off
	s_nop 0
	global_load_dwordx4 v[14:17], v[14:15], off
	s_nop 0
	global_load_dwordx4 v[18:21], v[18:19], off
	s_nop 0
	global_load_dwordx4 v[22:25], v[22:23], off
	s_nop 0
	global_load_dwordx4 v[26:29], v[28:29], off
	s_nop 0
	global_load_dwordx4 v[30:33], v[30:31], off
	ds_read_b128 v[130:133], v199
	ds_read_b128 v[134:137], v199 offset:64
	ds_read_b128 v[138:141], v199 offset:128
	ds_read_b128 v[142:145], v199 offset:192
	ds_read_b128 v[146:149], v199 offset:4352
	ds_read_b128 v[150:153], v199 offset:4416
	ds_read_b128 v[210:213], v199 offset:4480
	ds_read_b128 v[214:217], v199 offset:4544
	ds_read_b128 v[232:235], v165 offset:1280
	ds_read_b128 v[236:239], v165 offset:1344
	s_waitcnt lgkmcnt(9)
	v_mfma_f32_16x16x32_bf16 v[130:133], v[130:133], v[98:101], 0
	v_readlane_b32 s42, v252, 15
	v_readlane_b32 s43, v252, 16
	s_waitcnt lgkmcnt(8)
	v_mfma_f32_16x16x32_bf16 v[130:133], v[134:137], v[102:105], v[130:133]
	s_waitcnt lgkmcnt(7)
	v_mfma_f32_16x16x32_bf16 v[130:133], v[138:141], v[106:109], v[130:133]
	s_waitcnt lgkmcnt(5)
	v_mfma_f32_16x16x32_bf16 v[138:141], v[146:149], v[98:101], 0
	v_mfma_f32_16x16x32_bf16 v[134:137], v[142:145], v[110:113], v[130:133]
	s_waitcnt lgkmcnt(4)
	v_mfma_f32_16x16x32_bf16 v[138:141], v[150:153], v[102:105], v[138:141]
	s_waitcnt lgkmcnt(3)
	v_mfma_f32_16x16x32_bf16 v[138:141], v[210:213], v[106:109], v[138:141]
	s_waitcnt lgkmcnt(1)
	s_nop 2
	v_mul_f32_e32 v0, v232, v134
	v_cndmask_b32_e64 v132, v231, v0, s[42:43]
	v_readlane_b32 s42, v252, 17
	v_mul_f32_e32 v0, v233, v135
	v_readlane_b32 s43, v252, 18
	v_mfma_f32_16x16x32_bf16 v[138:141], v[214:217], v[110:113], v[138:141]
	s_nop 0
	v_cndmask_b32_e64 v133, v231, v0, s[42:43]
	v_readlane_b32 s42, v252, 19
	v_mul_f32_e32 v0, v234, v136
	v_readlane_b32 s43, v252, 20
	s_waitcnt lgkmcnt(0)
	s_nop 1
	v_mul_f32_e32 v130, v236, v138
	v_cndmask_b32_e64 v135, v231, v0, s[42:43]
	v_readlane_b32 s42, v252, 21
	v_mul_f32_e32 v0, v235, v137
	v_readlane_b32 s43, v252, 22
	s_nop 1
	v_cndmask_b32_e64 v136, v231, v0, s[42:43]
	v_readlane_b32 s42, v252, 23
	v_readlane_b32 s43, v252, 24
	v_max_f32_e32 v0, v135, v136
	v_max3_f32 v0, v132, v133, v0
	v_cndmask_b32_e64 v137, v231, v130, s[42:43]
	v_mul_f32_e32 v130, v237, v139
	v_cndmask_b32_e64 v134, v231, v130, s[50:51]
	v_mul_f32_e32 v130, v238, v140
	v_cndmask_b32_e64 v131, v231, v130, s[52:53]
	v_mul_f32_e32 v130, v239, v141
	v_cndmask_b32_e64 v130, v231, v130, s[54:55]
	v_max_f32_e32 v138, v131, v130
	v_max3_f32 v138, v137, v134, v138
	v_max3_f32 v175, v169, v0, v138
	s_waitcnt vmcnt(23)
	ds_write_b128 v198, v[66:69]
	s_waitcnt vmcnt(22)
	ds_write_b128 v198, v[70:73] offset:1088
	s_waitcnt vmcnt(21)
	ds_write_b128 v198, v[74:77] offset:2176
	s_waitcnt vmcnt(20)
	ds_write_b128 v198, v[78:81] offset:3264
	s_waitcnt vmcnt(19)
	ds_write_b128 v198, v[82:85] offset:4352
	s_waitcnt vmcnt(18)
	ds_write_b128 v198, v[86:89] offset:5440
	s_waitcnt vmcnt(17)
	ds_write_b128 v198, v[90:93] offset:6528
	s_waitcnt vmcnt(16)
	ds_write_b128 v198, v[94:97] offset:7616
	ds_read_b128 v[66:69], v167 offset:4864
	ds_read_b128 v[70:73], v167 offset:4880
	s_waitcnt lgkmcnt(1)
; #define LAS __attribute__((address_space(3)))
; #define GAS __attribute__((address_space(1)))
; __device__ __forceinline__ f32x4 mfma16(bf16x8 a, bf16x8 b, f32x4 c) { return __builtin_amdgcn_mfma_f32_16x16x32_bf16(a, b, c, 0, 0, 0); }
; __device__ __forceinline__ void att_core(LAS unsigned char* Vst, const LAS float* listr, const LAS unsigned* listT, const bf16* P, const bf16* AKVb, bf16* ACAT, const float* aqg, size_t tok, int cnt, int lane) {
;     ...
;     for (int st = 0; st < 8; ++st) {
; #pragma unroll
;         for (int i = 0; i < 8; ++i) *(LAS u32x4*)(Vst + (4 * i + fq) * 272 + fr * 16) = kb[st % 3][i];
;         __builtin_amdgcn_fence(__ATOMIC_RELEASE, "wavefront"); __builtin_amdgcn_wave_barrier();
;         bf16x8 Kf[2][4];
; #pragma unroll
;         for (int gg = 0; gg < 2; ++gg)
; #pragma unroll
;             for (int kk = 0; kk < 4; ++kk) Kf[gg][kk] = *(const LAS bf16x8*)(Vst + (16 * gg + fr) * 272 + kk * 64 + fq * 16);
;         const f32x4 lr0 = *(const LAS f32x4*)(listr + 32 * st + 4 * fq), lr1 = *(const LAS f32x4*)(listr + 32 * st + 16 + 4 * fq);
;         if (st + 3 < 8) {
;             const u32x4 o0 = *(const LAS u32x4*)(lt + (st + 3) * 32), o1 = *(const LAS u32x4*)(lt + (st + 3) * 32 + 4);
; #pragma unroll
;             for (int i = 0; i < 8; ++i) kb[st % 3][i] = *(const GAS u32x4*)(kbase + (i < 4 ? o0[i & 3] : o1[i & 3]));
;         }
;         __builtin_amdgcn_sched_barrier(0);
; #pragma unroll
;         for (int gg = 0; gg < 2; ++gg) {
;             const int g = 2 * st + gg;
;             f32x4 a = (f32x4){0.f, 0.f, 0.f, 0.f};
; #pragma unroll
;             for (int kk = 0; kk < 4; ++kk) a = mfma16(Kf[gg][kk], Qf[kk], a);
;             const f32x4 lr = gg ? lr1 : lr0;
; #pragma unroll
;             for (int r = 0; r < 4; ++r) lg[g][r] = (16 * g + 4 * fq + r < cnt) ? a[r] * lr[r] : -INFINITY;
;             mx = fmaxf(mx, fmaxf(fmaxf(lg[g][0], lg[g][1]), fmaxf(lg[g][2], lg[g][3])));
;         }
;         __builtin_amdgcn_fence(__ATOMIC_RELEASE, "wavefront"); __builtin_amdgcn_wave_barrier();
;         __builtin_amdgcn_sched_barrier(0);
;     }
	v_mov_b32_e32 v0, v66
	v_lshl_add_u64 v[74:75], v[160:161], 0, v[0:1]
	v_mov_b32_e32 v0, v67
	v_lshl_add_u64 v[66:67], v[160:161], 0, v[0:1]
	v_mov_b32_e32 v0, v68
	global_load_dwordx4 v[74:77], v[74:75], off
	s_nop 0
	global_load_dwordx4 v[78:81], v[66:67], off
	v_lshl_add_u64 v[66:67], v[160:161], 0, v[0:1]
	v_mov_b32_e32 v0, v69
	v_lshl_add_u64 v[82:83], v[160:161], 0, v[0:1]
	s_waitcnt lgkmcnt(0)
	v_mov_b32_e32 v0, v70
	v_lshl_add_u64 v[86:87], v[160:161], 0, v[0:1]
	v_mov_b32_e32 v0, v71
	v_lshl_add_u64 v[70:71], v[160:161], 0, v[0:1]
	v_mov_b32_e32 v0, v72
	global_load_dwordx4 v[66:69], v[66:67], off
	s_nop 0
	global_load_dwordx4 v[82:85], v[82:83], off
	s_nop 0
	global_load_dwordx4 v[86:89], v[86:87], off
	s_nop 0
	global_load_dwordx4 v[90:93], v[70:71], off
	v_lshl_add_u64 v[70:71], v[160:161], 0, v[0:1]
	v_mov_b32_e32 v0, v73
	v_lshl_add_u64 v[94:95], v[160:161], 0, v[0:1]
	global_load_dwordx4 v[70:73], v[70:71], off
	s_nop 0
	global_load_dwordx4 v[94:97], v[94:95], off
	ds_read_b128 v[138:141], v199
	ds_read_b128 v[142:145], v199 offset:64
	ds_read_b128 v[146:149], v199 offset:128
	ds_read_b128 v[150:153], v199 offset:192
	ds_read_b128 v[210:213], v199 offset:4352
	ds_read_b128 v[214:217], v199 offset:4416
	ds_read_b128 v[232:235], v199 offset:4480
	ds_read_b128 v[236:239], v199 offset:4544
	ds_read_b128 v[240:243], v165 offset:1408
	ds_read_b128 v[244:247], v165 offset:1472
	s_waitcnt lgkmcnt(9)
	v_mfma_f32_16x16x32_bf16 v[138:141], v[138:141], v[98:101], 0
	s_waitcnt lgkmcnt(8)
	v_mfma_f32_16x16x32_bf16 v[138:141], v[142:145], v[102:105], v[138:141]
	s_waitcnt lgkmcnt(7)
	v_mfma_f32_16x16x32_bf16 v[138:141], v[146:149], v[106:109], v[138:141]
	s_waitcnt lgkmcnt(5)
	v_mfma_f32_16x16x32_bf16 v[142:145], v[210:213], v[98:101], 0
	v_mfma_f32_16x16x32_bf16 v[138:141], v[150:153], v[110:113], v[138:141]
	s_waitcnt lgkmcnt(4)
	v_mfma_f32_16x16x32_bf16 v[142:145], v[214:217], v[102:105], v[142:145]
	s_waitcnt lgkmcnt(1)
	s_nop 4
	v_mul_f32_e32 v0, v240, v138
	v_cndmask_b32_e64 v173, v231, v0, s[56:57]
	v_mul_f32_e32 v0, v241, v139
	v_cndmask_b32_e64 v171, v231, v0, s[58:59]
	v_mul_f32_e32 v0, v242, v140
	v_cndmask_b32_e64 v169, v231, v0, s[60:61]
	v_mul_f32_e32 v0, v243, v141
	v_mfma_f32_16x16x32_bf16 v[138:141], v[232:235], v[106:109], v[142:145]
	v_cndmask_b32_e64 v153, v231, v0, s[62:63]
	v_max_f32_e32 v0, v169, v153
	v_max3_f32 v0, v173, v171, v0
	v_mfma_f32_16x16x32_bf16 v[138:141], v[236:239], v[110:113], v[138:141]
	s_waitcnt lgkmcnt(0)
	s_nop 6
	v_mul_f32_e32 v138, v244, v138
	v_cndmask_b32_e64 v152, v231, v138, s[64:65]
	v_mul_f32_e32 v138, v245, v139
	v_cndmask_b32_e64 v151, v231, v138, s[66:67]
	v_mul_f32_e32 v138, v246, v140
	v_cndmask_b32_e64 v150, v231, v138, s[68:69]
	v_mul_f32_e32 v138, v247, v141
	v_cndmask_b32_e64 v149, v231, v138, s[70:71]
	v_max_f32_e32 v138, v150, v149
	v_max3_f32 v138, v152, v151, v138
	v_max3_f32 v146, v175, v0, v138
	s_waitcnt vmcnt(23)
	ds_write_b128 v198, v[34:37]
	s_waitcnt vmcnt(22)
	ds_write_b128 v198, v[38:41] offset:1088
	s_waitcnt vmcnt(21)
	ds_write_b128 v198, v[42:45] offset:2176
	s_waitcnt vmcnt(20)
	ds_write_b128 v198, v[46:49] offset:3264
	s_waitcnt vmcnt(19)
	ds_write_b128 v198, v[50:53] offset:4352
	s_waitcnt vmcnt(18)
	ds_write_b128 v198, v[54:57] offset:5440
	s_waitcnt vmcnt(17)
	ds_write_b128 v198, v[58:61] offset:6528
	s_waitcnt vmcnt(16)
	ds_write_b128 v198, v[62:65] offset:7616
	ds_read_b128 v[34:37], v167 offset:4992
	ds_read_b128 v[38:41], v167 offset:5008
	s_waitcnt lgkmcnt(1)
	v_mov_b32_e32 v0, v34
	v_lshl_add_u64 v[42:43], v[160:161], 0, v[0:1]
	v_mov_b32_e32 v0, v35
	v_lshl_add_u64 v[34:35], v[160:161], 0, v[0:1]
	v_mov_b32_e32 v0, v36
	global_load_dwordx4 v[42:45], v[42:43], off
	s_nop 0
	global_load_dwordx4 v[46:49], v[34:35], off
	v_lshl_add_u64 v[34:35], v[160:161], 0, v[0:1]
	v_mov_b32_e32 v0, v37
	v_lshl_add_u64 v[50:51], v[160:161], 0, v[0:1]
	s_waitcnt lgkmcnt(0)
	v_mov_b32_e32 v0, v38
	v_lshl_add_u64 v[54:55], v[160:161], 0, v[0:1]
	v_mov_b32_e32 v0, v39
	v_lshl_add_u64 v[38:39], v[160:161], 0, v[0:1]
	v_mov_b32_e32 v0, v40
	global_load_dwordx4 v[34:37], v[34:35], off
	s_nop 0
	global_load_dwordx4 v[50:53], v[50:51], off
	s_nop 0
	global_load_dwordx4 v[54:57], v[54:55], off
	s_nop 0
	global_load_dwordx4 v[58:61], v[38:39], off
	v_lshl_add_u64 v[38:39], v[160:161], 0, v[0:1]
	v_mov_b32_e32 v0, v41
	v_lshl_add_u64 v[62:63], v[160:161], 0, v[0:1]
	global_load_dwordx4 v[38:41], v[38:39], off
	s_nop 0
	global_load_dwordx4 v[62:65], v[62:63], off
	ds_read_b128 v[138:141], v199
	ds_read_b128 v[142:145], v199 offset:64
	ds_read_b128 v[210:213], v199 offset:128
	ds_read_b128 v[214:217], v199 offset:192
	ds_read_b128 v[232:235], v199 offset:4352
	ds_read_b128 v[236:239], v199 offset:4416
	ds_read_b128 v[240:243], v199 offset:4480
	ds_read_b128 v[244:247], v199 offset:4544
	ds_read_b128 v[248:251], v165 offset:1536
	ds_read_b128 v[190:193], v165 offset:1600
	s_waitcnt lgkmcnt(9)
	v_mfma_f32_16x16x32_bf16 v[138:141], v[138:141], v[98:101], 0
	s_waitcnt lgkmcnt(8)
	v_mfma_f32_16x16x32_bf16 v[138:141], v[142:145], v[102:105], v[138:141]
	s_waitcnt lgkmcnt(5)
	v_mfma_f32_16x16x32_bf16 v[142:145], v[232:235], v[98:101], 0
	v_mfma_f32_16x16x32_bf16 v[138:141], v[210:213], v[106:109], v[138:141]
	s_waitcnt lgkmcnt(4)
	v_mfma_f32_16x16x32_bf16 v[142:145], v[236:239], v[102:105], v[142:145]
	v_mfma_f32_16x16x32_bf16 v[138:141], v[214:217], v[110:113], v[138:141]
	s_waitcnt lgkmcnt(3)
	v_mfma_f32_16x16x32_bf16 v[142:145], v[240:243], v[106:109], v[142:145]
	s_waitcnt lgkmcnt(1)
; #define LAS __attribute__((address_space(3)))
; #define GAS __attribute__((address_space(1)))
; __device__ __forceinline__ f32x4 mfma16(bf16x8 a, bf16x8 b, f32x4 c) { return __builtin_amdgcn_mfma_f32_16x16x32_bf16(a, b, c, 0, 0, 0); }
; __device__ __forceinline__ void att_core(LAS unsigned char* Vst, const LAS float* listr, const LAS unsigned* listT, const bf16* P, const bf16* AKVb, bf16* ACAT, const float* aqg, size_t tok, int cnt, int lane) {
;     ...
;     for (int st = 0; st < 8; ++st) {
; #pragma unroll
;         for (int i = 0; i < 8; ++i) *(LAS u32x4*)(Vst + (4 * i + fq) * 272 + fr * 16) = kb[st % 3][i];
;         __builtin_amdgcn_fence(__ATOMIC_RELEASE, "wavefront"); __builtin_amdgcn_wave_barrier();
;         bf16x8 Kf[2][4];
; #pragma unroll
;         for (int gg = 0; gg < 2; ++gg)
; #pragma unroll
;             for (int kk = 0; kk < 4; ++kk) Kf[gg][kk] = *(const LAS bf16x8*)(Vst + (16 * gg + fr) * 272 + kk * 64 + fq * 16);
;         const f32x4 lr0 = *(const LAS f32x4*)(listr + 32 * st + 4 * fq), lr1 = *(const LAS f32x4*)(listr + 32 * st + 16 + 4 * fq);
;         if (st + 3 < 8) {
;             const u32x4 o0 = *(const LAS u32x4*)(lt + (st + 3) * 32), o1 = *(const LAS u32x4*)(lt + (st + 3) * 32 + 4);
; #pragma unroll
;             for (int i = 0; i < 8; ++i) kb[st % 3][i] = *(const GAS u32x4*)(kbase + (i < 4 ? o0[i & 3] : o1[i & 3]));
;         }
;         __builtin_amdgcn_sched_barrier(0);
; #pragma unroll
;         for (int gg = 0; gg < 2; ++gg) {
;             const int g = 2 * st + gg;
;             f32x4 a = (f32x4){0.f, 0.f, 0.f, 0.f};
; #pragma unroll
;             for (int kk = 0; kk < 4; ++kk) a = mfma16(Kf[gg][kk], Qf[kk], a);
;             const f32x4 lr = gg ? lr1 : lr0;
; #pragma unroll
;             for (int r = 0; r < 4; ++r) lg[g][r] = (16 * g + 4 * fq + r < cnt) ? a[r] * lr[r] : -INFINITY;
;             mx = fmaxf(mx, fmaxf(fmaxf(lg[g][0], lg[g][1]), fmaxf(lg[g][2], lg[g][3])));
;         }
;         __builtin_amdgcn_fence(__ATOMIC_RELEASE, "wavefront"); __builtin_amdgcn_wave_barrier();
;         __builtin_amdgcn_sched_barrier(0);
;     }
	s_nop 4
	v_mul_f32_e32 v0, v248, v138
	v_cndmask_b32_e64 v211, v231, v0, s[72:73]
	v_mul_f32_e32 v0, v249, v139
	v_cndmask_b32_e64 v212, v231, v0, s[74:75]
	v_mul_f32_e32 v0, v250, v140
	v_cndmask_b32_e64 v210, v231, v0, s[76:77]
	v_mul_f32_e32 v0, v251, v141
	v_mfma_f32_16x16x32_bf16 v[138:141], v[244:247], v[110:113], v[142:145]
	v_cndmask_b32_e64 v209, v231, v0, s[78:79]
	s_waitcnt lgkmcnt(0)
	s_nop 5
	v_mul_f32_e32 v0, v190, v138
	v_cndmask_b32_e64 v181, v231, v0, s[80:81]
	v_mul_f32_e32 v0, v191, v139
	v_cndmask_b32_e64 v179, v231, v0, s[82:83]
	v_mul_f32_e32 v0, v192, v140
	v_cndmask_b32_e64 v177, v231, v0, s[84:85]
	v_mul_f32_e32 v0, v193, v141
	v_cndmask_b32_e64 v175, v231, v0, s[86:87]
	s_waitcnt vmcnt(23)
	ds_write_b128 v198, v[2:5]
	s_waitcnt vmcnt(22)
	ds_write_b128 v198, v[6:9] offset:1088
	s_waitcnt vmcnt(21)
	ds_write_b128 v198, v[10:13] offset:2176
	s_waitcnt vmcnt(20)
	ds_write_b128 v198, v[14:17] offset:3264
	s_waitcnt vmcnt(19)
	ds_write_b128 v198, v[18:21] offset:4352
	s_waitcnt vmcnt(18)
	ds_write_b128 v198, v[22:25] offset:5440
	s_waitcnt vmcnt(17)
	ds_write_b128 v198, v[26:29] offset:6528
	s_waitcnt vmcnt(16)
	ds_write_b128 v198, v[30:33] offset:7616
	ds_read_b128 v[2:5], v165 offset:1728
	ds_read_b128 v[6:9], v165 offset:1664
	ds_read_b128 v[10:13], v199 offset:4544
	ds_read_b128 v[14:17], v199 offset:4480
	ds_read_b128 v[18:21], v199 offset:4416
	ds_read_b128 v[22:25], v199 offset:4352
	ds_read_b128 v[26:29], v199 offset:192
	ds_read_b128 v[30:33], v199 offset:128
	ds_read_b128 v[138:141], v199 offset:64
	ds_read_b128 v[142:145], v199
	s_waitcnt lgkmcnt(0)
	v_mfma_f32_16x16x32_bf16 v[142:145], v[142:145], v[98:101], 0
	v_mfma_f32_16x16x32_bf16 v[138:141], v[138:141], v[102:105], v[142:145]
	v_mfma_f32_16x16x32_bf16 v[22:25], v[22:25], v[98:101], 0
	v_mfma_f32_16x16x32_bf16 v[30:33], v[30:33], v[106:109], v[138:141]
	v_mfma_f32_16x16x32_bf16 v[18:21], v[18:21], v[102:105], v[22:25]
	v_mfma_f32_16x16x32_bf16 v[26:29], v[26:29], v[110:113], v[30:33]
	v_mfma_f32_16x16x32_bf16 v[14:17], v[14:17], v[106:109], v[18:21]
	s_nop 6
	v_mul_f32_e32 v0, v6, v26
	v_cndmask_b32_e64 v190, v231, v0, s[88:89]
	v_mul_f32_e32 v0, v7, v27
	v_cndmask_b32_e64 v191, v231, v0, s[90:91]
	v_mul_f32_e32 v0, v8, v28
	v_cndmask_b32_e64 v192, v231, v0, s[92:93]
	v_mul_f32_e32 v0, v9, v29
	v_mfma_f32_16x16x32_bf16 v[6:9], v[10:13], v[110:113], v[14:17]
	v_cndmask_b32_e64 v193, v231, v0, s[94:95]
	s_nop 6
	v_mul_f32_e32 v0, v2, v6
	v_cndmask_b32_e64 v213, v231, v0, s[96:97]
	v_mul_f32_e32 v0, v3, v7
	v_cndmask_b32_e64 v214, v231, v0, s[4:5]
	v_mul_f32_e32 v0, v4, v8
	v_cndmask_b32_e64 v215, v231, v0, s[0:1]
	v_mul_f32_e32 v0, v5, v9
	v_cndmask_b32_e64 v216, v231, v0, s[2:3]
	s_waitcnt vmcnt(15)
	ds_write_b128 v198, v[74:77]
	s_waitcnt vmcnt(14)
	ds_write_b128 v198, v[78:81] offset:1088
	s_waitcnt vmcnt(13)
	ds_write_b128 v198, v[66:69] offset:2176
	s_waitcnt vmcnt(12)
	ds_write_b128 v198, v[82:85] offset:3264
	s_waitcnt vmcnt(11)
	ds_write_b128 v198, v[86:89] offset:4352
	s_waitcnt vmcnt(10)
	ds_write_b128 v198, v[90:93] offset:5440
	s_waitcnt vmcnt(9)
	ds_write_b128 v198, v[70:73] offset:6528
	s_waitcnt vmcnt(8)
	ds_write_b128 v198, v[94:97] offset:7616
	ds_read_b128 v[2:5], v165 offset:1856
	ds_read_b128 v[6:9], v165 offset:1792
	ds_read_b128 v[10:13], v199 offset:4544
	ds_read_b128 v[14:17], v199 offset:4480
	ds_read_b128 v[18:21], v199 offset:4416
	ds_read_b128 v[22:25], v199 offset:4352
	ds_read_b128 v[26:29], v199 offset:192
	ds_read_b128 v[30:33], v199 offset:128
	ds_read_b128 v[66:69], v199 offset:64
	ds_read_b128 v[70:73], v199
	s_waitcnt lgkmcnt(0)
	v_mfma_f32_16x16x32_bf16 v[70:73], v[70:73], v[98:101], 0
	v_mfma_f32_16x16x32_bf16 v[66:69], v[66:69], v[102:105], v[70:73]
	v_mfma_f32_16x16x32_bf16 v[22:25], v[22:25], v[98:101], 0
	v_mfma_f32_16x16x32_bf16 v[30:33], v[30:33], v[106:109], v[66:69]
	v_mfma_f32_16x16x32_bf16 v[18:21], v[18:21], v[102:105], v[22:25]
	v_mfma_f32_16x16x32_bf16 v[26:29], v[26:29], v[110:113], v[30:33]
	v_mfma_f32_16x16x32_bf16 v[14:17], v[14:17], v[106:109], v[18:21]
	s_nop 6
	v_mul_f32_e32 v0, v6, v26
	v_cndmask_b32_e64 v217, v231, v0, s[6:7]
	v_mul_f32_e32 v0, v7, v27
	v_cndmask_b32_e64 v218, v231, v0, s[8:9]
	v_mul_f32_e32 v0, v8, v28
	v_cndmask_b32_e64 v219, v231, v0, s[10:11]
	v_mul_f32_e32 v0, v9, v29
	v_mfma_f32_16x16x32_bf16 v[6:9], v[10:13], v[110:113], v[14:17]
	v_cndmask_b32_e64 v232, v231, v0, s[12:13]
	s_nop 6
	v_mul_f32_e32 v0, v2, v6
	v_cndmask_b32_e64 v233, v231, v0, s[14:15]
	v_mul_f32_e32 v0, v3, v7
	v_cndmask_b32_e64 v140, v231, v0, s[16:17]
	v_mul_f32_e32 v0, v4, v8
	v_cndmask_b32_e64 v138, v231, v0, s[18:19]
	v_mul_f32_e32 v0, v5, v9
	v_cndmask_b32_e64 v139, v231, v0, s[20:21]
	s_waitcnt vmcnt(7)
	ds_write_b128 v198, v[42:45]
	s_waitcnt vmcnt(6)
	ds_write_b128 v198, v[46:49] offset:1088
	s_waitcnt vmcnt(5)
	ds_write_b128 v198, v[34:37] offset:2176
	s_waitcnt vmcnt(4)
	ds_write_b128 v198, v[50:53] offset:3264
	s_waitcnt vmcnt(3)
	ds_write_b128 v198, v[54:57] offset:4352
	s_waitcnt vmcnt(2)
	ds_write_b128 v198, v[58:61] offset:5440
	s_waitcnt vmcnt(1)
	ds_write_b128 v198, v[38:41] offset:6528
	s_waitcnt vmcnt(0)
	ds_write_b128 v198, v[62:65] offset:7616
	ds_read_b128 v[2:5], v165 offset:1984
	ds_read_b128 v[6:9], v165 offset:1920
	ds_read_b128 v[10:13], v199 offset:4544
	ds_read_b128 v[14:17], v199 offset:4480
	ds_read_b128 v[18:21], v199 offset:4416
	ds_read_b128 v[22:25], v199 offset:4352
	ds_read_b128 v[26:29], v199 offset:192
	ds_read_b128 v[30:33], v199 offset:128
	ds_read_b128 v[34:37], v199 offset:64
	ds_read_b128 v[38:41], v199
	v_max_f32_e32 v0, v210, v209
	v_max_f32_e32 v42, v177, v175
	v_max3_f32 v0, v211, v212, v0
	v_max3_f32 v42, v181, v179, v42
	v_max3_f32 v0, v146, v0, v42
	v_max_f32_e32 v42, v192, v193
	v_max_f32_e32 v43, v215, v216
	v_max3_f32 v42, v190, v191, v42
	v_max3_f32 v43, v213, v214, v43
	v_max3_f32 v0, v0, v42, v43
	v_max_f32_e32 v42, v219, v232
	v_max_f32_e32 v43, v138, v139
	v_max3_f32 v42, v217, v218, v42
	v_max3_f32 v43, v233, v140, v43
	v_max3_f32 v165, v0, v42, v43
	s_waitcnt lgkmcnt(0)
; #define LAS __attribute__((address_space(3)))
; #define GAS __attribute__((address_space(1)))
; __device__ __forceinline__ f32x4 mfma16(bf16x8 a, bf16x8 b, f32x4 c) { return __builtin_amdgcn_mfma_f32_16x16x32_bf16(a, b, c, 0, 0, 0); }
; __device__ __forceinline__ void att_core(LAS unsigned char* Vst, const LAS float* listr, const LAS unsigned* listT, const bf16* P, const bf16* AKVb, bf16* ACAT, const float* aqg, size_t tok, int cnt, int lane) {
;     ...
; #pragma unroll
;         for (int gg = 0; gg < 2; ++gg) {
;             const int g = 2 * st + gg;
;             f32x4 a = (f32x4){0.f, 0.f, 0.f, 0.f};
; #pragma unroll
;             for (int kk = 0; kk < 4; ++kk) a = mfma16(Kf[gg][kk], Qf[kk], a);
;             const f32x4 lr = gg ? lr1 : lr0;
; #pragma unroll
;             for (int r = 0; r < 4; ++r) lg[g][r] = (16 * g + 4 * fq + r < cnt) ? a[r] * lr[r] : -INFINITY;
;             mx = fmaxf(mx, fmaxf(fmaxf(lg[g][0], lg[g][1]), fmaxf(lg[g][2], lg[g][3])));
;         }
;         __builtin_amdgcn_fence(__ATOMIC_RELEASE, "wavefront"); __builtin_amdgcn_wave_barrier();
;         __builtin_amdgcn_sched_barrier(0);
;     }
;     u32x4 vb[3][8];
; #pragma unroll
;     for (int s2 = 0; s2 < 3; ++s2) {
;         const u32x4 o0 = *(const LAS u32x4*)(lt + s2 * 32), o1 = *(const LAS u32x4*)(lt + s2 * 32 + 4);
; #pragma unroll
;         for (int i = 0; i < 8; ++i) vb[s2][i] = *(const GAS u32x4*)(kbase + 256 + (i < 4 ? o0[i & 3] : o1[i & 3]));
;     }
;     mx = fmaxf(mx, __shfl_xor(mx, 16)); mx = fmaxf(mx, __shfl_xor(mx, 32));
	v_mfma_f32_16x16x32_bf16 v[38:41], v[38:41], v[98:101], 0
	v_mfma_f32_16x16x32_bf16 v[34:37], v[34:37], v[102:105], v[38:41]
	v_mfma_f32_16x16x32_bf16 v[30:33], v[30:33], v[106:109], v[34:37]
	v_mfma_f32_16x16x32_bf16 v[22:25], v[22:25], v[98:101], 0
	v_mfma_f32_16x16x32_bf16 v[26:29], v[26:29], v[110:113], v[30:33]
	v_mfma_f32_16x16x32_bf16 v[18:21], v[18:21], v[102:105], v[22:25]
	s_nop 6
	v_mul_f32_e32 v0, v6, v26
	v_cndmask_b32_e64 v141, v231, v0, s[22:23]
	v_mul_f32_e32 v0, v7, v27
	v_cndmask_b32_e64 v142, v231, v0, s[24:25]
	v_mul_f32_e32 v0, v8, v28
	v_cndmask_b32_e64 v143, v231, v0, s[26:27]
	v_mul_f32_e32 v0, v9, v29
	v_mfma_f32_16x16x32_bf16 v[6:9], v[14:17], v[106:109], v[18:21]
	v_cndmask_b32_e64 v148, v231, v0, s[28:29]
	v_max_f32_e32 v0, v143, v148
	v_max3_f32 v28, v141, v142, v0
	v_mfma_f32_16x16x32_bf16 v[6:9], v[10:13], v[110:113], v[6:9]
	s_nop 7
	v_mul_f32_e32 v0, v2, v6
	v_cndmask_b32_e64 v144, v231, v0, s[30:31]
	v_mul_f32_e32 v0, v3, v7
	v_cndmask_b32_e64 v145, v231, v0, s[34:35]
	v_mul_f32_e32 v0, v4, v8
	v_cndmask_b32_e64 v146, v231, v0, s[36:37]
	v_mul_f32_e32 v0, v5, v9
	v_cndmask_b32_e64 v147, v231, v0, s[38:39]
	v_max_f32_e32 v0, v146, v147
	v_max3_f32 v29, v144, v145, v0
	ds_read_b128 v[8:11], v167 offset:4096
	ds_read_b128 v[12:15], v167 offset:4112
	v_max3_f32 v38, v165, v28, v29
	ds_bpermute_b32 v39, v185, v38
	s_waitcnt lgkmcnt(2)
	v_mov_b32_e32 v0, v8
	v_lshl_add_u64 v[2:3], v[160:161], 0, v[0:1]
	v_mov_b32_e32 v0, v9
	v_lshl_add_u64 v[6:7], v[160:161], 0, v[0:1]
	v_mov_b32_e32 v0, v10
	v_lshl_add_u64 v[16:17], v[160:161], 0, v[0:1]
	v_mov_b32_e32 v0, v11
	v_lshl_add_u64 v[10:11], v[160:161], 0, v[0:1]
	s_waitcnt lgkmcnt(1)
	v_mov_b32_e32 v0, v12
	global_load_dwordx4 v[2:5], v[2:3], off offset:256
	s_nop 0
	global_load_dwordx4 v[6:9], v[6:7], off offset:256
	s_nop 0
	global_load_dwordx4 v[42:45], v[16:17], off offset:256
	global_load_dwordx4 v[78:81], v[10:11], off offset:256
	v_lshl_add_u64 v[10:11], v[160:161], 0, v[0:1]
	v_mov_b32_e32 v0, v13
	v_lshl_add_u64 v[12:13], v[160:161], 0, v[0:1]
	global_load_dwordx4 v[82:85], v[10:11], off offset:256
	global_load_dwordx4 v[86:89], v[12:13], off offset:256
	ds_read_b128 v[10:13], v167 offset:4224
	v_mov_b32_e32 v0, v14
	v_lshl_add_u64 v[16:17], v[160:161], 0, v[0:1]
	v_mov_b32_e32 v0, v15
	v_lshl_add_u64 v[14:15], v[160:161], 0, v[0:1]
	global_load_dwordx4 v[90:93], v[16:17], off offset:256
	global_load_dwordx4 v[94:97], v[14:15], off offset:256
	ds_read_b128 v[14:17], v167 offset:4240
	s_waitcnt lgkmcnt(1)
	v_mov_b32_e32 v0, v10
	v_lshl_add_u64 v[18:19], v[160:161], 0, v[0:1]
	v_mov_b32_e32 v0, v11
	v_lshl_add_u64 v[10:11], v[160:161], 0, v[0:1]
	v_mov_b32_e32 v0, v12
	global_load_dwordx4 v[46:49], v[18:19], off offset:256
	global_load_dwordx4 v[50:53], v[10:11], off offset:256
	v_lshl_add_u64 v[10:11], v[160:161], 0, v[0:1]
	v_mov_b32_e32 v0, v13
	v_lshl_add_u64 v[12:13], v[160:161], 0, v[0:1]
	s_waitcnt lgkmcnt(0)
	v_mov_b32_e32 v0, v14
	global_load_dwordx4 v[54:57], v[10:11], off offset:256
	global_load_dwordx4 v[58:61], v[12:13], off offset:256
	v_lshl_add_u64 v[10:11], v[160:161], 0, v[0:1]
	v_mov_b32_e32 v0, v15
	v_lshl_add_u64 v[12:13], v[160:161], 0, v[0:1]
	v_mov_b32_e32 v0, v16
	global_load_dwordx4 v[62:65], v[10:11], off offset:256
	global_load_dwordx4 v[66:69], v[12:13], off offset:256
	v_lshl_add_u64 v[10:11], v[160:161], 0, v[0:1]
	v_mov_b32_e32 v0, v17
	ds_read_b128 v[16:19], v167 offset:4352
	v_lshl_add_u64 v[12:13], v[160:161], 0, v[0:1]
	global_load_dwordx4 v[70:73], v[10:11], off offset:256
	global_load_dwordx4 v[74:77], v[12:13], off offset:256
	ds_read_b128 v[32:35], v167 offset:4368
	s_waitcnt lgkmcnt(1)
	v_mov_b32_e32 v0, v16
	v_lshl_add_u64 v[10:11], v[160:161], 0, v[0:1]
	v_mov_b32_e32 v0, v17
	v_lshl_add_u64 v[14:15], v[160:161], 0, v[0:1]
	v_mov_b32_e32 v0, v18
	v_lshl_add_u64 v[20:21], v[160:161], 0, v[0:1]
	v_mov_b32_e32 v0, v19
	v_lshl_add_u64 v[22:23], v[160:161], 0, v[0:1]
	s_waitcnt lgkmcnt(0)
	v_mov_b32_e32 v0, v32
	v_lshl_add_u64 v[26:27], v[160:161], 0, v[0:1]
	v_mov_b32_e32 v0, v33
	v_lshl_add_u64 v[30:31], v[160:161], 0, v[0:1]
	v_mov_b32_e32 v0, v34
	v_lshl_add_u64 v[36:37], v[160:161], 0, v[0:1]
	v_max_f32_e32 v0, v39, v39
	v_max_f32_e32 v98, v38, v0
	ds_bpermute_b32 v99, v194, v98
	v_mov_b32_e32 v0, v35
	v_lshl_add_u64 v[38:39], v[160:161], 0, v[0:1]
	global_load_dwordx4 v[10:13], v[10:11], off offset:256
	s_nop 0
	global_load_dwordx4 v[14:17], v[14:15], off offset:256
	s_nop 0
	global_load_dwordx4 v[18:21], v[20:21], off offset:256
	s_nop 0
	global_load_dwordx4 v[22:25], v[22:23], off offset:256
	s_waitcnt lgkmcnt(0)
; #define LAS __attribute__((address_space(3)))
; #define GAS __attribute__((address_space(1)))
; __device__ __forceinline__ unsigned pk2(float lo, float hi) { unsigned r; asm("v_cvt_pk_bf16_f32 %0, %1, %2" : "=v"(r) : "v"(lo), "v"(hi)); return r; }
; __device__ __forceinline__ s16x4 ldtr(LAS unsigned char* p) { return __builtin_amdgcn_ds_read_tr16_b64_v4i16((LAS s16x4*)p); }
; __device__ __forceinline__ void att_core(LAS unsigned char* Vst, const LAS float* listr, const LAS unsigned* listT, const bf16* P, const bf16* AKVb, bf16* ACAT, const float* aqg, size_t tok, int cnt, int lane) {
;     ...
;     mx = fmaxf(mx, __shfl_xor(mx, 16)); mx = fmaxf(mx, __shfl_xor(mx, 32));
;     float sum = 0.f;
; #pragma unroll
;     for (int g = 0; g < 16; ++g)
; #pragma unroll
;         for (int r = 0; r < 4; ++r) { const float pz = __builtin_amdgcn_exp2f(lg[g][r] - mx); lg[g][r] = pz; sum += pz; }
;     sum += __shfl_xor(sum, 16); sum += __shfl_xor(sum, 32);
;     bf16x8 Pf[8];
; #pragma unroll
;     for (int G = 0; G < 8; ++G) { u32x4 t; t.x = pk2(lg[2 * G][0], lg[2 * G][1]); t.y = pk2(lg[2 * G][2], lg[2 * G][3]); t.z = pk2(lg[2 * G + 1][0], lg[2 * G + 1][1]); t.w = pk2(lg[2 * G + 1][2], lg[2 * G + 1][3]); Pf[G] = __builtin_bit_cast(bf16x8, t); }
;     f32x4 O[8];
; #pragma unroll
;     for (int nb = 0; nb < 8; ++nb) O[nb] = (f32x4){0.f, 0.f, 0.f, 0.f};
;     const LAS unsigned char* vbse = Vst + (4 * fq + (fr >> 2)) * 288 + (4 * (fr & 3)) * 2;
; #pragma unroll
;     for (int G = 0; G < 8; ++G) {
; #pragma unroll
;         for (int i = 0; i < 8; ++i) *(LAS u32x4*)(Vst + (4 * i + fq) * 288 + fr * 16) = vb[G % 3][i];
;         __builtin_amdgcn_fence(__ATOMIC_RELEASE, "wavefront"); __builtin_amdgcn_wave_barrier();
;         s16x4 tc[2][2], tn[2][2];
; #pragma unroll
;         for (int u = 0; u < 2; ++u) { tc[u][0] = ldtr((LAS unsigned char*)vbse + 32 * u); tc[u][1] = ldtr((LAS unsigned char*)vbse + 16 * 288 + 32 * u); }
;         if (G + 3 < 8) {
;             const u32x4 o0 = *(const LAS u32x4*)(lt + (G + 3) * 32), o1 = *(const LAS u32x4*)(lt + (G + 3) * 32 + 4);
; #pragma unroll
;             for (int i = 0; i < 8; ++i) vb[G % 3][i] = *(const GAS u32x4*)(kbase + 256 + (i < 4 ? o0[i & 3] : o1[i & 3]));
	v_max_f32_e32 v0, v99, v99
	v_max_f32_e32 v165, v98, v0
	v_sub_f32_e32 v0, v126, v165
	v_exp_f32_e32 v126, v0
	v_sub_f32_e32 v0, v127, v165
	v_exp_f32_e32 v127, v0
	v_sub_f32_e32 v0, v128, v165
	v_exp_f32_e32 v128, v0
	v_sub_f32_e32 v0, v122, v165
	v_exp_f32_e32 v234, v0
	v_sub_f32_e32 v98, v114, v165
	v_add_f32_e32 v0, 0, v126
	v_exp_f32_e32 v235, v98
	v_sub_f32_e32 v98, v115, v165
	v_add_f32_e32 v0, v127, v0
	v_exp_f32_e32 v236, v98
	v_sub_f32_e32 v98, v116, v165
	v_add_f32_e32 v0, v128, v0
	v_exp_f32_e32 v237, v98
	v_sub_f32_e32 v98, v117, v165
	v_add_f32_e32 v0, v234, v0
	v_exp_f32_e32 v238, v98
	v_sub_f32_e32 v98, v118, v165
	v_add_f32_e32 v0, v235, v0
	v_exp_f32_e32 v118, v98
	v_sub_f32_e32 v98, v119, v165
	v_add_f32_e32 v0, v236, v0
	v_exp_f32_e32 v119, v98
	v_sub_f32_e32 v98, v120, v165
	v_add_f32_e32 v0, v237, v0
	v_exp_f32_e32 v120, v98
	v_sub_f32_e32 v98, v121, v165
	v_add_f32_e32 v0, v238, v0
	v_exp_f32_e32 v121, v98
	v_sub_f32_e32 v98, v123, v165
	v_add_f32_e32 v0, v118, v0
	v_exp_f32_e32 v239, v98
	v_sub_f32_e32 v98, v124, v165
	v_add_f32_e32 v0, v119, v0
	v_exp_f32_e32 v240, v98
	v_sub_f32_e32 v98, v125, v165
	v_add_f32_e32 v0, v120, v0
	v_exp_f32_e32 v241, v98
	v_sub_f32_e32 v98, v129, v165
	v_add_f32_e32 v0, v121, v0
	v_exp_f32_e32 v242, v98
	v_sub_f32_e32 v98, v132, v165
	v_add_f32_e32 v0, v239, v0
	v_exp_f32_e32 v132, v98
	v_sub_f32_e32 v98, v133, v165
	v_add_f32_e32 v0, v240, v0
	v_exp_f32_e32 v133, v98
	v_sub_f32_e32 v98, v135, v165
	v_add_f32_e32 v0, v241, v0
	v_exp_f32_e32 v135, v98
	v_sub_f32_e32 v98, v136, v165
	v_add_f32_e32 v0, v242, v0
	v_exp_f32_e32 v136, v98
	v_sub_f32_e32 v98, v137, v165
	v_add_f32_e32 v0, v132, v0
	v_exp_f32_e32 v137, v98
	v_sub_f32_e32 v98, v134, v165
	v_add_f32_e32 v0, v133, v0
	v_exp_f32_e32 v134, v98
	v_sub_f32_e32 v98, v131, v165
	v_add_f32_e32 v0, v135, v0
	v_exp_f32_e32 v243, v98
	v_sub_f32_e32 v98, v130, v165
	v_add_f32_e32 v0, v136, v0
	v_exp_f32_e32 v244, v98
	v_sub_f32_e32 v98, v173, v165
	v_add_f32_e32 v0, v137, v0
	v_exp_f32_e32 v173, v98
	v_sub_f32_e32 v98, v171, v165
	v_add_f32_e32 v0, v134, v0
	v_exp_f32_e32 v171, v98
	v_sub_f32_e32 v98, v169, v165
	v_add_f32_e32 v0, v243, v0
	v_exp_f32_e32 v169, v98
	v_sub_f32_e32 v98, v153, v165
	v_add_f32_e32 v0, v244, v0
	v_exp_f32_e32 v153, v98
	v_sub_f32_e32 v98, v152, v165
	v_add_f32_e32 v0, v173, v0
	v_exp_f32_e32 v152, v98
	v_sub_f32_e32 v98, v151, v165
	v_add_f32_e32 v0, v171, v0
	v_exp_f32_e32 v151, v98
	v_sub_f32_e32 v98, v150, v165
	v_add_f32_e32 v0, v169, v0
	v_exp_f32_e32 v150, v98
	v_sub_f32_e32 v98, v149, v165
	v_add_f32_e32 v0, v153, v0
	v_exp_f32_e32 v149, v98
	v_sub_f32_e32 v98, v211, v165
	v_add_f32_e32 v0, v152, v0
	v_exp_f32_e32 v211, v98
	v_sub_f32_e32 v98, v212, v165
	v_add_f32_e32 v0, v151, v0
	v_exp_f32_e32 v212, v98
	v_sub_f32_e32 v98, v210, v165
	v_add_f32_e32 v0, v150, v0
	v_exp_f32_e32 v210, v98
	v_sub_f32_e32 v98, v209, v165
	v_add_f32_e32 v0, v149, v0
	v_exp_f32_e32 v209, v98
	v_sub_f32_e32 v98, v181, v165
	v_add_f32_e32 v0, v211, v0
	v_exp_f32_e32 v181, v98
	v_sub_f32_e32 v98, v179, v165
	v_add_f32_e32 v0, v212, v0
	v_exp_f32_e32 v179, v98
	v_sub_f32_e32 v98, v177, v165
	v_add_f32_e32 v0, v210, v0
	v_exp_f32_e32 v177, v98
	v_sub_f32_e32 v98, v175, v165
	v_add_f32_e32 v0, v209, v0
	v_exp_f32_e32 v175, v98
	v_sub_f32_e32 v98, v190, v165
	v_add_f32_e32 v0, v181, v0
	v_exp_f32_e32 v190, v98
	v_sub_f32_e32 v98, v191, v165
	v_add_f32_e32 v0, v179, v0
	v_exp_f32_e32 v191, v98
	v_sub_f32_e32 v98, v192, v165
	v_add_f32_e32 v0, v177, v0
	v_exp_f32_e32 v192, v98
	v_sub_f32_e32 v98, v193, v165
	v_add_f32_e32 v0, v175, v0
	v_exp_f32_e32 v193, v98
	v_sub_f32_e32 v98, v213, v165
	v_add_f32_e32 v0, v190, v0
	v_exp_f32_e32 v213, v98
	v_sub_f32_e32 v98, v214, v165
	v_add_f32_e32 v0, v191, v0
	v_exp_f32_e32 v214, v98
	v_sub_f32_e32 v98, v215, v165
	v_add_f32_e32 v0, v192, v0
	v_exp_f32_e32 v215, v98
	v_sub_f32_e32 v98, v216, v165
	v_add_f32_e32 v0, v193, v0
	v_exp_f32_e32 v216, v98
	v_sub_f32_e32 v98, v217, v165
	v_add_f32_e32 v0, v213, v0
	v_exp_f32_e32 v217, v98
	v_sub_f32_e32 v98, v218, v165
	v_add_f32_e32 v0, v214, v0
	v_exp_f32_e32 v218, v98
	v_sub_f32_e32 v98, v219, v165
	v_add_f32_e32 v0, v215, v0
	v_exp_f32_e32 v219, v98
	v_sub_f32_e32 v98, v232, v165
	v_add_f32_e32 v0, v216, v0
	v_exp_f32_e32 v232, v98
	global_load_dwordx4 v[26:29], v[26:27], off offset:256
	s_nop 0
	global_load_dwordx4 v[30:33], v[30:31], off offset:256
	s_nop 0
	global_load_dwordx4 v[34:37], v[36:37], off offset:256
	s_nop 0
	global_load_dwordx4 v[38:41], v[38:39], off offset:256
	v_add_f32_e32 v0, v217, v0
	s_waitcnt vmcnt(23)
	ds_write_b128 v200, v[2:5]
	s_waitcnt vmcnt(22)
	ds_write_b128 v200, v[6:9] offset:1152
	s_waitcnt vmcnt(21)
	ds_write_b128 v200, v[42:45] offset:2304
	s_waitcnt vmcnt(20)
	ds_write_b128 v200, v[78:81] offset:3456
	s_waitcnt vmcnt(19)
	ds_write_b128 v200, v[82:85] offset:4608
	s_waitcnt vmcnt(18)
	ds_write_b128 v200, v[86:89] offset:5760
	s_waitcnt vmcnt(17)
	ds_write_b128 v200, v[90:93] offset:6912
	s_waitcnt vmcnt(16)
	ds_write_b128 v200, v[94:97] offset:8064
	ds_read_b128 v[2:5], v167 offset:4480
	ds_read_b128 v[6:9], v167 offset:4496
	v_add_f32_e32 v0, v218, v0
	v_add_f32_e32 v0, v219, v0
	v_add_f32_e32 v122, v232, v0
	v_sub_f32_e32 v0, v233, v165
	v_exp_f32_e32 v233, v0
	v_sub_f32_e32 v0, v140, v165
	v_exp_f32_e32 v140, v0
	s_waitcnt lgkmcnt(1)
	v_mov_b32_e32 v0, v2
	v_lshl_add_u64 v[42:43], v[160:161], 0, v[0:1]
	v_mov_b32_e32 v0, v3
	v_lshl_add_u64 v[2:3], v[160:161], 0, v[0:1]
	v_mov_b32_e32 v0, v4
	global_load_dwordx4 v[86:89], v[42:43], off offset:256
	global_load_dwordx4 v[90:93], v[2:3], off offset:256
	v_lshl_add_u64 v[2:3], v[160:161], 0, v[0:1]
	v_mov_b32_e32 v0, v5
	v_lshl_add_u64 v[4:5], v[160:161], 0, v[0:1]
	s_waitcnt lgkmcnt(0)
; __device__ __forceinline__ void att_core(LAS unsigned char* Vst, const LAS float* listr, const LAS unsigned* listT, const bf16* P, const bf16* AKVb, bf16* ACAT, const float* aqg, size_t tok, int cnt, int lane) {
;     ...
;     mx = fmaxf(mx, __shfl_xor(mx, 16)); mx = fmaxf(mx, __shfl_xor(mx, 32));
;     float sum = 0.f;
; #pragma unroll
;     for (int g = 0; g < 16; ++g)
; #pragma unroll
;         for (int r = 0; r < 4; ++r) { const float pz = __builtin_amdgcn_exp2f(lg[g][r] - mx); lg[g][r] = pz; sum += pz; }
;     sum += __shfl_xor(sum, 16); sum += __shfl_xor(sum, 32);
;     bf16x8 Pf[8];
; #pragma unroll
;     for (int G = 0; G < 8; ++G) { u32x4 t; t.x = pk2(lg[2 * G][0], lg[2 * G][1]); t.y = pk2(lg[2 * G][2], lg[2 * G][3]); t.z = pk2(lg[2 * G + 1][0], lg[2 * G + 1][1]); t.w = pk2(lg[2 * G + 1][2], lg[2 * G + 1][3]); Pf[G] = __builtin_bit_cast(bf16x8, t); }
;     f32x4 O[8];
; #pragma unroll
;     for (int nb = 0; nb < 8; ++nb) O[nb] = (f32x4){0.f, 0.f, 0.f, 0.f};
;     const LAS unsigned char* vbse = Vst + (4 * fq + (fr >> 2)) * 288 + (4 * (fr & 3)) * 2;
; #pragma unroll
;     for (int G = 0; G < 8; ++G) {
; #pragma unroll
;         for (int i = 0; i < 8; ++i) *(LAS u32x4*)(Vst + (4 * i + fq) * 288 + fr * 16) = vb[G % 3][i];
;         __builtin_amdgcn_fence(__ATOMIC_RELEASE, "wavefront"); __builtin_amdgcn_wave_barrier();
;         s16x4 tc[2][2], tn[2][2];
; #pragma unroll
;         for (int u = 0; u < 2; ++u) { tc[u][0] = ldtr((LAS unsigned char*)vbse + 32 * u); tc[u][1] = ldtr((LAS unsigned char*)vbse + 16 * 288 + 32 * u); }
;         if (G + 3 < 8) {
;             const u32x4 o0 = *(const LAS u32x4*)(lt + (G + 3) * 32), o1 = *(const LAS u32x4*)(lt + (G + 3) * 32 + 4);
; #pragma unroll
;             for (int i = 0; i < 8; ++i) vb[G % 3][i] = *(const GAS u32x4*)(kbase + 256 + (i < 4 ? o0[i & 3] : o1[i & 3]));
;         }
; #pragma unroll
;         for (int np = 0; np < 4; ++np) {
;             if (np + 1 < 4) {
; #pragma unroll
;                 for (int u = 0; u < 2; ++u) { tn[u][0] = ldtr((LAS unsigned char*)vbse + 32 * (2 * (np + 1) + u)); tn[u][1] = ldtr((LAS unsigned char*)vbse + 16 * 288 + 32 * (2 * (np + 1) + u)); } }
;             __builtin_amdgcn_sched_barrier(0);
; #pragma unroll
;             for (int u = 0; u < 2; ++u) O[2 * np + u] = mfma16(__builtin_shufflevector(tc[u][0], tc[u][1], 0, 1, 2, 3, 4, 5, 6, 7), Pf[G], O[2 * np + u]);
	v_mov_b32_e32 v0, v6
	global_load_dwordx4 v[94:97], v[2:3], off offset:256
	global_load_dwordx4 v[98:101], v[4:5], off offset:256
	v_lshl_add_u64 v[2:3], v[160:161], 0, v[0:1]
	v_mov_b32_e32 v0, v7
	v_lshl_add_u64 v[4:5], v[160:161], 0, v[0:1]
	v_mov_b32_e32 v0, v8
	global_load_dwordx4 v[102:105], v[2:3], off offset:256
	global_load_dwordx4 v[106:109], v[4:5], off offset:256
	v_lshl_add_u64 v[2:3], v[160:161], 0, v[0:1]
	v_mov_b32_e32 v0, v9
	v_lshl_add_u64 v[4:5], v[160:161], 0, v[0:1]
	global_load_dwordx4 v[110:113], v[2:3], off offset:256
	global_load_dwordx4 v[114:117], v[4:5], off offset:256
	v_sub_f32_e32 v0, v138, v165
	v_exp_f32_e32 v0, v0
	v_sub_f32_e32 v2, v139, v165
	v_exp_f32_e32 v2, v2
	v_sub_f32_e32 v4, v141, v165
	v_add_f32_e32 v3, v233, v122
	v_exp_f32_e32 v4, v4
	v_sub_f32_e32 v5, v142, v165
	v_add_f32_e32 v3, v140, v3
	v_exp_f32_e32 v5, v5
	v_sub_f32_e32 v6, v143, v165
	v_add_f32_e32 v3, v0, v3
	v_exp_f32_e32 v245, v6
	v_sub_f32_e32 v6, v148, v165
	v_add_f32_e32 v3, v2, v3
	v_exp_f32_e32 v148, v6
	v_sub_f32_e32 v6, v144, v165
	v_add_f32_e32 v3, v4, v3
	v_exp_f32_e32 v246, v6
	v_sub_f32_e32 v6, v145, v165
	v_add_f32_e32 v3, v5, v3
	v_exp_f32_e32 v247, v6
	v_sub_f32_e32 v6, v146, v165
	v_add_f32_e32 v3, v245, v3
	v_exp_f32_e32 v248, v6
	v_sub_f32_e32 v6, v147, v165
	v_add_f32_e32 v3, v148, v3
	v_exp_f32_e32 v165, v6
	v_cvt_pk_bf16_f32 v125, v128, v234
	v_cvt_pk_bf16_f32 v128, v118, v119
	v_cvt_pk_bf16_f32 v129, v120, v121
	v_cvt_pk_bf16_f32 v118, v132, v133
	v_cvt_pk_bf16_f32 v119, v135, v136
	v_cvt_pk_bf16_f32 v120, v137, v134
	v_cvt_pk_bf16_f32 v8, v233, v140
	ds_read_b64_tr_b16 v[132:133], v195
	ds_read_b64_tr_b16 v[136:137], v195 offset:32
	ds_read_b64_tr_b16 v[140:141], v195 offset:64
	ds_read_b64_tr_b16 v[144:145], v195 offset:96
	ds_read_b64_tr_b16 v[134:135], v195 offset:4608
	ds_read_b64_tr_b16 v[138:139], v195 offset:4640
	ds_read_b64_tr_b16 v[142:143], v195 offset:4672
	ds_read_b64_tr_b16 v[146:147], v195 offset:4704
	v_add_f32_e32 v3, v246, v3
	v_add_f32_e32 v3, v247, v3
	v_add_f32_e32 v3, v248, v3
	v_add_f32_e32 v3, v165, v3
	ds_bpermute_b32 v6, v185, v3
	v_cvt_pk_bf16_f32 v124, v126, v127
	v_cvt_pk_bf16_f32 v126, v235, v236
	v_cvt_pk_bf16_f32 v127, v237, v238
	v_cvt_pk_bf16_f32 v130, v239, v240
	s_waitcnt lgkmcnt(0)
	v_add_f32_e32 v122, v3, v6
	ds_bpermute_b32 v123, v194, v122
	v_cvt_pk_bf16_f32 v131, v241, v242
	v_cvt_pk_bf16_f32 v121, v243, v244
	v_cvt_pk_bf16_f32 v82, v173, v171
	v_cvt_pk_bf16_f32 v83, v169, v153
	v_cvt_pk_bf16_f32 v84, v152, v151
	v_cvt_pk_bf16_f32 v85, v150, v149
	v_cvt_pk_bf16_f32 v78, v211, v212
	v_cvt_pk_bf16_f32 v79, v210, v209
	v_cvt_pk_bf16_f32 v80, v181, v179
	v_cvt_pk_bf16_f32 v81, v177, v175
	v_cvt_pk_bf16_f32 v42, v190, v191
	v_cvt_pk_bf16_f32 v43, v192, v193
	v_cvt_pk_bf16_f32 v44, v213, v214
	v_cvt_pk_bf16_f32 v45, v215, v216
	v_cvt_pk_bf16_f32 v6, v217, v218
	v_cvt_pk_bf16_f32 v7, v219, v232
	v_cvt_pk_bf16_f32 v9, v0, v2
	v_cvt_pk_bf16_f32 v2, v4, v5
	v_cvt_pk_bf16_f32 v3, v245, v148
	v_cvt_pk_bf16_f32 v4, v246, v247
	v_cvt_pk_bf16_f32 v5, v248, v165
	v_mfma_f32_16x16x32_bf16 v[132:135], v[132:135], v[124:127], 0
	v_mfma_f32_16x16x32_bf16 v[136:139], v[136:139], v[124:127], 0
	ds_read_b64_tr_b16 v[150:151], v195 offset:4736
	ds_read_b64_tr_b16 v[148:149], v195 offset:128
	ds_read_b64_tr_b16 v[192:193], v195 offset:4768
	ds_read_b64_tr_b16 v[190:191], v195 offset:160
	v_mfma_f32_16x16x32_bf16 v[140:143], v[140:143], v[124:127], 0
	v_mfma_f32_16x16x32_bf16 v[144:147], v[144:147], v[124:127], 0
	ds_read_b64_tr_b16 v[212:213], v195 offset:4800
	ds_read_b64_tr_b16 v[210:211], v195 offset:192
	ds_read_b64_tr_b16 v[216:217], v195 offset:4832
	ds_read_b64_tr_b16 v[214:215], v195 offset:224
	s_waitcnt lgkmcnt(6)
	v_mfma_f32_16x16x32_bf16 v[148:151], v[148:151], v[124:127], 0
	s_waitcnt lgkmcnt(4)
	v_mfma_f32_16x16x32_bf16 v[190:193], v[190:193], v[124:127], 0
	s_waitcnt lgkmcnt(2)
	v_mfma_f32_16x16x32_bf16 v[210:213], v[210:213], v[124:127], 0
	s_waitcnt lgkmcnt(0)
	v_mfma_f32_16x16x32_bf16 v[124:127], v[214:217], v[124:127], 0
	s_waitcnt vmcnt(23)
	ds_write_b128 v200, v[46:49]
	s_waitcnt vmcnt(22)
	ds_write_b128 v200, v[50:53] offset:1152
	s_waitcnt vmcnt(21)
	ds_write_b128 v200, v[54:57] offset:2304
	s_waitcnt vmcnt(20)
	ds_write_b128 v200, v[58:61] offset:3456
	s_waitcnt vmcnt(19)
	ds_write_b128 v200, v[62:65] offset:4608
	s_waitcnt vmcnt(18)
	ds_write_b128 v200, v[66:69] offset:5760
	s_waitcnt vmcnt(17)
	ds_write_b128 v200, v[70:73] offset:6912
	s_waitcnt vmcnt(16)
	ds_write_b128 v200, v[74:77] offset:8064
	ds_read_b128 v[52:55], v167 offset:4608
	ds_read_b128 v[68:71], v167 offset:4624
	s_waitcnt lgkmcnt(1)
	v_mov_b32_e32 v0, v52
	v_lshl_add_u64 v[46:47], v[160:161], 0, v[0:1]
	v_mov_b32_e32 v0, v53
	v_lshl_add_u64 v[50:51], v[160:161], 0, v[0:1]
	v_mov_b32_e32 v0, v54
	v_lshl_add_u64 v[56:57], v[160:161], 0, v[0:1]
	v_mov_b32_e32 v0, v55
	v_lshl_add_u64 v[58:59], v[160:161], 0, v[0:1]
	s_waitcnt lgkmcnt(0)
	v_mov_b32_e32 v0, v68
	v_lshl_add_u64 v[62:63], v[160:161], 0, v[0:1]
	v_mov_b32_e32 v0, v69
	v_lshl_add_u64 v[66:67], v[160:161], 0, v[0:1]
	v_mov_b32_e32 v0, v70
	v_lshl_add_u64 v[72:73], v[160:161], 0, v[0:1]
	v_mov_b32_e32 v0, v71
	v_lshl_add_u64 v[74:75], v[160:161], 0, v[0:1]
	global_load_dwordx4 v[46:49], v[46:47], off offset:256
	s_nop 0
	global_load_dwordx4 v[50:53], v[50:51], off offset:256
	s_nop 0
	global_load_dwordx4 v[54:57], v[56:57], off offset:256
	s_nop 0
	global_load_dwordx4 v[58:61], v[58:59], off offset:256
	s_nop 0
	global_load_dwordx4 v[62:65], v[62:63], off offset:256
	s_nop 0
	global_load_dwordx4 v[66:69], v[66:67], off offset:256
	s_nop 0
	global_load_dwordx4 v[70:73], v[72:73], off offset:256
	s_nop 0
	global_load_dwordx4 v[74:77], v[74:75], off offset:256
	ds_read_b64_tr_b16 v[214:215], v195
	ds_read_b64_tr_b16 v[232:233], v195 offset:32
	ds_read_b64_tr_b16 v[236:237], v195 offset:64
	ds_read_b64_tr_b16 v[240:241], v195 offset:96
	ds_read_b64_tr_b16 v[216:217], v195 offset:4608
	ds_read_b64_tr_b16 v[234:235], v195 offset:4640
	ds_read_b64_tr_b16 v[238:239], v195 offset:4672
	ds_read_b64_tr_b16 v[242:243], v195 offset:4704
	s_waitcnt lgkmcnt(3)
; #define LAS __attribute__((address_space(3)))
; #define GAS __attribute__((address_space(1)))
; __device__ __forceinline__ f32x4 mfma16(bf16x8 a, bf16x8 b, f32x4 c) { return __builtin_amdgcn_mfma_f32_16x16x32_bf16(a, b, c, 0, 0, 0); }
; __device__ __forceinline__ s16x4 ldtr(LAS unsigned char* p) { return __builtin_amdgcn_ds_read_tr16_b64_v4i16((LAS s16x4*)p); }
; __device__ __forceinline__ void att_core(LAS unsigned char* Vst, const LAS float* listr, const LAS unsigned* listT, const bf16* P, const bf16* AKVb, bf16* ACAT, const float* aqg, size_t tok, int cnt, int lane) {
;     ...
;     const LAS unsigned char* vbse = Vst + (4 * fq + (fr >> 2)) * 288 + (4 * (fr & 3)) * 2;
; #pragma unroll
;     for (int G = 0; G < 8; ++G) {
; #pragma unroll
;         for (int i = 0; i < 8; ++i) *(LAS u32x4*)(Vst + (4 * i + fq) * 288 + fr * 16) = vb[G % 3][i];
;         __builtin_amdgcn_fence(__ATOMIC_RELEASE, "wavefront"); __builtin_amdgcn_wave_barrier();
;         s16x4 tc[2][2], tn[2][2];
; #pragma unroll
;         for (int u = 0; u < 2; ++u) { tc[u][0] = ldtr((LAS unsigned char*)vbse + 32 * u); tc[u][1] = ldtr((LAS unsigned char*)vbse + 16 * 288 + 32 * u); }
;         if (G + 3 < 8) {
;             const u32x4 o0 = *(const LAS u32x4*)(lt + (G + 3) * 32), o1 = *(const LAS u32x4*)(lt + (G + 3) * 32 + 4);
; #pragma unroll
;             for (int i = 0; i < 8; ++i) vb[G % 3][i] = *(const GAS u32x4*)(kbase + 256 + (i < 4 ? o0[i & 3] : o1[i & 3]));
;         }
; #pragma unroll
;         for (int np = 0; np < 4; ++np) {
;             if (np + 1 < 4) {
; #pragma unroll
;                 for (int u = 0; u < 2; ++u) { tn[u][0] = ldtr((LAS unsigned char*)vbse + 32 * (2 * (np + 1) + u)); tn[u][1] = ldtr((LAS unsigned char*)vbse + 16 * 288 + 32 * (2 * (np + 1) + u)); } }
;             __builtin_amdgcn_sched_barrier(0);
; #pragma unroll
;             for (int u = 0; u < 2; ++u) O[2 * np + u] = mfma16(__builtin_shufflevector(tc[u][0], tc[u][1], 0, 1, 2, 3, 4, 5, 6, 7), Pf[G], O[2 * np + u]);
;             __builtin_amdgcn_sched_barrier(0);
;             if (np + 1 < 4) {
; #pragma unroll
;                 for (int u = 0; u < 2; ++u) { tc[u][0] = tn[u][0]; tc[u][1] = tn[u][1]; } }
;         }
;         __builtin_amdgcn_fence(__ATOMIC_RELEASE, "wavefront"); __builtin_amdgcn_wave_barrier();
;         __builtin_amdgcn_sched_barrier(0);
;     }
	v_mfma_f32_16x16x32_bf16 v[132:135], v[214:217], v[128:131], v[132:135]
	s_waitcnt lgkmcnt(2)
	v_mfma_f32_16x16x32_bf16 v[136:139], v[232:235], v[128:131], v[136:139]
	ds_read_b64_tr_b16 v[216:217], v195 offset:4736
	ds_read_b64_tr_b16 v[214:215], v195 offset:128
	ds_read_b64_tr_b16 v[234:235], v195 offset:4768
	ds_read_b64_tr_b16 v[232:233], v195 offset:160
	s_waitcnt lgkmcnt(5)
	v_mfma_f32_16x16x32_bf16 v[140:143], v[236:239], v[128:131], v[140:143]
	s_waitcnt lgkmcnt(4)
	v_mfma_f32_16x16x32_bf16 v[144:147], v[240:243], v[128:131], v[144:147]
	ds_read_b64_tr_b16 v[238:239], v195 offset:4800
	ds_read_b64_tr_b16 v[236:237], v195 offset:192
	ds_read_b64_tr_b16 v[242:243], v195 offset:4832
	ds_read_b64_tr_b16 v[240:241], v195 offset:224
	s_waitcnt lgkmcnt(6)
	v_mfma_f32_16x16x32_bf16 v[148:151], v[214:217], v[128:131], v[148:151]
	s_waitcnt lgkmcnt(4)
	v_mfma_f32_16x16x32_bf16 v[190:193], v[232:235], v[128:131], v[190:193]
	s_waitcnt lgkmcnt(2)
	v_mfma_f32_16x16x32_bf16 v[210:213], v[236:239], v[128:131], v[210:213]
	s_waitcnt lgkmcnt(0)
	v_mfma_f32_16x16x32_bf16 v[124:127], v[240:243], v[128:131], v[124:127]
	s_waitcnt vmcnt(23)
	ds_write_b128 v200, v[10:13]
	s_waitcnt vmcnt(22)
	ds_write_b128 v200, v[14:17] offset:1152
	s_waitcnt vmcnt(21)
	ds_write_b128 v200, v[18:21] offset:2304
	s_waitcnt vmcnt(20)
	ds_write_b128 v200, v[22:25] offset:3456
	s_waitcnt vmcnt(19)
	ds_write_b128 v200, v[26:29] offset:4608
	s_waitcnt vmcnt(18)
	ds_write_b128 v200, v[30:33] offset:5760
	s_waitcnt vmcnt(17)
	ds_write_b128 v200, v[34:37] offset:6912
	s_waitcnt vmcnt(16)
	ds_write_b128 v200, v[38:41] offset:8064
	ds_read_b128 v[16:19], v167 offset:4736
	ds_read_b128 v[32:35], v167 offset:4752
	s_waitcnt lgkmcnt(1)
	v_mov_b32_e32 v0, v16
	v_lshl_add_u64 v[10:11], v[160:161], 0, v[0:1]
	v_mov_b32_e32 v0, v17
	v_lshl_add_u64 v[14:15], v[160:161], 0, v[0:1]
	v_mov_b32_e32 v0, v18
	v_lshl_add_u64 v[20:21], v[160:161], 0, v[0:1]
	v_mov_b32_e32 v0, v19
	v_lshl_add_u64 v[22:23], v[160:161], 0, v[0:1]
	s_waitcnt lgkmcnt(0)
	v_mov_b32_e32 v0, v32
	v_lshl_add_u64 v[26:27], v[160:161], 0, v[0:1]
	v_mov_b32_e32 v0, v33
	v_lshl_add_u64 v[30:31], v[160:161], 0, v[0:1]
	v_mov_b32_e32 v0, v34
	v_lshl_add_u64 v[36:37], v[160:161], 0, v[0:1]
	v_mov_b32_e32 v0, v35
	v_lshl_add_u64 v[38:39], v[160:161], 0, v[0:1]
	global_load_dwordx4 v[10:13], v[10:11], off offset:256
	s_nop 0
	global_load_dwordx4 v[14:17], v[14:15], off offset:256
	s_nop 0
	global_load_dwordx4 v[18:21], v[20:21], off offset:256
	s_nop 0
	global_load_dwordx4 v[22:25], v[22:23], off offset:256
	s_nop 0
	global_load_dwordx4 v[26:29], v[26:27], off offset:256
	s_nop 0
	global_load_dwordx4 v[30:33], v[30:31], off offset:256
	s_nop 0
	global_load_dwordx4 v[34:37], v[36:37], off offset:256
	s_nop 0
	global_load_dwordx4 v[38:41], v[38:39], off offset:256
	ds_read_b64_tr_b16 v[128:129], v195
	ds_read_b64_tr_b16 v[214:215], v195 offset:32
	ds_read_b64_tr_b16 v[232:233], v195 offset:64
	ds_read_b64_tr_b16 v[236:237], v195 offset:96
	ds_read_b64_tr_b16 v[130:131], v195 offset:4608
	ds_read_b64_tr_b16 v[216:217], v195 offset:4640
	ds_read_b64_tr_b16 v[234:235], v195 offset:4672
	ds_read_b64_tr_b16 v[238:239], v195 offset:4704
	s_waitcnt lgkmcnt(3)
	v_mfma_f32_16x16x32_bf16 v[128:131], v[128:131], v[118:121], v[132:135]
	s_waitcnt lgkmcnt(2)
	v_mfma_f32_16x16x32_bf16 v[132:135], v[214:217], v[118:121], v[136:139]
	s_nop 2
	ds_read_b64_tr_b16 v[138:139], v195 offset:4736
	ds_read_b64_tr_b16 v[136:137], v195 offset:128
	ds_read_b64_tr_b16 v[216:217], v195 offset:4768
	ds_read_b64_tr_b16 v[214:215], v195 offset:160
	s_waitcnt lgkmcnt(5)
	v_mfma_f32_16x16x32_bf16 v[140:143], v[232:235], v[118:121], v[140:143]
	s_waitcnt lgkmcnt(4)
	v_mfma_f32_16x16x32_bf16 v[144:147], v[236:239], v[118:121], v[144:147]
	ds_read_b64_tr_b16 v[234:235], v195 offset:4800
	ds_read_b64_tr_b16 v[232:233], v195 offset:192
	ds_read_b64_tr_b16 v[238:239], v195 offset:4832
	ds_read_b64_tr_b16 v[236:237], v195 offset:224
	s_waitcnt lgkmcnt(6)
	v_mfma_f32_16x16x32_bf16 v[136:139], v[136:139], v[118:121], v[148:151]
	s_waitcnt lgkmcnt(4)
	v_mfma_f32_16x16x32_bf16 v[148:151], v[214:217], v[118:121], v[190:193]
	s_waitcnt lgkmcnt(2)
	v_mfma_f32_16x16x32_bf16 v[190:193], v[232:235], v[118:121], v[210:213]
	s_waitcnt lgkmcnt(0)
	v_mfma_f32_16x16x32_bf16 v[118:121], v[236:239], v[118:121], v[124:127]
	s_waitcnt vmcnt(23)
	ds_write_b128 v200, v[86:89]
	s_waitcnt vmcnt(22)
	ds_write_b128 v200, v[90:93] offset:1152
	s_waitcnt vmcnt(21)
	ds_write_b128 v200, v[94:97] offset:2304
	s_waitcnt vmcnt(20)
	ds_write_b128 v200, v[98:101] offset:3456
	s_waitcnt vmcnt(19)
	ds_write_b128 v200, v[102:105] offset:4608
	s_waitcnt vmcnt(18)
	ds_write_b128 v200, v[106:109] offset:5760
	s_waitcnt vmcnt(17)
	ds_write_b128 v200, v[110:113] offset:6912
	s_waitcnt vmcnt(16)
	ds_write_b128 v200, v[114:117] offset:8064
	ds_read_b128 v[92:95], v167 offset:4864
	ds_read_b128 v[108:111], v167 offset:4880
	s_waitcnt lgkmcnt(1)
	v_mov_b32_e32 v0, v92
	v_lshl_add_u64 v[86:87], v[160:161], 0, v[0:1]
	v_mov_b32_e32 v0, v93
	v_lshl_add_u64 v[90:91], v[160:161], 0, v[0:1]
	v_mov_b32_e32 v0, v94
	v_lshl_add_u64 v[96:97], v[160:161], 0, v[0:1]
	v_mov_b32_e32 v0, v95
	v_lshl_add_u64 v[98:99], v[160:161], 0, v[0:1]
	s_waitcnt lgkmcnt(0)
; #define LAS __attribute__((address_space(3)))
; #define GAS __attribute__((address_space(1)))
; __device__ __forceinline__ f32x4 mfma16(bf16x8 a, bf16x8 b, f32x4 c) { return __builtin_amdgcn_mfma_f32_16x16x32_bf16(a, b, c, 0, 0, 0); }
; __device__ __forceinline__ s16x4 ldtr(LAS unsigned char* p) { return __builtin_amdgcn_ds_read_tr16_b64_v4i16((LAS s16x4*)p); }
; __device__ __forceinline__ void att_core(LAS unsigned char* Vst, const LAS float* listr, const LAS unsigned* listT, const bf16* P, const bf16* AKVb, bf16* ACAT, const float* aqg, size_t tok, int cnt, int lane) {
;     ...
;     const LAS unsigned char* vbse = Vst + (4 * fq + (fr >> 2)) * 288 + (4 * (fr & 3)) * 2;
; #pragma unroll
;     for (int G = 0; G < 8; ++G) {
; #pragma unroll
;         for (int i = 0; i < 8; ++i) *(LAS u32x4*)(Vst + (4 * i + fq) * 288 + fr * 16) = vb[G % 3][i];
;         __builtin_amdgcn_fence(__ATOMIC_RELEASE, "wavefront"); __builtin_amdgcn_wave_barrier();
;         s16x4 tc[2][2], tn[2][2];
; #pragma unroll
;         for (int u = 0; u < 2; ++u) { tc[u][0] = ldtr((LAS unsigned char*)vbse + 32 * u); tc[u][1] = ldtr((LAS unsigned char*)vbse + 16 * 288 + 32 * u); }
;         if (G + 3 < 8) {
;             const u32x4 o0 = *(const LAS u32x4*)(lt + (G + 3) * 32), o1 = *(const LAS u32x4*)(lt + (G + 3) * 32 + 4);
; #pragma unroll
;             for (int i = 0; i < 8; ++i) vb[G % 3][i] = *(const GAS u32x4*)(kbase + 256 + (i < 4 ? o0[i & 3] : o1[i & 3]));
;         }
; #pragma unroll
;         for (int np = 0; np < 4; ++np) {
;             if (np + 1 < 4) {
; #pragma unroll
;                 for (int u = 0; u < 2; ++u) { tn[u][0] = ldtr((LAS unsigned char*)vbse + 32 * (2 * (np + 1) + u)); tn[u][1] = ldtr((LAS unsigned char*)vbse + 16 * 288 + 32 * (2 * (np + 1) + u)); } }
;             __builtin_amdgcn_sched_barrier(0);
; #pragma unroll
;             for (int u = 0; u < 2; ++u) O[2 * np + u] = mfma16(__builtin_shufflevector(tc[u][0], tc[u][1], 0, 1, 2, 3, 4, 5, 6, 7), Pf[G], O[2 * np + u]);
;             __builtin_amdgcn_sched_barrier(0);
;             if (np + 1 < 4) {
; #pragma unroll
;                 for (int u = 0; u < 2; ++u) { tc[u][0] = tn[u][0]; tc[u][1] = tn[u][1]; } }
;         }
;         __builtin_amdgcn_fence(__ATOMIC_RELEASE, "wavefront"); __builtin_amdgcn_wave_barrier();
;         __builtin_amdgcn_sched_barrier(0);
;     }
	v_mov_b32_e32 v0, v108
	v_lshl_add_u64 v[102:103], v[160:161], 0, v[0:1]
	v_mov_b32_e32 v0, v109
	v_lshl_add_u64 v[106:107], v[160:161], 0, v[0:1]
	v_mov_b32_e32 v0, v110
	v_lshl_add_u64 v[112:113], v[160:161], 0, v[0:1]
	v_mov_b32_e32 v0, v111
	v_lshl_add_u64 v[114:115], v[160:161], 0, v[0:1]
	global_load_dwordx4 v[86:89], v[86:87], off offset:256
	s_nop 0
	global_load_dwordx4 v[90:93], v[90:91], off offset:256
	s_nop 0
	global_load_dwordx4 v[94:97], v[96:97], off offset:256
	s_nop 0
	global_load_dwordx4 v[98:101], v[98:99], off offset:256
	s_nop 0
	global_load_dwordx4 v[102:105], v[102:103], off offset:256
	s_nop 0
	global_load_dwordx4 v[106:109], v[106:107], off offset:256
	s_nop 0
	global_load_dwordx4 v[110:113], v[112:113], off offset:256
	s_nop 0
	global_load_dwordx4 v[114:117], v[114:115], off offset:256
	ds_read_b64_tr_b16 v[124:125], v195
	ds_read_b64_tr_b16 v[210:211], v195 offset:32
	ds_read_b64_tr_b16 v[214:215], v195 offset:64
	ds_read_b64_tr_b16 v[232:233], v195 offset:96
	ds_read_b64_tr_b16 v[126:127], v195 offset:4608
	ds_read_b64_tr_b16 v[212:213], v195 offset:4640
	ds_read_b64_tr_b16 v[216:217], v195 offset:4672
	ds_read_b64_tr_b16 v[234:235], v195 offset:4704
	s_waitcnt lgkmcnt(3)
	v_mfma_f32_16x16x32_bf16 v[124:127], v[124:127], v[82:85], v[128:131]
	s_waitcnt lgkmcnt(2)
	v_mfma_f32_16x16x32_bf16 v[128:131], v[210:213], v[82:85], v[132:135]
	s_nop 2
	ds_read_b64_tr_b16 v[134:135], v195 offset:4736
	ds_read_b64_tr_b16 v[132:133], v195 offset:128
	ds_read_b64_tr_b16 v[212:213], v195 offset:4768
	ds_read_b64_tr_b16 v[210:211], v195 offset:160
	s_waitcnt lgkmcnt(5)
	v_mfma_f32_16x16x32_bf16 v[140:143], v[214:217], v[82:85], v[140:143]
	s_waitcnt lgkmcnt(4)
	v_mfma_f32_16x16x32_bf16 v[144:147], v[232:235], v[82:85], v[144:147]
	ds_read_b64_tr_b16 v[216:217], v195 offset:4800
	ds_read_b64_tr_b16 v[214:215], v195 offset:192
	ds_read_b64_tr_b16 v[234:235], v195 offset:4832
	ds_read_b64_tr_b16 v[232:233], v195 offset:224
	s_waitcnt lgkmcnt(6)
	v_mfma_f32_16x16x32_bf16 v[132:135], v[132:135], v[82:85], v[136:139]
	s_waitcnt lgkmcnt(4)
	v_mfma_f32_16x16x32_bf16 v[136:139], v[210:213], v[82:85], v[148:151]
	s_waitcnt lgkmcnt(2)
	v_mfma_f32_16x16x32_bf16 v[148:151], v[214:217], v[82:85], v[190:193]
	s_waitcnt lgkmcnt(0)
	v_mfma_f32_16x16x32_bf16 v[82:85], v[232:235], v[82:85], v[118:121]
	s_waitcnt vmcnt(23)
	ds_write_b128 v200, v[46:49]
	s_waitcnt vmcnt(22)
	ds_write_b128 v200, v[50:53] offset:1152
	s_waitcnt vmcnt(21)
	ds_write_b128 v200, v[54:57] offset:2304
	s_waitcnt vmcnt(20)
	ds_write_b128 v200, v[58:61] offset:3456
	s_waitcnt vmcnt(19)
	ds_write_b128 v200, v[62:65] offset:4608
	s_waitcnt vmcnt(18)
	ds_write_b128 v200, v[66:69] offset:5760
	s_waitcnt vmcnt(17)
	ds_write_b128 v200, v[70:73] offset:6912
	s_waitcnt vmcnt(16)
	ds_write_b128 v200, v[74:77] offset:8064
	ds_read_b128 v[52:55], v167 offset:4992
	ds_read_b128 v[62:65], v167 offset:5008
	s_waitcnt lgkmcnt(1)
	v_mov_b32_e32 v0, v52
	v_lshl_add_u64 v[46:47], v[160:161], 0, v[0:1]
	v_mov_b32_e32 v0, v53
	v_lshl_add_u64 v[50:51], v[160:161], 0, v[0:1]
	v_mov_b32_e32 v0, v54
	v_lshl_add_u64 v[56:57], v[160:161], 0, v[0:1]
	v_mov_b32_e32 v0, v55
	v_lshl_add_u64 v[58:59], v[160:161], 0, v[0:1]
	s_waitcnt lgkmcnt(0)
	v_mov_b32_e32 v0, v62
	v_lshl_add_u64 v[66:67], v[160:161], 0, v[0:1]
	v_mov_b32_e32 v0, v63
	v_lshl_add_u64 v[62:63], v[160:161], 0, v[0:1]
	v_mov_b32_e32 v0, v64
	global_load_dwordx4 v[46:49], v[46:47], off offset:256
	s_nop 0
	global_load_dwordx4 v[50:53], v[50:51], off offset:256
	s_nop 0
	global_load_dwordx4 v[54:57], v[56:57], off offset:256
	s_nop 0
	global_load_dwordx4 v[58:61], v[58:59], off offset:256
	s_nop 0
	global_load_dwordx4 v[66:69], v[66:67], off offset:256
	s_nop 0
	global_load_dwordx4 v[70:73], v[62:63], off offset:256
	v_lshl_add_u64 v[62:63], v[160:161], 0, v[0:1]
	v_mov_b32_e32 v0, v65
	v_lshl_add_u64 v[74:75], v[160:161], 0, v[0:1]
	global_load_dwordx4 v[62:65], v[62:63], off offset:256
	s_nop 0
	global_load_dwordx4 v[74:77], v[74:75], off offset:256
	ds_read_b64_tr_b16 v[118:119], v195
	ds_read_b64_tr_b16 v[190:191], v195 offset:32
	ds_read_b64_tr_b16 v[210:211], v195 offset:64
	ds_read_b64_tr_b16 v[214:215], v195 offset:96
	ds_read_b64_tr_b16 v[120:121], v195 offset:4608
	ds_read_b64_tr_b16 v[192:193], v195 offset:4640
	ds_read_b64_tr_b16 v[212:213], v195 offset:4672
	ds_read_b64_tr_b16 v[216:217], v195 offset:4704
	s_waitcnt lgkmcnt(3)
	v_mfma_f32_16x16x32_bf16 v[118:121], v[118:121], v[78:81], v[124:127]
	s_waitcnt lgkmcnt(2)
	v_mfma_f32_16x16x32_bf16 v[124:127], v[190:193], v[78:81], v[128:131]
	s_nop 2
	ds_read_b64_tr_b16 v[130:131], v195 offset:4736
	ds_read_b64_tr_b16 v[128:129], v195 offset:128
	ds_read_b64_tr_b16 v[192:193], v195 offset:4768
	ds_read_b64_tr_b16 v[190:191], v195 offset:160
	s_waitcnt lgkmcnt(5)
	v_mfma_f32_16x16x32_bf16 v[140:143], v[210:213], v[78:81], v[140:143]
	s_waitcnt lgkmcnt(4)
	v_mfma_f32_16x16x32_bf16 v[144:147], v[214:217], v[78:81], v[144:147]
	ds_read_b64_tr_b16 v[212:213], v195 offset:4800
	ds_read_b64_tr_b16 v[210:211], v195 offset:192
	ds_read_b64_tr_b16 v[216:217], v195 offset:4832
	ds_read_b64_tr_b16 v[214:215], v195 offset:224
	s_waitcnt lgkmcnt(6)
	v_mfma_f32_16x16x32_bf16 v[128:131], v[128:131], v[78:81], v[132:135]
	s_waitcnt lgkmcnt(4)
	v_mfma_f32_16x16x32_bf16 v[132:135], v[190:193], v[78:81], v[136:139]
	s_waitcnt lgkmcnt(2)
	v_mfma_f32_16x16x32_bf16 v[136:139], v[210:213], v[78:81], v[148:151]
	s_waitcnt lgkmcnt(0)
	v_mfma_f32_16x16x32_bf16 v[78:81], v[214:217], v[78:81], v[82:85]
	s_waitcnt vmcnt(23)
	ds_write_b128 v200, v[10:13]
	s_waitcnt vmcnt(22)
	ds_write_b128 v200, v[14:17] offset:1152
	s_waitcnt vmcnt(21)
; #define LAS __attribute__((address_space(3)))
; #define GAS __attribute__((address_space(1)))
; __device__ __forceinline__ f32x4 mfma16(bf16x8 a, bf16x8 b, f32x4 c) { return __builtin_amdgcn_mfma_f32_16x16x32_bf16(a, b, c, 0, 0, 0); }
; __device__ __forceinline__ s16x4 ldtr(LAS unsigned char* p) { return __builtin_amdgcn_ds_read_tr16_b64_v4i16((LAS s16x4*)p); }
; __device__ __forceinline__ void att_core(LAS unsigned char* Vst, const LAS float* listr, const LAS unsigned* listT, const bf16* P, const bf16* AKVb, bf16* ACAT, const float* aqg, size_t tok, int cnt, int lane) {
;     ...
;     const LAS unsigned char* vbse = Vst + (4 * fq + (fr >> 2)) * 288 + (4 * (fr & 3)) * 2;
; #pragma unroll
;     for (int G = 0; G < 8; ++G) {
; #pragma unroll
;         for (int i = 0; i < 8; ++i) *(LAS u32x4*)(Vst + (4 * i + fq) * 288 + fr * 16) = vb[G % 3][i];
;         __builtin_amdgcn_fence(__ATOMIC_RELEASE, "wavefront"); __builtin_amdgcn_wave_barrier();
;         s16x4 tc[2][2], tn[2][2];
; #pragma unroll
;         for (int u = 0; u < 2; ++u) { tc[u][0] = ldtr((LAS unsigned char*)vbse + 32 * u); tc[u][1] = ldtr((LAS unsigned char*)vbse + 16 * 288 + 32 * u); }
;         if (G + 3 < 8) {
;             const u32x4 o0 = *(const LAS u32x4*)(lt + (G + 3) * 32), o1 = *(const LAS u32x4*)(lt + (G + 3) * 32 + 4);
; #pragma unroll
;             for (int i = 0; i < 8; ++i) vb[G % 3][i] = *(const GAS u32x4*)(kbase + 256 + (i < 4 ? o0[i & 3] : o1[i & 3]));
;         }
; #pragma unroll
;         for (int np = 0; np < 4; ++np) {
;             if (np + 1 < 4) {
; #pragma unroll
;                 for (int u = 0; u < 2; ++u) { tn[u][0] = ldtr((LAS unsigned char*)vbse + 32 * (2 * (np + 1) + u)); tn[u][1] = ldtr((LAS unsigned char*)vbse + 16 * 288 + 32 * (2 * (np + 1) + u)); } }
;             __builtin_amdgcn_sched_barrier(0);
; #pragma unroll
;             for (int u = 0; u < 2; ++u) O[2 * np + u] = mfma16(__builtin_shufflevector(tc[u][0], tc[u][1], 0, 1, 2, 3, 4, 5, 6, 7), Pf[G], O[2 * np + u]);
;             __builtin_amdgcn_sched_barrier(0);
;             if (np + 1 < 4) {
; #pragma unroll
;                 for (int u = 0; u < 2; ++u) { tc[u][0] = tn[u][0]; tc[u][1] = tn[u][1]; } }
;         }
;         __builtin_amdgcn_fence(__ATOMIC_RELEASE, "wavefront"); __builtin_amdgcn_wave_barrier();
;         __builtin_amdgcn_sched_barrier(0);
;     }
	ds_write_b128 v200, v[18:21] offset:2304
	s_waitcnt vmcnt(20)
	ds_write_b128 v200, v[22:25] offset:3456
	s_waitcnt vmcnt(19)
	ds_write_b128 v200, v[26:29] offset:4608
	s_waitcnt vmcnt(18)
	ds_write_b128 v200, v[30:33] offset:5760
	s_waitcnt vmcnt(17)
	ds_write_b128 v200, v[34:37] offset:6912
	s_waitcnt vmcnt(16)
	ds_write_b128 v200, v[38:41] offset:8064
	ds_read_b64_tr_b16 v[10:11], v195
	ds_read_b64_tr_b16 v[14:15], v195 offset:32
	ds_read_b64_tr_b16 v[18:19], v195 offset:64
	ds_read_b64_tr_b16 v[22:23], v195 offset:96
	ds_read_b64_tr_b16 v[12:13], v195 offset:4608
	ds_read_b64_tr_b16 v[16:17], v195 offset:4640
	ds_read_b64_tr_b16 v[20:21], v195 offset:4672
	ds_read_b64_tr_b16 v[24:25], v195 offset:4704
	s_waitcnt lgkmcnt(3)
	v_mfma_f32_16x16x32_bf16 v[10:13], v[10:13], v[42:45], v[118:121]
	s_waitcnt lgkmcnt(2)
	v_mfma_f32_16x16x32_bf16 v[14:17], v[14:17], v[42:45], v[124:127]
	ds_read_b64_tr_b16 v[28:29], v195 offset:4736
	ds_read_b64_tr_b16 v[26:27], v195 offset:128
	ds_read_b64_tr_b16 v[32:33], v195 offset:4768
	ds_read_b64_tr_b16 v[30:31], v195 offset:160
	s_waitcnt lgkmcnt(5)
	v_mfma_f32_16x16x32_bf16 v[18:21], v[18:21], v[42:45], v[140:143]
	s_waitcnt lgkmcnt(4)
	v_mfma_f32_16x16x32_bf16 v[22:25], v[22:25], v[42:45], v[144:147]
	ds_read_b64_tr_b16 v[36:37], v195 offset:4800
	ds_read_b64_tr_b16 v[34:35], v195 offset:192
	ds_read_b64_tr_b16 v[40:41], v195 offset:4832
	ds_read_b64_tr_b16 v[38:39], v195 offset:224
	s_waitcnt lgkmcnt(6)
	v_mfma_f32_16x16x32_bf16 v[26:29], v[26:29], v[42:45], v[128:131]
	s_waitcnt lgkmcnt(4)
	v_mfma_f32_16x16x32_bf16 v[30:33], v[30:33], v[42:45], v[132:135]
	s_waitcnt lgkmcnt(2)
	v_mfma_f32_16x16x32_bf16 v[34:37], v[34:37], v[42:45], v[136:139]
	s_waitcnt lgkmcnt(0)
	v_mfma_f32_16x16x32_bf16 v[38:41], v[38:41], v[42:45], v[78:81]
	s_waitcnt vmcnt(15)
	ds_write_b128 v200, v[86:89]
	s_waitcnt vmcnt(14)
	ds_write_b128 v200, v[90:93] offset:1152
	s_waitcnt vmcnt(13)
	ds_write_b128 v200, v[94:97] offset:2304
	s_waitcnt vmcnt(12)
	ds_write_b128 v200, v[98:101] offset:3456
	s_waitcnt vmcnt(11)
	ds_write_b128 v200, v[102:105] offset:4608
	s_waitcnt vmcnt(10)
	ds_write_b128 v200, v[106:109] offset:5760
	s_waitcnt vmcnt(9)
	ds_write_b128 v200, v[110:113] offset:6912
	s_waitcnt vmcnt(8)
	ds_write_b128 v200, v[114:117] offset:8064
	ds_read_b64_tr_b16 v[42:43], v195
	ds_read_b64_tr_b16 v[78:79], v195 offset:32
	ds_read_b64_tr_b16 v[82:83], v195 offset:64
	ds_read_b64_tr_b16 v[86:87], v195 offset:96
	ds_read_b64_tr_b16 v[44:45], v195 offset:4608
	ds_read_b64_tr_b16 v[80:81], v195 offset:4640
	ds_read_b64_tr_b16 v[84:85], v195 offset:4672
	ds_read_b64_tr_b16 v[88:89], v195 offset:4704
	s_waitcnt lgkmcnt(3)
	v_mfma_f32_16x16x32_bf16 v[10:13], v[42:45], v[6:9], v[10:13]
	s_waitcnt lgkmcnt(2)
	v_mfma_f32_16x16x32_bf16 v[14:17], v[78:81], v[6:9], v[14:17]
	ds_read_b64_tr_b16 v[44:45], v195 offset:4736
	ds_read_b64_tr_b16 v[42:43], v195 offset:128
	ds_read_b64_tr_b16 v[80:81], v195 offset:4768
	ds_read_b64_tr_b16 v[78:79], v195 offset:160
	s_waitcnt lgkmcnt(5)
	v_mfma_f32_16x16x32_bf16 v[18:21], v[82:85], v[6:9], v[18:21]
	s_waitcnt lgkmcnt(4)
	v_mfma_f32_16x16x32_bf16 v[22:25], v[86:89], v[6:9], v[22:25]
	ds_read_b64_tr_b16 v[84:85], v195 offset:4800
	ds_read_b64_tr_b16 v[82:83], v195 offset:192
	ds_read_b64_tr_b16 v[88:89], v195 offset:4832
	ds_read_b64_tr_b16 v[86:87], v195 offset:224
	s_waitcnt lgkmcnt(6)
	v_mfma_f32_16x16x32_bf16 v[26:29], v[42:45], v[6:9], v[26:29]
	s_waitcnt lgkmcnt(4)
	v_mfma_f32_16x16x32_bf16 v[30:33], v[78:81], v[6:9], v[30:33]
	s_waitcnt lgkmcnt(2)
	v_mfma_f32_16x16x32_bf16 v[34:37], v[82:85], v[6:9], v[34:37]
	s_waitcnt lgkmcnt(0)
	v_mfma_f32_16x16x32_bf16 v[6:9], v[86:89], v[6:9], v[38:41]
	s_waitcnt vmcnt(7)
	ds_write_b128 v200, v[46:49]
	s_waitcnt vmcnt(6)
	ds_write_b128 v200, v[50:53] offset:1152
	s_waitcnt vmcnt(5)
	ds_write_b128 v200, v[54:57] offset:2304
	s_waitcnt vmcnt(4)
	ds_write_b128 v200, v[58:61] offset:3456
	s_waitcnt vmcnt(3)
	ds_write_b128 v200, v[66:69] offset:4608
	s_waitcnt vmcnt(2)
	ds_write_b128 v200, v[70:73] offset:5760
	s_waitcnt vmcnt(1)
	ds_write_b128 v200, v[62:65] offset:6912
	s_waitcnt vmcnt(0)
	ds_write_b128 v200, v[74:77] offset:8064
	ds_read_b64_tr_b16 v[38:39], v195
	ds_read_b64_tr_b16 v[42:43], v195 offset:32
	ds_read_b64_tr_b16 v[46:47], v195 offset:64
	ds_read_b64_tr_b16 v[50:51], v195 offset:96
	ds_read_b64_tr_b16 v[40:41], v195 offset:4608
	ds_read_b64_tr_b16 v[44:45], v195 offset:4640
	ds_read_b64_tr_b16 v[48:49], v195 offset:4672
	ds_read_b64_tr_b16 v[52:53], v195 offset:4704
	s_waitcnt lgkmcnt(3)
	v_mfma_f32_16x16x32_bf16 v[10:13], v[38:41], v[2:5], v[10:13]
	s_waitcnt lgkmcnt(2)
	v_mfma_f32_16x16x32_bf16 v[14:17], v[42:45], v[2:5], v[14:17]
	ds_read_b64_tr_b16 v[40:41], v195 offset:4736
	ds_read_b64_tr_b16 v[38:39], v195 offset:128
	ds_read_b64_tr_b16 v[44:45], v195 offset:4768
	ds_read_b64_tr_b16 v[42:43], v195 offset:160
	s_waitcnt lgkmcnt(5)
	v_mfma_f32_16x16x32_bf16 v[18:21], v[46:49], v[2:5], v[18:21]
	s_waitcnt lgkmcnt(4)
	v_mfma_f32_16x16x32_bf16 v[22:25], v[50:53], v[2:5], v[22:25]
	ds_read_b64_tr_b16 v[48:49], v195 offset:4800
	ds_read_b64_tr_b16 v[46:47], v195 offset:192
	ds_read_b64_tr_b16 v[52:53], v195 offset:4832
	ds_read_b64_tr_b16 v[50:51], v195 offset:224
	s_waitcnt lgkmcnt(6)
	v_mfma_f32_16x16x32_bf16 v[26:29], v[38:41], v[2:5], v[26:29]
	s_waitcnt lgkmcnt(4)
	v_mfma_f32_16x16x32_bf16 v[30:33], v[42:45], v[2:5], v[30:33]
	s_waitcnt lgkmcnt(2)
	v_mfma_f32_16x16x32_bf16 v[34:37], v[46:49], v[2:5], v[34:37]
	s_waitcnt lgkmcnt(0)
; #define LAS __attribute__((address_space(3)))
; #define GAS __attribute__((address_space(1)))
; __device__ __forceinline__ float bflo(unsigned w) { return __uint_as_float(w << 16); }
; __device__ __forceinline__ float bfhi(unsigned w) { return __uint_as_float(w & 0xffff0000u); }
; __device__ __forceinline__ unsigned pk2(float lo, float hi) { unsigned r; asm("v_cvt_pk_bf16_f32 %0, %1, %2" : "=v"(r) : "v"(lo), "v"(hi)); return r; }
; __device__ __forceinline__ void att_core(LAS unsigned char* Vst, const LAS float* listr, const LAS unsigned* listT, const bf16* P, const bf16* AKVb, bf16* ACAT, const float* aqg, size_t tok, int cnt, int lane) {
;     ...
;     const float rs = __builtin_amdgcn_rcpf(sum);
;     LAS float* Ot = (LAS float*)Vst;
; #pragma unroll
;     for (int nb = 0; nb < 8; ++nb) *(LAS f32x4*)(Ot + fr * 132 + 16 * nb + 4 * fq) = O[nb] * rs;
;     __builtin_amdgcn_fence(__ATOMIC_RELEASE, "wavefront"); __builtin_amdgcn_wave_barrier();
;     {
;         u32x2 sg[8];
; #pragma unroll
;         for (int j = 0; j < 8; ++j) sg[j] = *(const GAS u32x2*)(P + tok * NP + C_AG + 256 * j + 4 * lane);
; #pragma unroll
;         for (int j = 0; j < 8; ++j) {
;             const int c = 256 * j + 4 * lane;
;             const f32x4 o4 = *(const LAS f32x4*)(Ot + (c >> 7) * 132 + (c & 127));
;             u32x2 o; o.x = pk2(o4.x * bflo(sg[j].x), o4.y * bfhi(sg[j].x)); o.y = pk2(o4.z * bflo(sg[j].y), o4.w * bfhi(sg[j].y));
;             *(GAS u32x2*)(ACAT + ((size_t)NTOK + tok) * DM + c) = o;
;         }
;     }
;     __builtin_amdgcn_fence(__ATOMIC_RELEASE, "wavefront"); __builtin_amdgcn_wave_barrier();
	v_mfma_f32_16x16x32_bf16 v[2:5], v[50:53], v[2:5], v[6:9]
	v_add_f32_e32 v0, v122, v123
	v_rcp_f32_e32 v0, v0
	v_mov_b32_e32 v167, v1
	s_mov_b64 s[42:43], 0x5200
	s_movk_i32 s33, 0x5000
	v_pk_mul_f32 v[8:9], v[0:1], v[12:13] op_sel_hi:[0,1]
	v_pk_mul_f32 v[6:7], v[0:1], v[10:11] op_sel_hi:[0,1]
	ds_write_b128 v196, v[6:9]
	v_pk_mul_f32 v[8:9], v[0:1], v[16:17] op_sel_hi:[0,1]
	v_pk_mul_f32 v[6:7], v[0:1], v[14:15] op_sel_hi:[0,1]
	ds_write_b128 v196, v[6:9] offset:64
	v_pk_mul_f32 v[8:9], v[0:1], v[20:21] op_sel_hi:[0,1]
	v_pk_mul_f32 v[6:7], v[0:1], v[18:19] op_sel_hi:[0,1]
	ds_write_b128 v196, v[6:9] offset:128
	v_pk_mul_f32 v[8:9], v[0:1], v[24:25] op_sel_hi:[0,1]
	v_pk_mul_f32 v[6:7], v[0:1], v[22:23] op_sel_hi:[0,1]
	v_pk_mul_f32 v[4:5], v[0:1], v[4:5] op_sel_hi:[0,1]
	v_pk_mul_f32 v[2:3], v[0:1], v[2:3] op_sel_hi:[0,1]
	ds_write_b128 v196, v[6:9] offset:192
	v_pk_mul_f32 v[8:9], v[0:1], v[28:29] op_sel_hi:[0,1]
	v_pk_mul_f32 v[6:7], v[0:1], v[26:27] op_sel_hi:[0,1]
	ds_write_b128 v196, v[2:5] offset:448
	v_lshl_add_u64 v[2:3], v[182:183], 0, v[166:167]
	ds_write_b128 v196, v[6:9] offset:256
	v_pk_mul_f32 v[8:9], v[0:1], v[32:33] op_sel_hi:[0,1]
	v_pk_mul_f32 v[6:7], v[0:1], v[30:31] op_sel_hi:[0,1]
	v_lshl_add_u64 v[4:5], v[2:3], 0, s[42:43]
	v_add_co_u32_e32 v2, vcc, s33, v2
	ds_write_b128 v196, v[6:9] offset:320
	v_pk_mul_f32 v[8:9], v[0:1], v[36:37] op_sel_hi:[0,1]
	v_pk_mul_f32 v[6:7], v[0:1], v[34:35] op_sel_hi:[0,1]
	v_addc_co_u32_e32 v3, vcc, 0, v3, vcc
	ds_write_b128 v196, v[6:9] offset:384
	global_load_dwordx2 v[18:19], v[2:3], off offset:512
	global_load_dwordx2 v[20:21], v[4:5], off offset:512
	global_load_dwordx2 v[22:23], v[4:5], off offset:1024
	global_load_dwordx2 v[12:13], v[4:5], off offset:1536
	global_load_dwordx2 v[10:11], v[4:5], off offset:2048
	global_load_dwordx2 v[8:9], v[4:5], off offset:2560
	global_load_dwordx2 v[6:7], v[4:5], off offset:3072
	global_load_dwordx2 v[2:3], v[4:5], off offset:3584
	ds_read_b128 v[14:17], v201
	v_lshlrev_b64 v[4:5], 12, v[156:157]
	v_lshl_add_u64 v[4:5], s[46:47], 0, v[4:5]
	s_mov_b64 s[42:43], 0x2000000
	v_lshl_add_u64 v[4:5], v[4:5], 0, s[42:43]
	v_mov_b32_e32 v169, v1
	v_mov_b32_e32 v171, v1
	v_mov_b32_e32 v173, v1
	v_mov_b32_e32 v175, v1
	v_mov_b32_e32 v177, v1
	v_mov_b32_e32 v179, v1
	v_mov_b32_e32 v181, v1
	s_mov_b64 s[42:43], 0
	s_and_b64 vcc, exec, s[40:41]
	s_mov_b32 s33, 1
	s_waitcnt vmcnt(7)
	v_lshlrev_b32_e32 v0, 16, v18
	s_waitcnt lgkmcnt(0)
	v_mul_f32_e32 v0, v14, v0
	v_and_b32_e32 v14, 0xffff0000, v18
	v_mul_f32_e32 v14, v15, v14
	v_and_b32_e32 v15, 0xffff0000, v19
	v_cvt_pk_bf16_f32 v14, v0, v14
	v_lshlrev_b32_e32 v0, 16, v19
	v_mul_f32_e32 v15, v17, v15
	v_mul_f32_e32 v0, v16, v0
	v_cvt_pk_bf16_f32 v15, v0, v15
	v_lshl_add_u64 v[16:17], v[4:5], 0, v[166:167]
	global_store_dwordx2 v[16:17], v[14:15], off
	ds_read_b128 v[14:17], v202
	s_waitcnt vmcnt(7)
	v_lshlrev_b32_e32 v0, 16, v20
	s_waitcnt lgkmcnt(0)
	v_mul_f32_e32 v0, v14, v0
	v_and_b32_e32 v14, 0xffff0000, v20
	v_mul_f32_e32 v14, v15, v14
	v_and_b32_e32 v15, 0xffff0000, v21
	v_cvt_pk_bf16_f32 v14, v0, v14
	v_lshlrev_b32_e32 v0, 16, v21
	v_mul_f32_e32 v15, v17, v15
	v_mul_f32_e32 v0, v16, v0
	v_cvt_pk_bf16_f32 v15, v0, v15
	v_lshl_add_u64 v[16:17], v[4:5], 0, v[168:169]
	global_store_dwordx2 v[16:17], v[14:15], off
	ds_read_b128 v[14:17], v203
	s_waitcnt vmcnt(7)
	v_lshlrev_b32_e32 v0, 16, v22
	s_waitcnt lgkmcnt(0)
	v_mul_f32_e32 v0, v14, v0
	v_and_b32_e32 v14, 0xffff0000, v22
	v_mul_f32_e32 v14, v15, v14
	v_and_b32_e32 v15, 0xffff0000, v23
	v_cvt_pk_bf16_f32 v14, v0, v14
	v_lshlrev_b32_e32 v0, 16, v23
	v_mul_f32_e32 v15, v17, v15
	v_mul_f32_e32 v0, v16, v0
	v_cvt_pk_bf16_f32 v15, v0, v15
	v_lshl_add_u64 v[16:17], v[4:5], 0, v[170:171]
	global_store_dwordx2 v[16:17], v[14:15], off
	ds_read_b128 v[14:17], v204
	s_waitcnt vmcnt(7)
	v_lshlrev_b32_e32 v0, 16, v12
	v_and_b32_e32 v12, 0xffff0000, v12
	s_waitcnt lgkmcnt(0)
	v_mul_f32_e32 v0, v14, v0
	v_mul_f32_e32 v12, v15, v12
	v_cvt_pk_bf16_f32 v12, v0, v12
	v_lshlrev_b32_e32 v0, 16, v13
	v_and_b32_e32 v13, 0xffff0000, v13
	v_mul_f32_e32 v13, v17, v13
	v_mul_f32_e32 v0, v16, v0
	v_cvt_pk_bf16_f32 v13, v0, v13
	v_lshl_add_u64 v[14:15], v[4:5], 0, v[172:173]
	global_store_dwordx2 v[14:15], v[12:13], off
	ds_read_b128 v[12:15], v205
	s_waitcnt vmcnt(7)
	v_lshlrev_b32_e32 v0, 16, v10
	v_and_b32_e32 v10, 0xffff0000, v10
	s_waitcnt lgkmcnt(0)
	v_mul_f32_e32 v0, v12, v0
	v_mul_f32_e32 v10, v13, v10
	v_cvt_pk_bf16_f32 v10, v0, v10
	v_lshlrev_b32_e32 v0, 16, v11
	v_and_b32_e32 v11, 0xffff0000, v11
	v_mul_f32_e32 v11, v15, v11
	v_mul_f32_e32 v0, v14, v0
	v_cvt_pk_bf16_f32 v11, v0, v11
	v_lshl_add_u64 v[12:13], v[4:5], 0, v[174:175]
	global_store_dwordx2 v[12:13], v[10:11], off
	ds_read_b128 v[10:13], v206
	s_waitcnt vmcnt(7)
	v_lshlrev_b32_e32 v0, 16, v8
	v_and_b32_e32 v8, 0xffff0000, v8
	s_waitcnt lgkmcnt(0)
	v_mul_f32_e32 v0, v10, v0
	v_mul_f32_e32 v8, v11, v8
	v_cvt_pk_bf16_f32 v8, v0, v8
	v_lshlrev_b32_e32 v0, 16, v9
	v_and_b32_e32 v9, 0xffff0000, v9
	v_mul_f32_e32 v9, v13, v9
	v_mul_f32_e32 v0, v12, v0
	v_cvt_pk_bf16_f32 v9, v0, v9
	v_lshl_add_u64 v[10:11], v[4:5], 0, v[176:177]
	global_store_dwordx2 v[10:11], v[8:9], off
	ds_read_b128 v[8:11], v207
	s_waitcnt vmcnt(7)
	v_lshlrev_b32_e32 v0, 16, v6
	v_and_b32_e32 v6, 0xffff0000, v6
	s_waitcnt lgkmcnt(0)
	v_mul_f32_e32 v0, v8, v0
	v_mul_f32_e32 v6, v9, v6
	v_cvt_pk_bf16_f32 v6, v0, v6
	v_lshlrev_b32_e32 v0, 16, v7
	v_and_b32_e32 v7, 0xffff0000, v7
	v_mul_f32_e32 v7, v11, v7
	v_mul_f32_e32 v0, v10, v0
	v_cvt_pk_bf16_f32 v7, v0, v7
	v_lshl_add_u64 v[8:9], v[4:5], 0, v[178:179]
	global_store_dwordx2 v[8:9], v[6:7], off
	ds_read_b128 v[6:9], v208
	s_waitcnt vmcnt(7)
	v_lshlrev_b32_e32 v0, 16, v2
	v_and_b32_e32 v2, 0xffff0000, v2
	v_lshl_add_u64 v[4:5], v[4:5], 0, v[180:181]
	s_waitcnt lgkmcnt(0)
	v_mul_f32_e32 v0, v6, v0
	v_mul_f32_e32 v2, v7, v2
	v_cvt_pk_bf16_f32 v2, v0, v2
	v_lshlrev_b32_e32 v0, 16, v3
	v_and_b32_e32 v3, 0xffff0000, v3
	v_mul_f32_e32 v3, v9, v3
	v_mul_f32_e32 v0, v8, v0
	v_cvt_pk_bf16_f32 v3, v0, v3
	global_store_dwordx2 v[4:5], v[2:3], off
	s_cbranch_vccz .LBB0_1010
	s_branch .LBB0_580

; #define LAS __attribute__((address_space(3)))
; #define GAS __attribute__((address_space(1)))
; __device__ __forceinline__ void state_unit(LAS unsigned char* lds, const bf16* RQKV, bf16* TS, unsigned* flag, int b, int h, int e, int tid) {
;     asm volatile("" : "+s"(RQKV), "+s"(TS), "+s"(flag), "+s"(e), "+v"(tid));
;     const int lane = tid & 63, w = __builtin_amdgcn_readfirstlane(tid >> 6), fr = lane & 15, fq = lane >> 4;
;     const bf16* RK = RQKV + RQKV_ONE / 2 + (size_t)((b * 8 + h) * 2048) * 256; const bf16* RV = RK + RQKV_ONE / 2;
;     bf16* TSb = TS + (size_t)((b * 8 + h) * 8) * 65536;
;     constexpr int KB = 64 * 528, VPITCH = 144, VB = 64 * VPITCH, SBUF = KB + VB;
;     const float l2g = __log2f(1.f - exp2f(-5.f - (float)h));
;     const float c64 = __builtin_amdgcn_exp2f(64.f * l2g);
;     f32x4 T[2][4];
; #pragma unroll
;     for (int i = 0; i < 2; ++i)
; #pragma unroll
;         for (int j = 0; j < 4; ++j) T[i][j] = (f32x4){0.f, 0.f, 0.f, 0.f};
;     const int srow = tid >> 5, sch = tid & 31;
;     const size_t soff = (size_t)srow * 256 + sch * 8;
;     const int vtok = tid >> 3, vpc = tid & 7;
;     const size_t voff = (size_t)vtok * 256 + 64 * e + vpc * 8;
;     const float vsc = __builtin_amdgcn_exp2f((float)(63 - vtok) * l2g);
;     u32x4 kreg[4][4], vreg[4];
; #pragma unroll
;     for (int ts = 0; ts < 4; ++ts) {
; #pragma unroll
;         for (int i = 0; i < 4; ++i) kreg[ts][i] = __builtin_nontemporal_load((const GAS u32x4*)(RK + soff + (size_t)(64 * ts + 16 * i) * 256));
;         vreg[ts] = *(const GAS u32x4*)(RV + voff + (size_t)(64 * ts) * 256);
;     }
; __global__ void __launch_bounds__(512, 2) mega_fwd(Params p) {
;     ...
;                     unsigned* flagp = (unsigned*)(wsl + CTL_FLAG) + ((l * 4 + b) * 8 + a0) * 16;
.LBB0_1012:
	s_xor_b64 s[4:5], s[0:1], -1
	v_readlane_b32 s0, v254, 36
	s_add_i32 s0, s0, s26
	s_lshl_b32 s0, s0, 4
	v_cvt_f32_i32_e32 v0, s26
	s_ashr_i32 s1, s0, 31
	s_lshl_b64 s[0:1], s[0:1], 2
	v_readlane_b32 s2, v254, 25
	s_add_u32 s2, s2, s0
	v_readlane_b32 s0, v254, 26
	s_addc_u32 s3, s0, s1
	s_mov_b64 s[0:1], -1
	s_and_b64 vcc, exec, s[4:5]
	v_sub_f32_e32 v134, 0xc0a00000, v0
	s_cbranch_vccz .LBB0_1028
	v_readlane_b32 s6, v254, 35
	s_add_i32 s6, s26, s6
	s_lshl_b32 s6, s6, 11
	v_readlane_b32 s8, v254, 15
	v_readlane_b32 s0, v254, 23
	s_ashr_i32 s7, s6, 31
	v_readlane_b32 s9, v254, 16
	s_mov_b64 s[4:5], s[2:3]
	v_mov_b32_e32 v135, v220
	v_readlane_b32 s1, v254, 24
	s_mov_b32 s13, s12
	s_lshl_b64 s[6:7], s[6:7], 9
	s_add_u32 s6, s8, s6
	s_addc_u32 s7, s9, s7
	s_add_u32 s10, s6, 0x2000000
	s_mov_b32 s6, 0xc2fc0000
	v_cmp_gt_f32_e32 vcc, s6, v134
	s_addc_u32 s11, s7, 0
	s_and_b64 s[6:7], vcc, exec
	v_cndmask_b32_e32 v0, 0, v227, vcc
	v_add_f32_e32 v0, v134, v0
	v_exp_f32_e32 v0, v0
	s_cselect_b32 s6, 0xffffffc0, 0
	v_ashrrev_i32_e32 v86, 3, v135
	s_nop 0
	v_sub_u32_e32 v2, 63, v86
	v_ldexp_f32 v0, v0, s6
	v_sub_f32_e32 v0, 1.0, v0
	v_log_f32_e32 v0, v0
	v_cvt_f32_i32_e32 v2, v2
	v_ashrrev_i32_e32 v84, 5, v135
	v_ashrrev_i32_e32 v85, 31, v84
	v_ashrrev_i32_e32 v87, 31, v86
	s_lshl_b32 s6, s13, 6
	v_lshlrev_b64 v[88:89], 9, v[84:85]
	v_lshlrev_b32_e32 v4, 4, v135
	v_mul_f32_e32 v83, 0x42800000, v0
	s_ashr_i32 s7, s6, 31
	v_mul_f32_e32 v94, v0, v2
	v_lshl_add_u64 v[2:3], s[10:11], 0, v[88:89]
	v_and_b32_e32 v0, 0x1f0, v4
	v_lshlrev_b64 v[90:91], 9, v[86:87]
	v_lshl_add_u64 v[74:75], v[2:3], 0, v[0:1]
	v_lshl_add_u64 v[2:3], s[10:11], 0, v[90:91]
	s_lshl_b64 s[10:11], s[6:7], 1
	s_movk_i32 s7, 0x2000
	v_add_co_u32_e32 v6, vcc, s7, v74
	s_movk_i32 s7, 0x6000
	s_nop 0
	v_addc_co_u32_e32 v7, vcc, 0, v75, vcc
	v_add_co_u32_e32 v10, vcc, s73, v74
	v_lshl_add_u64 v[2:3], v[2:3], 0, s[10:11]
	s_nop 0
	v_addc_co_u32_e32 v11, vcc, 0, v75, vcc
	v_and_b32_e32 v92, 0x70, v4
	v_mov_b32_e32 v93, v1
	v_add_co_u32_e32 v12, vcc, s7, v74
	v_lshl_add_u64 v[76:77], v[2:3], 0, v[92:93]
	s_nop 0
	v_addc_co_u32_e32 v13, vcc, 0, v75, vcc
	s_brev_b32 s7, 64
	global_load_dwordx4 v[2:5], v[74:75], off nt
	s_nop 0
	global_load_dwordx4 v[6:9], v[6:7], off nt
	s_nop 0
	global_load_dwordx4 v[14:17], v[10:11], off nt
	global_load_dwordx4 v[18:21], v[12:13], off nt
	v_add_co_u32_e32 v10, vcc, s7, v76
	s_mov_b32 s7, 0x8000
	s_nop 0
	v_addc_co_u32_e32 v11, vcc, 0, v77, vcc
	v_add_co_u32_e32 v12, vcc, s7, v74
	s_mov_b32 s7, 0xa000
	s_nop 0
	v_addc_co_u32_e32 v13, vcc, 0, v75, vcc
	v_add_co_u32_e32 v22, vcc, s7, v74
	s_mov_b32 s7, 0xc000
	s_nop 0
	v_addc_co_u32_e32 v23, vcc, 0, v75, vcc
	v_add_co_u32_e32 v30, vcc, s7, v74
	s_mov_b32 s7, 0xe000
	s_nop 0
	v_addc_co_u32_e32 v31, vcc, 0, v75, vcc
	v_add_co_u32_e32 v34, vcc, s7, v74
	s_mov_b32 s7, 0x2008000
	s_nop 0
	v_addc_co_u32_e32 v35, vcc, 0, v75, vcc
	v_add_co_u32_e32 v36, vcc, s7, v76
	s_mov_b32 s7, 0x10000
	s_nop 0
	v_addc_co_u32_e32 v37, vcc, 0, v77, vcc
	global_load_dwordx4 v[26:29], v[10:11], off
	s_nop 0
	global_load_dwordx4 v[10:13], v[12:13], off nt
	s_nop 0
	global_load_dwordx4 v[22:25], v[22:23], off nt
	s_nop 0
	global_load_dwordx4 v[30:33], v[30:31], off nt
	s_nop 0
	global_load_dwordx4 v[42:45], v[34:35], off nt
	global_load_dwordx4 v[46:49], v[36:37], off
	v_add_co_u32_e32 v34, vcc, s7, v74
	s_mov_b32 s7, 0x12000
	s_nop 0
	v_addc_co_u32_e32 v35, vcc, 0, v75, vcc
	v_add_co_u32_e32 v38, vcc, s7, v74
	s_mov_b32 s7, 0x14000
	s_nop 0
	v_addc_co_u32_e32 v39, vcc, 0, v75, vcc
	v_add_co_u32_e32 v50, vcc, s7, v74
	s_mov_b32 s7, 0x16000
	s_nop 0
	v_addc_co_u32_e32 v51, vcc, 0, v75, vcc
	v_add_co_u32_e32 v52, vcc, s7, v74
	s_mov_b32 s7, 0x2010000
	s_nop 0
	v_addc_co_u32_e32 v53, vcc, 0, v75, vcc
	global_load_dwordx4 v[34:37], v[34:35], off nt
	s_nop 0
	global_load_dwordx4 v[38:41], v[38:39], off nt
	s_nop 0
	global_load_dwordx4 v[54:57], v[50:51], off nt
; #define GAS __attribute__((address_space(1)))
; __device__ __forceinline__ void state_unit(LAS unsigned char* lds, const bf16* RQKV, bf16* TS, unsigned* flag, int b, int h, int e, int tid) {
;     ...
;     const int srow = tid >> 5, sch = tid & 31;
;     const size_t soff = (size_t)srow * 256 + sch * 8;
;     const int vtok = tid >> 3, vpc = tid & 7;
;     const size_t voff = (size_t)vtok * 256 + 64 * e + vpc * 8;
;     const float vsc = __builtin_amdgcn_exp2f((float)(63 - vtok) * l2g);
;     u32x4 kreg[4][4], vreg[4];
; #pragma unroll
;     for (int ts = 0; ts < 4; ++ts) {
; #pragma unroll
;         for (int i = 0; i < 4; ++i) kreg[ts][i] = __builtin_nontemporal_load((const GAS u32x4*)(RK + soff + (size_t)(64 * ts + 16 * i) * 256));
;         vreg[ts] = *(const GAS u32x4*)(RV + voff + (size_t)(64 * ts) * 256);
;     }
;     __syncthreads();
	global_load_dwordx4 v[58:61], v[52:53], off nt
	v_add_co_u32_e32 v50, vcc, s7, v76
	s_mov_b32 s7, 0x18000
	s_nop 0
	v_addc_co_u32_e32 v51, vcc, 0, v77, vcc
	v_add_co_u32_e32 v52, vcc, s7, v74
	s_mov_b32 s7, 0x1a000
	s_nop 0
	v_addc_co_u32_e32 v53, vcc, 0, v75, vcc
	v_add_co_u32_e32 v62, vcc, s7, v74
	s_mov_b32 s7, 0x1c000
	s_nop 0
	v_addc_co_u32_e32 v63, vcc, 0, v75, vcc
	v_add_co_u32_e32 v70, vcc, s7, v74
	s_mov_b32 s7, 0x1e000
	s_nop 0
	v_addc_co_u32_e32 v71, vcc, 0, v75, vcc
	v_add_co_u32_e32 v74, vcc, s7, v74
	s_mov_b32 s7, 0x2018000
	s_nop 0
	v_addc_co_u32_e32 v75, vcc, 0, v75, vcc
	v_add_co_u32_e32 v78, vcc, s7, v76
	global_load_dwordx4 v[66:69], v[50:51], off
	s_nop 0
	global_load_dwordx4 v[50:53], v[52:53], off nt
	v_addc_co_u32_e32 v79, vcc, 0, v77, vcc
	global_load_dwordx4 v[62:65], v[62:63], off nt
	s_nop 0
	global_load_dwordx4 v[70:73], v[70:71], off nt
	s_nop 0
	global_load_dwordx4 v[74:77], v[74:75], off nt
	s_nop 0
	global_load_dwordx4 v[78:81], v[78:79], off
	s_movk_i32 s7, 0x90
	v_bfe_u32 v85, v135, 4, 2
	v_exp_f32_e32 v114, v83
	v_mul_lo_u32 v83, v86, s7
	v_bfe_u32 v86, v135, 2, 2
	v_lshl_or_b32 v87, v85, 3, v86
	v_lshlrev_b32_e32 v86, 3, v135
	v_and_b32_e32 v93, 24, v86
	v_and_or_b32 v86, v135, 15, s6
	s_movk_i32 s13, 0x210
	v_mul_lo_u32 v138, v84, s13
	v_or_b32_e32 v84, 16, v86
	v_readfirstlane_b32 s14, v135
	v_exp_f32_e32 v136, v94
	v_lshlrev_b32_e32 v94, 2, v85
	v_ashrrev_i32_e32 v85, 31, v84
	s_and_b32 s7, s14, 0xffffffc0
	s_ashr_i32 s6, s14, 1
	v_lshlrev_b64 v[120:121], 9, v[84:85]
	v_or_b32_e32 v84, 32, v86
	s_lshl_b32 s13, s26, 11
	v_readlane_b32 s14, v254, 30
	s_add_i32 s7, s7, 0
	v_ashrrev_i32_e32 v85, 31, v84
	s_add_i32 s14, s14, s13
	s_andn2_b32 s6, s6, 31
	v_add_u32_e32 v97, s7, v93
	v_readlane_b32 s7, v253, 32
	v_lshlrev_b64 v[122:123], 9, v[84:85]
	v_or_b32_e32 v84, 48, v86
	s_ashr_i32 s15, s14, 31
	v_add_u32_e32 v96, 0, v83
	v_add_u32_e32 v98, 0, v93
	v_add_u32_e32 v83, s7, v83
	v_add_u32_e32 v93, s7, v93
	s_ashr_i32 s7, s6, 31
	v_ashrrev_i32_e32 v85, 31, v84
	s_lshl_b64 s[14:15], s[14:15], 9
	v_lshlrev_b64 v[124:125], 9, v[84:85]
	v_lshl_add_u64 v[84:85], v[90:91], 0, s[14:15]
	s_add_u32 s10, s8, s10
	v_or_b32_e32 v84, v84, v92
	s_addc_u32 s11, s9, s11
	v_lshl_add_u64 v[126:127], s[10:11], 0, v[84:85]
	v_lshl_add_u64 v[84:85], v[88:89], 0, s[14:15]
	v_or_b32_e32 v84, v84, v0
	v_lshl_add_u64 v[128:129], s[8:9], 0, v[84:85]
	s_lshl_b32 s8, s26, 3
	v_readlane_b32 s9, v254, 31
	s_add_i32 s8, s9, s8
	s_ashr_i32 s9, s8, 31
	s_lshl_b64 s[8:9], s[8:9], 17
	s_add_u32 s0, s0, s8
	s_addc_u32 s1, s1, s9
	v_mov_b32_e32 v82, 0
	v_add_u32_e32 v137, 0, v0
	v_add_u32_e32 v95, 0x6300, v138
	v_mul_u32_u24_e32 v99, 0x210, v87
	v_mul_u32_u24_e32 v100, 0x90, v87
	v_ashrrev_i32_e32 v87, 31, v86
	s_add_u32 s13, s0, 0x20000
	v_mov_b32_e32 v116, v114
	v_mov_b32_e32 v117, v114
	v_lshlrev_b64 v[118:119], 9, v[86:87]
	s_addc_u32 s14, s1, 0
	s_mov_b64 s[8:9], 0
	v_lshlrev_b32_e32 v0, 1, v94
	v_add_u32_e32 v139, v96, v92
	v_add_u32_e32 v140, v97, v99
	v_add_u32_e32 v141, v98, v100
	v_add_u32_e32 v142, v137, v95
	v_add_u32_e32 v143, v83, v92
	v_add_u32_e32 v144, v93, v100
	v_mov_b32_e32 v83, v82
	v_mov_b32_e32 v84, v82
	v_mov_b32_e32 v85, v82
	v_mov_b32_e32 v86, v82
	v_mov_b32_e32 v87, v82
	v_mov_b32_e32 v88, v82
	v_mov_b32_e32 v89, v82
	v_mov_b32_e32 v90, v82
	v_mov_b32_e32 v91, v82
	v_mov_b32_e32 v92, v82
	v_mov_b32_e32 v93, v82
	v_mov_b32_e32 v94, v82
	v_mov_b32_e32 v95, v82
	v_mov_b32_e32 v96, v82
	v_mov_b32_e32 v97, v82
	v_mov_b32_e32 v98, v82
	v_mov_b32_e32 v99, v82
	v_mov_b32_e32 v100, v82
	v_mov_b32_e32 v101, v82
	v_mov_b32_e32 v102, v82
	v_mov_b32_e32 v103, v82
	v_mov_b32_e32 v104, v82
	v_mov_b32_e32 v105, v82
	v_mov_b32_e32 v106, v82
	v_mov_b32_e32 v107, v82
	v_mov_b32_e32 v108, v82
	v_mov_b32_e32 v109, v82
	v_mov_b32_e32 v110, v82
	v_mov_b32_e32 v111, v82
	v_mov_b32_e32 v112, v82
	v_mov_b32_e32 v113, v82
	s_barrier
	s_branch .LBB0_1015

; #define LAS __attribute__((address_space(3)))
; #define GAS __attribute__((address_space(1)))
; __device__ __forceinline__ void ret_unit(LAS unsigned char* lds, const bf16* P, const bf16* RQKV, const bf16* TS, unsigned* flag, bf16* ACAT, const float* rog, int b, int h, int qb, int tid) {
;     asm volatile("" : "+s"(P), "+s"(RQKV), "+s"(TS), "+s"(flag), "+s"(ACAT), "+s"(rog), "+s"(qb), "+v"(tid));
;     const bf16* RQ = RQKV + (size_t)((b * 8 + h) * 2048) * 256; const bf16* RK = RQ + RQKV_ONE / 2; const bf16* RV = RK + RQKV_ONE / 2;
;     const int lane = tid & 63, w = __builtin_amdgcn_readfirstlane(tid >> 6), fr = lane & 15, fq = lane >> 4;
;     constexpr int BUFB = 64 * 528 + 64 * 544;
;     const int qi = 128 * qb + 16 * w + fr;
;     const size_t tq = (size_t)(b * SEQ + qi);
;     f32x4 O[16];
; #pragma unroll
;     for (int nb = 0; nb < 16; ++nb) O[nb] = (f32x4){0.f, 0.f, 0.f, 0.f};
;     const float l2g = __log2f(1.f - exp2f(-5.f - (float)h));
;     const int nkt = 2 * qb + 2;
;     const int qc = 2 * qb + (w >> 2);
;     const int srow = tid >> 5, sch = tid & 31;
;     const size_t soff = (size_t)srow * 256 + sch * 8;
;     u32x4 kreg[4], vreg[4];
;     const int sc = qb >> 1, m0 = 4 * sc;
;     bf16x8 Qf[8];
; #pragma unroll
;     for (int kk = 0; kk < 8; ++kk) Qf[kk] = *(const GAS bf16x8*)(RQ + (size_t)qi * 256 + 32 * kk + 8 * fq);
;     f32x4 ca[4];
;     float l2gp = l2g; asm volatile("" : "+v"(l2gp));
;     { const float ai = __builtin_amdgcn_exp2f((float)(16 * (w & 3) + fr) * l2gp);
; #pragma unroll
;       for (int g = 0; g < 4; ++g)
; #pragma unroll
;           for (int r = 0; r < 4; ++r) ca[g][r] = ai * __builtin_amdgcn_exp2f(-(float)(16 * g + 4 * fq + r) * l2gp); }
; #pragma unroll
;     for (int i = 0; i < 4; ++i) { const size_t o = soff + (size_t)(64 * m0 + 16 * i) * 256; kreg[i] = __builtin_nontemporal_load((const GAS u32x4*)(RK + o)); vreg[i] = __builtin_nontemporal_load((const GAS u32x4*)(RV + o)); }
; #pragma unroll
;     for (int i = 0; i < 4; ++i) { *(LAS u32x4*)(lds + (srow + 16 * i) * 528 + sch * 16) = kreg[i]; *(LAS u32x4*)(lds + 64 * 528 + (srow + 16 * i) * 544 + sch * 16) = vreg[i]; }
;     __syncthreads();
.LBB0_1028:
	s_and_b64 vcc, exec, s[0:1]
	s_cbranch_vccz .LBB0_1042
	s_lshl_b32 s10, s26, 11
	v_readlane_b32 s11, v254, 37
	s_add_i32 s10, s10, s11
	v_readlane_b32 s8, v254, 23
	v_readlane_b32 s0, v254, 5
	v_readlane_b32 s14, v254, 15
	v_readlane_b32 s6, v254, 17
	v_readlane_b32 s4, v254, 3
	s_ashr_i32 s11, s10, 31
	v_readlane_b32 s9, v254, 24
	v_readlane_b32 s1, v254, 6
	v_readlane_b32 s15, v254, 16
	v_readlane_b32 s7, v254, 18
	v_readlane_b32 s5, v254, 4
	v_mov_b32_e32 v185, v220
	s_lshl_b64 s[16:17], s[10:11], 9
	s_add_u32 s16, s14, s16
	s_addc_u32 s17, s15, s17
	s_mov_b32 s13, 0xc2fc0000
	s_add_u32 s14, s16, 0x4000000
	v_readfirstlane_b32 s19, v185
	v_cmp_gt_f32_e32 vcc, s13, v134
	s_addc_u32 s15, s17, 0
	s_ashr_i32 s27, s19, 6
	v_cndmask_b32_e32 v0, 0, v227, vcc
	s_lshl_b32 s29, s12, 7
	s_lshl_b32 s18, s27, 4
	v_add_f32_e32 v0, v134, v0
	v_and_b32_e32 v182, 15, v185
	s_add_i32 s11, s18, s29
	v_exp_f32_e32 v0, v0
	v_or_b32_e32 v148, s11, v182
	s_and_b64 s[20:21], vcc, exec
	v_ashrrev_i32_e32 v149, 31, v148
	s_cselect_b32 s13, 0xffffffc0, 0
	s_lshl_b32 s30, s12, 1
	s_ashr_i32 s28, s12, 1
	s_nop 0
	v_lshlrev_b64 v[2:3], 9, v[148:149]
	v_ldexp_f32 v0, v0, s13
	v_ashrrev_i32_e32 v4, 5, v185
	v_lshl_add_u64 v[2:3], s[16:17], 0, v[2:3]
	s_add_u32 s16, s16, 0x2000000
	v_sub_f32_e32 v6, 1.0, v0
	v_ashrrev_i32_e32 v5, 31, v4
	s_addc_u32 s17, s17, 0
	s_lshl_b32 s12, s28, 8
	v_and_b32_e32 v10, 31, v185
	v_log_f32_e32 v184, v6
	v_lshlrev_b64 v[146:147], 8, v[4:5]
	s_ashr_i32 s13, s12, 31
	v_lshl_or_b32 v146, v10, 3, v146
	s_lshl_b64 s[20:21], s[12:13], 8
	v_and_b32_e32 v0, 48, v185
	v_lshl_add_u64 v[6:7], s[20:21], 0, v[146:147]
	s_or_b32 s20, s12, 16
	v_lshl_add_u64 v[2:3], v[2:3], 0, v[0:1]
	v_lshlrev_b64 v[6:7], 1, v[6:7]
	s_ashr_i32 s21, s20, 31
	global_load_dwordx4 v[66:69], v[2:3], off
	global_load_dwordx4 v[74:77], v[2:3], off offset:64
	global_load_dwordx4 v[82:85], v[2:3], off offset:128
	global_load_dwordx4 v[90:93], v[2:3], off offset:192
	global_load_dwordx4 v[94:97], v[2:3], off offset:256
	global_load_dwordx4 v[86:89], v[2:3], off offset:320
	global_load_dwordx4 v[78:81], v[2:3], off offset:384
	global_load_dwordx4 v[70:73], v[2:3], off offset:448
	v_mov_b32_e32 v2, v184
	v_lshl_add_u64 v[8:9], s[16:17], 0, v[6:7]
	v_lshl_add_u64 v[6:7], s[14:15], 0, v[6:7]
	s_lshl_b64 s[20:21], s[20:21], 8
	global_load_dwordx4 v[98:101], v[8:9], off nt
	global_load_dwordx4 v[102:105], v[6:7], off nt
	v_lshl_add_u64 v[6:7], s[20:21], 0, v[146:147]
	s_or_b32 s20, s12, 32
	v_lshlrev_b64 v[6:7], 1, v[6:7]
	s_ashr_i32 s21, s20, 31
	v_lshl_add_u64 v[8:9], s[16:17], 0, v[6:7]
	v_lshl_add_u64 v[6:7], s[14:15], 0, v[6:7]
	s_lshl_b64 s[20:21], s[20:21], 8
	global_load_dwordx4 v[106:109], v[8:9], off nt
	global_load_dwordx4 v[110:113], v[6:7], off nt
	v_lshl_add_u64 v[6:7], s[20:21], 0, v[146:147]
	s_or_b32 s20, s12, 48
	v_lshlrev_b64 v[6:7], 1, v[6:7]
	s_ashr_i32 s21, s20, 31
	v_lshl_add_u64 v[8:9], s[16:17], 0, v[6:7]
	v_lshl_add_u64 v[6:7], s[14:15], 0, v[6:7]
	s_lshl_b64 s[20:21], s[20:21], 8
	global_load_dwordx4 v[114:117], v[8:9], off nt
	global_load_dwordx4 v[118:121], v[6:7], off nt
	v_lshl_add_u64 v[6:7], s[20:21], 0, v[146:147]
	v_lshlrev_b64 v[6:7], 1, v[6:7]
	v_lshl_add_u64 v[8:9], s[16:17], 0, v[6:7]
	v_lshl_add_u64 v[6:7], s[14:15], 0, v[6:7]
	global_load_dwordx4 v[122:125], v[8:9], off nt
	global_load_dwordx4 v[126:129], v[6:7], off nt
	s_movk_i32 s13, 0x210
	v_mul_lo_u32 v195, v4, s13
	s_movk_i32 s13, 0x220
	v_lshl_add_u32 v194, v10, 4, 0
	v_mul_lo_u32 v196, v4, s13
	s_lshl_b32 s13, s28, 2
	v_add_u32_e32 v149, v194, v195
	s_cmp_gt_i32 s13, s30
	v_mul_u32_u24_e32 v183, 0x210, v182
	v_add_u32_e32 v3, v194, v196
	s_waitcnt vmcnt(7)
	ds_write_b128 v149, v[98:101]
	s_waitcnt vmcnt(6)
	ds_write_b128 v3, v[102:105] offset:33792
	s_waitcnt vmcnt(5)
	ds_write_b128 v149, v[106:109] offset:8448
	s_waitcnt vmcnt(4)
	ds_write_b128 v3, v[110:113] offset:42496
	s_waitcnt vmcnt(3)
	ds_write_b128 v149, v[114:117] offset:16896
	s_waitcnt vmcnt(2)
	ds_write_b128 v3, v[118:121] offset:51200
	s_waitcnt vmcnt(1)
	ds_write_b128 v149, v[122:125] offset:25344
	s_waitcnt vmcnt(0)
	ds_write_b128 v3, v[126:129] offset:59904
	s_waitcnt lgkmcnt(0)
	s_barrier
; #define LAS __attribute__((address_space(3)))
; #define GAS __attribute__((address_space(1)))
; __device__ __forceinline__ void ret_unit(LAS unsigned char* lds, const bf16* P, const bf16* RQKV, const bf16* TS, unsigned* flag, bf16* ACAT, const float* rog, int b, int h, int qb, int tid) {
;     ...
;     const int sc = qb >> 1, m0 = 4 * sc;
;     bf16x8 Qf[8];
; #pragma unroll
;     for (int kk = 0; kk < 8; ++kk) Qf[kk] = *(const GAS bf16x8*)(RQ + (size_t)qi * 256 + 32 * kk + 8 * fq);
;     f32x4 ca[4];
;     float l2gp = l2g; asm volatile("" : "+v"(l2gp));
;     { const float ai = __builtin_amdgcn_exp2f((float)(16 * (w & 3) + fr) * l2gp);
; #pragma unroll
;       for (int g = 0; g < 4; ++g)
; #pragma unroll
;           for (int r = 0; r < 4; ++r) ca[g][r] = ai * __builtin_amdgcn_exp2f(-(float)(16 * g + 4 * fq + r) * l2gp); }
; #pragma unroll
;     for (int i = 0; i < 4; ++i) { const size_t o = soff + (size_t)(64 * m0 + 16 * i) * 256; kreg[i] = __builtin_nontemporal_load((const GAS u32x4*)(RK + o)); vreg[i] = __builtin_nontemporal_load((const GAS u32x4*)(RV + o)); }
; #pragma unroll
;     for (int i = 0; i < 4; ++i) { *(LAS u32x4*)(lds + (srow + 16 * i) * 528 + sch * 16) = kreg[i]; *(LAS u32x4*)(lds + 64 * 528 + (srow + 16 * i) * 544 + sch * 16) = vreg[i]; }
;     __syncthreads();
;     for (int m = m0; m < nkt; ++m) {
	s_cbranch_scc1 .LBB0_1043
	v_and_or_b32 v3, s18, 48, v182
	v_cvt_f32_ubyte0_e32 v3, v3
	v_mul_f32_e32 v3, v2, v3
	v_exp_f32_e32 v4, v3
	v_lshrrev_b32_e32 v3, 2, v185
	v_and_b32_e32 v3, 12, v3
	v_cvt_f32_ubyte0_e32 v5, v3
	v_mul_f32_e64 v5, v2, -v5
	v_exp_f32_e32 v6, v5
	v_or_b32_e32 v5, 1, v3
	v_cvt_f32_ubyte0_e32 v5, v5
	v_mul_f32_e64 v5, v2, -v5
	v_exp_f32_e32 v7, v5
	v_or_b32_e32 v5, 2, v3
	v_cvt_f32_ubyte0_e32 v5, v5
	v_mul_f32_e64 v5, v2, -v5
	v_exp_f32_e32 v8, v5
	v_or_b32_e32 v5, 3, v3
	v_cvt_f32_ubyte0_e32 v5, v5
	v_mul_f32_e64 v5, v2, -v5
	v_exp_f32_e32 v9, v5
	v_or_b32_e32 v5, 16, v3
	v_cvt_f32_ubyte0_e32 v5, v5
	v_mul_f32_e64 v5, v2, -v5
	v_exp_f32_e32 v10, v5
	v_or_b32_e32 v5, 17, v3
	v_cvt_f32_ubyte0_e32 v5, v5
	v_mul_f32_e64 v5, v2, -v5
	v_exp_f32_e32 v11, v5
	v_or_b32_e32 v5, 18, v3
	v_cvt_f32_ubyte0_e32 v5, v5
	v_mul_f32_e64 v5, v2, -v5
	v_exp_f32_e32 v12, v5
	v_or_b32_e32 v5, 19, v3
	v_cvt_f32_ubyte0_e32 v5, v5
	v_mul_f32_e64 v5, v2, -v5
	v_exp_f32_e32 v13, v5
	v_or_b32_e32 v5, 32, v3
	v_cvt_f32_ubyte0_e32 v5, v5
	v_mul_f32_e64 v5, v2, -v5
	v_exp_f32_e32 v14, v5
	v_or_b32_e32 v5, 33, v3
	v_cvt_f32_ubyte0_e32 v5, v5
	v_mul_f32_e64 v5, v2, -v5
	v_exp_f32_e32 v15, v5
	v_or_b32_e32 v5, 34, v3
	v_cvt_f32_ubyte0_e32 v5, v5
	v_mul_f32_e64 v5, v2, -v5
	v_exp_f32_e32 v16, v5
	v_or_b32_e32 v5, 35, v3
	v_cvt_f32_ubyte0_e32 v5, v5
	v_mul_f32_e64 v5, v2, -v5
	v_exp_f32_e32 v17, v5
	v_or_b32_e32 v5, 48, v3
	v_cvt_f32_ubyte0_e32 v5, v5
	v_mul_f32_e64 v5, v2, -v5
	v_exp_f32_e32 v18, v5
	v_or_b32_e32 v5, 49, v3
	v_cvt_f32_ubyte0_e32 v5, v5
	v_mul_f32_e64 v5, v2, -v5
	v_exp_f32_e32 v19, v5
	v_or_b32_e32 v5, 50, v3
	v_cvt_f32_ubyte0_e32 v5, v5
	v_mul_f32_e64 v5, v2, -v5
	v_exp_f32_e32 v20, v5
	v_or_b32_e32 v5, 51, v3
	v_cvt_f32_ubyte0_e32 v5, v5
	v_mul_f32_e64 v2, v2, -v5
	v_exp_f32_e32 v21, v2
	v_lshrrev_b32_e32 v2, 2, v182
	v_or_b32_e32 v2, v3, v2
	v_mul_u32_u24_e32 v198, 0x220, v2
	v_lshlrev_b32_e32 v2, 3, v185
	v_and_b32_e32 v199, 24, v2
	v_add_u32_e32 v2, s18, v182
	s_ashr_i32 s19, s19, 8
	v_sub_u32_e32 v2, v2, v3
	v_mov_b32_e32 v54, v1
	v_mov_b32_e32 v55, v1
	v_mov_b32_e32 v56, v1
	v_mov_b32_e32 v57, v1
	v_pk_mul_f32 v[150:151], v[4:5], v[20:21] op_sel_hi:[0,1]
	v_pk_mul_f32 v[152:153], v[4:5], v[18:19] op_sel_hi:[0,1]
	v_pk_mul_f32 v[154:155], v[4:5], v[16:17] op_sel_hi:[0,1]
	v_pk_mul_f32 v[156:157], v[4:5], v[14:15] op_sel_hi:[0,1]
	v_pk_mul_f32 v[158:159], v[4:5], v[12:13] op_sel_hi:[0,1]
	v_pk_mul_f32 v[160:161], v[4:5], v[10:11] op_sel_hi:[0,1]
	v_pk_mul_f32 v[162:163], v[4:5], v[8:9] op_sel_hi:[0,1]
	v_pk_mul_f32 v[164:165], v[4:5], v[6:7] op_sel_hi:[0,1]
	v_subrev_u32_e32 v200, s12, v2
	s_lshl_b32 s18, s19, 6
	v_mov_b64_e32 v[64:65], v[56:57]
	v_mov_b64_e32 v[60:61], v[56:57]
	v_mov_b64_e32 v[50:51], v[54:55]
	v_mov_b64_e32 v[46:47], v[54:55]
	v_mov_b64_e32 v[42:43], v[54:55]
	v_mov_b64_e32 v[38:39], v[54:55]
	v_mov_b64_e32 v[34:35], v[54:55]
	v_mov_b64_e32 v[30:31], v[54:55]
	v_mov_b64_e32 v[26:27], v[54:55]
	v_mov_b64_e32 v[22:23], v[54:55]
	v_mov_b64_e32 v[18:19], v[54:55]
	v_mov_b64_e32 v[14:15], v[54:55]
	v_mov_b64_e32 v[10:11], v[54:55]
	v_mov_b64_e32 v[6:7], v[54:55]
	v_mov_b64_e32 v[2:3], v[54:55]
	s_add_i32 s31, s30, s19
	v_and_b32_e32 v197, 48, v185
	s_sub_i32 s33, s18, s12
	s_add_i32 s18, s12, 0x70
	v_mov_b64_e32 v[62:63], v[54:55]
	v_mov_b64_e32 v[58:59], v[54:55]
	v_mov_b64_e32 v[52:53], v[56:57]
	v_mov_b64_e32 v[48:49], v[56:57]
	v_mov_b64_e32 v[44:45], v[56:57]
	v_mov_b64_e32 v[40:41], v[56:57]
	v_mov_b64_e32 v[36:37], v[56:57]
	v_mov_b64_e32 v[32:33], v[56:57]
	v_mov_b64_e32 v[28:29], v[56:57]
	v_mov_b64_e32 v[24:25], v[56:57]
	v_mov_b64_e32 v[20:21], v[56:57]
	v_mov_b64_e32 v[16:17], v[56:57]
	v_mov_b64_e32 v[12:13], v[56:57]
	v_mov_b64_e32 v[8:9], v[56:57]
	v_mov_b64_e32 v[4:5], v[56:57]
	s_branch .LBB0_1032

; __global__ void __launch_bounds__(512, 2) mega_fwd(Params p) {
	.amdhsa_kernel _Z8mega_fwd6Params
		.amdhsa_group_segment_fixed_size 0
		.amdhsa_private_segment_fixed_size 0
		.amdhsa_kernarg_size 352
		.amdhsa_user_sgpr_count 2
		.amdhsa_user_sgpr_dispatch_ptr 0
		.amdhsa_user_sgpr_queue_ptr 0
		.amdhsa_user_sgpr_kernarg_segment_ptr 1
		.amdhsa_user_sgpr_dispatch_id 0
		.amdhsa_user_sgpr_kernarg_preload_length 0
		.amdhsa_user_sgpr_kernarg_preload_offset 0
		.amdhsa_user_sgpr_private_segment_size 0
		.amdhsa_uses_dynamic_stack 0
		.amdhsa_enable_private_segment 0
		.amdhsa_system_sgpr_workgroup_id_x 1
		.amdhsa_system_sgpr_workgroup_id_y 0
		.amdhsa_system_sgpr_workgroup_id_z 0
		.amdhsa_system_sgpr_workgroup_info 0
		.amdhsa_system_vgpr_workitem_id 2
		.amdhsa_next_free_vgpr 255
		.amdhsa_next_free_sgpr 102
		.amdhsa_accum_offset 256
		.amdhsa_reserve_vcc 1
		.amdhsa_float_round_mode_32 0
		.amdhsa_float_round_mode_16_64 0
		.amdhsa_float_denorm_mode_32 3
		.amdhsa_float_denorm_mode_16_64 3
		.amdhsa_dx10_clamp 1
		.amdhsa_ieee_mode 1
		.amdhsa_fp16_overflow 0
		.amdhsa_tg_split 0
		.amdhsa_exception_fp_ieee_invalid_op 0
		.amdhsa_exception_fp_denorm_src 0
		.amdhsa_exception_fp_ieee_div_zero 0
		.amdhsa_exception_fp_ieee_overflow 0
		.amdhsa_exception_fp_ieee_underflow 0
		.amdhsa_exception_fp_ieee_inexact 0
		.amdhsa_exception_int_div_zero 0
	.end_amdhsa_kernel

; __global__ void __launch_bounds__(512, 2) mega_fwd(Params p) {
amdhsa.kernels:
  - .agpr_count:     0
    .args:
      - .offset:         0
        .size:           96
        .value_kind:     by_value
      - .offset:         96
        .size:           4
        .value_kind:     hidden_block_count_x
      - .offset:         100
        .size:           4
        .value_kind:     hidden_block_count_y
      - .offset:         104
        .size:           4
        .value_kind:     hidden_block_count_z
      - .offset:         108
        .size:           2
        .value_kind:     hidden_group_size_x
      - .offset:         110
        .size:           2
        .value_kind:     hidden_group_size_y
      - .offset:         112
        .size:           2
        .value_kind:     hidden_group_size_z
      - .offset:         114
        .size:           2
        .value_kind:     hidden_remainder_x
      - .offset:         116
        .size:           2
        .value_kind:     hidden_remainder_y
      - .offset:         118
        .size:           2
        .value_kind:     hidden_remainder_z
      - .offset:         136
        .size:           8
        .value_kind:     hidden_global_offset_x
      - .offset:         144
        .size:           8
        .value_kind:     hidden_global_offset_y
      - .offset:         152
        .size:           8
        .value_kind:     hidden_global_offset_z
      - .offset:         160
        .size:           2
        .value_kind:     hidden_grid_dims
      - .offset:         184
        .size:           8
        .value_kind:     hidden_multigrid_sync_arg
      - .offset:         216
        .size:           4
        .value_kind:     hidden_dynamic_lds_size
    .group_segment_fixed_size: 0
    .kernarg_segment_align: 8
    .kernarg_segment_size: 352
    .language:       OpenCL C
    .language_version:
      - 2
      - 0
    .max_flat_workgroup_size: 512
    .name:           _Z8mega_fwd6Params
    .private_segment_fixed_size: 0
    .sgpr_count:     108
    .sgpr_spill_count: 181
    .symbol:         _Z8mega_fwd6Params.kd
    .uniform_work_group_size: 1
    .uses_dynamic_stack: false
    .vgpr_count:     255
    .vgpr_spill_count: 0
    .wavefront_size: 64
